# the 15 GEMM K-loop heads aligned to 64 bytes (on top of norm-loop consolidation)
# baseline (speedup 1.0000x reference)
; #define PG8_WAIT_V(n) asm volatile("s_waitcnt vmcnt(" #n ")" ::: "memory")
; template <class Epi, class Sched, bool ALIGN_EPI = true, bool SP2 = true, bool FULLLINE = false, bool NOSTAGE = false, bool FP8 = false>
; __device__ __forceinline__ void gemm_phase(PG8_LAS unsigned char* lds, const Gemm g, const Sched& S, const Epi& E) {
;     ...
;         const bool has_next = S.next(ui + 1, nxt);
;         const char* nA = has_next ? PG8_ABASE(nxt) : cA; const char* nB = has_next ? PG8_BBASE(nxt) : cB;
;     ...
;         static_assert(SP2, "only the SP2 loop is kept");
;         { const int t = 0; if constexpr (Epi::NST == 16) PG8_ITER(PG8_WAIT_V(24)); else if constexpr (Epi::NST == 8) PG8_ITER(PG8_WAIT_V(16)); else PG8_ITER(PG8_WAIT_V(8)); }
.LBB0_261:
	s_ashr_i32 s75, s74, 31
	s_lshl_b64 s[40:41], s[74:75], 20
	s_add_u32 s76, s58, s40
	ds_read_b128 v[2:5], v156
	ds_read_b128 v[6:9], v156 offset:1024
	ds_read_b128 v[10:13], v156 offset:2048
	ds_read_b128 v[14:17], v156 offset:3072
	ds_read_b128 v[18:21], v157
	ds_read_b128 v[22:25], v157 offset:1024
	ds_read_b128 v[26:29], v157 offset:2048
	ds_read_b128 v[30:33], v157 offset:3072
	s_addc_u32 s77, s59, s41
	s_ashr_i32 s73, s72, 31
	s_lshl_b64 s[40:41], s[72:73], 20
	s_add_u32 s78, s84, s40
	s_addc_u32 s79, s85, s41
	s_and_b64 s[40:41], s[8:9], exec
	s_cselect_b32 s3, s77, s83
	s_cselect_b32 s11, s76, s82
	s_cselect_b32 s13, s79, s81
	s_cselect_b32 s42, s78, s80
	v_lshl_add_u64 v[138:139], s[82:83], 0, v[140:141]
	s_mov_b32 m0, s89
	v_lshl_add_u64 v[66:67], v[138:139], 0, s[20:21]
	ds_read_b128 v[34:37], v158
	ds_read_b128 v[38:41], v158 offset:1024
	ds_read_b128 v[42:45], v158 offset:2048
	ds_read_b128 v[46:49], v158 offset:3072
	ds_read_b128 v[50:53], v158 offset:4096
	ds_read_b128 v[54:57], v158 offset:5120
	ds_read_b128 v[58:61], v158 offset:6144
	ds_read_b128 v[62:65], v158 offset:7168
	global_load_lds_dwordx4 v[66:67], off
	v_lshl_add_u64 v[66:67], v[138:139], 0, s[22:23]
	s_mov_b32 m0, s45
	s_nop 0
	global_load_lds_dwordx4 v[66:67], off
	s_waitcnt vmcnt(24)
	s_waitcnt lgkmcnt(0)
	s_barrier
	s_waitcnt lgkmcnt(0)
	v_mfma_f32_16x16x32_bf16 v[86:89], v[10:13], v[50:53], 0
	v_mfma_f32_16x16x32_bf16 v[90:93], v[14:17], v[54:57], v[86:89]
	v_mfma_f32_16x16x32_bf16 v[86:89], v[2:5], v[58:61], 0
	v_mfma_f32_16x16x32_bf16 v[66:69], v[2:5], v[34:37], 0
	v_mfma_f32_16x16x32_bf16 v[70:73], v[10:13], v[34:37], 0
	v_mfma_f32_16x16x32_bf16 v[74:77], v[2:5], v[42:45], 0
	v_mfma_f32_16x16x32_bf16 v[78:81], v[10:13], v[42:45], 0
	v_mfma_f32_16x16x32_bf16 v[82:85], v[2:5], v[50:53], 0
	v_mfma_f32_16x16x32_bf16 v[94:97], v[6:9], v[62:65], v[86:89]
	v_mfma_f32_16x16x32_bf16 v[86:89], v[10:13], v[58:61], 0
	v_mfma_f32_16x16x32_bf16 v[66:69], v[6:9], v[38:41], v[66:69]
	v_mfma_f32_16x16x32_bf16 v[70:73], v[14:17], v[38:41], v[70:73]
	v_mfma_f32_16x16x32_bf16 v[74:77], v[6:9], v[46:49], v[74:77]
	v_mfma_f32_16x16x32_bf16 v[78:81], v[14:17], v[46:49], v[78:81]
	v_mfma_f32_16x16x32_bf16 v[82:85], v[6:9], v[54:57], v[82:85]
	v_mfma_f32_16x16x32_bf16 v[106:109], v[14:17], v[62:65], v[86:89]
	v_mfma_f32_16x16x32_bf16 v[86:89], v[18:21], v[34:37], 0
	v_mfma_f32_16x16x32_bf16 v[34:37], v[26:29], v[34:37], 0
	v_mfma_f32_16x16x32_bf16 v[110:113], v[22:25], v[38:41], v[86:89]
	v_mfma_f32_16x16x32_bf16 v[34:37], v[30:33], v[38:41], v[34:37]
	v_mfma_f32_16x16x32_bf16 v[38:41], v[18:21], v[42:45], 0
	v_mfma_f32_16x16x32_bf16 v[42:45], v[26:29], v[42:45], 0
	v_mfma_f32_16x16x32_bf16 v[38:41], v[22:25], v[46:49], v[38:41]
	v_mfma_f32_16x16x32_bf16 v[42:45], v[30:33], v[46:49], v[42:45]
	v_mfma_f32_16x16x32_bf16 v[46:49], v[18:21], v[50:53], 0
	v_mfma_f32_16x16x32_bf16 v[50:53], v[26:29], v[50:53], 0
	v_mfma_f32_16x16x32_bf16 v[46:49], v[22:25], v[54:57], v[46:49]
	v_mfma_f32_16x16x32_bf16 v[50:53], v[30:33], v[54:57], v[50:53]
	v_mfma_f32_16x16x32_bf16 v[54:57], v[18:21], v[58:61], 0
	v_mfma_f32_16x16x32_bf16 v[58:61], v[26:29], v[58:61], 0
	v_mfma_f32_16x16x32_bf16 v[54:57], v[22:25], v[62:65], v[54:57]
	v_mfma_f32_16x16x32_bf16 v[58:61], v[30:33], v[62:65], v[58:61]
	s_barrier
	v_lshl_add_u64 v[154:155], s[80:81], 0, v[142:143]
	s_add_i32 s43, s62, s88
	v_lshl_add_u64 v[130:131], v[154:155], 0, s[24:25]
	s_mov_b32 m0, s43
	s_add_i32 s53, s43, 0x2000
	ds_read_b128 v[62:65], v158 offset:16384
	ds_read_b128 v[86:89], v158 offset:17408
	ds_read_b128 v[98:101], v158 offset:18432
	ds_read_b128 v[102:105], v158 offset:19456
	ds_read_b128 v[114:117], v158 offset:20480
	ds_read_b128 v[118:121], v158 offset:21504
	ds_read_b128 v[122:125], v158 offset:22528
	ds_read_b128 v[126:129], v158 offset:23552
	global_load_lds_dwordx4 v[130:131], off
	v_lshl_add_u64 v[130:131], v[154:155], 0, s[26:27]
	s_mov_b32 m0, s53
	s_add_i32 s73, s63, s88
	global_load_lds_dwordx4 v[130:131], off
	v_lshl_add_u64 v[130:131], v[154:155], 0, s[28:29]
	s_mov_b32 m0, s73
	s_add_i32 s40, s73, 0x2000
	global_load_lds_dwordx4 v[130:131], off
	v_lshl_add_u64 v[130:131], v[154:155], 0, s[30:31]
	s_mov_b32 m0, s40
	s_nop 0
	global_load_lds_dwordx4 v[130:131], off
	v_lshl_add_u64 v[130:131], v[138:139], 0, s[24:25]
	s_mov_b32 m0, s44
	s_nop 0
	global_load_lds_dwordx4 v[130:131], off
	v_lshl_add_u64 v[130:131], v[138:139], 0, s[26:27]
	s_mov_b32 m0, s90
	s_nop 0
	global_load_lds_dwordx4 v[130:131], off
	s_waitcnt vmcnt(24)
	s_waitcnt lgkmcnt(0)
	s_barrier
	s_waitcnt lgkmcnt(0)
	v_mfma_f32_16x16x32_bf16 v[130:133], v[2:5], v[62:65], 0
	v_mfma_f32_16x16x32_bf16 v[150:153], v[2:5], v[98:101], 0
	v_mfma_f32_16x16x32_bf16 v[170:173], v[2:5], v[114:117], 0
	v_mfma_f32_16x16x32_bf16 v[2:5], v[2:5], v[122:125], 0
	v_mfma_f32_16x16x32_bf16 v[130:133], v[6:9], v[86:89], v[130:133]
	v_mfma_f32_16x16x32_bf16 v[150:153], v[6:9], v[102:105], v[150:153]
	v_mfma_f32_16x16x32_bf16 v[170:173], v[6:9], v[118:121], v[170:173]
	v_mfma_f32_16x16x32_bf16 v[2:5], v[6:9], v[126:129], v[2:5]
	v_mfma_f32_16x16x32_bf16 v[6:9], v[10:13], v[122:125], 0
	v_mfma_f32_16x16x32_bf16 v[134:137], v[10:13], v[62:65], 0
	v_mfma_f32_16x16x32_bf16 v[166:169], v[10:13], v[98:101], 0
	v_mfma_f32_16x16x32_bf16 v[174:177], v[10:13], v[114:117], 0
	v_mfma_f32_16x16x32_bf16 v[6:9], v[14:17], v[126:129], v[6:9]
	v_mfma_f32_16x16x32_bf16 v[134:137], v[14:17], v[86:89], v[134:137]
	v_mfma_f32_16x16x32_bf16 v[166:169], v[14:17], v[102:105], v[166:169]
	v_mfma_f32_16x16x32_bf16 v[174:177], v[14:17], v[118:121], v[174:177]
	v_mfma_f32_16x16x32_bf16 v[10:13], v[18:21], v[62:65], 0
	v_mfma_f32_16x16x32_bf16 v[14:17], v[26:29], v[62:65], 0
	v_mfma_f32_16x16x32_bf16 v[62:65], v[18:21], v[98:101], 0
	v_mfma_f32_16x16x32_bf16 v[178:181], v[22:25], v[102:105], v[62:65]
	v_mfma_f32_16x16x32_bf16 v[62:65], v[26:29], v[98:101], 0
	v_mfma_f32_16x16x32_bf16 v[182:185], v[30:33], v[102:105], v[62:65]
	v_mfma_f32_16x16x32_bf16 v[62:65], v[18:21], v[114:117], 0
	v_mfma_f32_16x16x32_bf16 v[18:21], v[18:21], v[122:125], 0
	v_mfma_f32_16x16x32_bf16 v[10:13], v[22:25], v[86:89], v[10:13]
	v_mfma_f32_16x16x32_bf16 v[14:17], v[30:33], v[86:89], v[14:17]
	v_mfma_f32_16x16x32_bf16 v[186:189], v[22:25], v[118:121], v[62:65]
	v_mfma_f32_16x16x32_bf16 v[62:65], v[26:29], v[114:117], 0
	v_mfma_f32_16x16x32_bf16 v[194:197], v[22:25], v[126:129], v[18:21]
	v_mfma_f32_16x16x32_bf16 v[18:21], v[26:29], v[122:125], 0
	v_mfma_f32_16x16x32_bf16 v[190:193], v[30:33], v[118:121], v[62:65]
	v_mfma_f32_16x16x32_bf16 v[198:201], v[30:33], v[126:129], v[18:21]
	s_barrier
; #define PG8_WAIT_V(n) asm volatile("s_waitcnt vmcnt(" #n ")" ::: "memory")
; template <class Epi, class Sched, bool ALIGN_EPI = true, bool SP2 = true, bool FULLLINE = false, bool NOSTAGE = false, bool FP8 = false>
; __device__ __forceinline__ void gemm_phase(PG8_LAS unsigned char* lds, const Gemm g, const Sched& S, const Epi& E) {
;     ...
;         static_assert(SP2, "only the SP2 loop is kept");
;         { const int t = 0; if constexpr (Epi::NST == 16) PG8_ITER(PG8_WAIT_V(24)); else if constexpr (Epi::NST == 8) PG8_ITER(PG8_WAIT_V(16)); else PG8_ITER(PG8_WAIT_V(8)); }
;         for (int t = 2; t < nt; t += 2) PG8_ITER(PG8_WAIT_V(8));
	ds_read_b128 v[26:29], v159
	ds_read_b128 v[30:33], v159 offset:1024
	s_nop 0
	ds_read_b128 v[62:65], v159 offset:2048
	ds_read_b128 v[202:205], v159 offset:3072
	ds_read_b128 v[206:209], v160
	ds_read_b128 v[210:213], v160 offset:1024
	ds_read_b128 v[214:217], v160 offset:2048
	ds_read_b128 v[218:221], v160 offset:3072
	s_mov_b32 m0, s91
	v_lshl_add_u64 v[86:87], v[138:139], 0, s[28:29]
	ds_read_b128 v[18:21], v158 offset:32768
	ds_read_b128 v[22:25], v158 offset:33792
	ds_read_b128 v[222:225], v158 offset:34816
	ds_read_b128 v[226:229], v158 offset:35840
	ds_read_b128 v[230:233], v158 offset:36864
	ds_read_b128 v[234:237], v158 offset:37888
	ds_read_b128 v[238:241], v158 offset:38912
	ds_read_b128 v[242:245], v158 offset:39936
	global_load_lds_dwordx4 v[86:87], off
	v_lshl_add_u64 v[86:87], v[138:139], 0, s[30:31]
	s_mov_b32 m0, s92
	s_nop 0
	global_load_lds_dwordx4 v[86:87], off
	s_waitcnt vmcnt(8)
	s_waitcnt lgkmcnt(0)
	s_barrier
	s_waitcnt lgkmcnt(0)
	v_mfma_f32_16x16x32_bf16 v[66:69], v[26:29], v[18:21], v[66:69]
	v_mfma_f32_16x16x32_bf16 v[118:121], v[30:33], v[22:25], v[66:69]
	v_mfma_f32_16x16x32_bf16 v[66:69], v[62:65], v[18:21], v[70:73]
	v_mfma_f32_16x16x32_bf16 v[114:117], v[202:205], v[22:25], v[66:69]
	v_mfma_f32_16x16x32_bf16 v[66:69], v[26:29], v[222:225], v[74:77]
	v_mfma_f32_16x16x32_bf16 v[102:105], v[30:33], v[226:229], v[66:69]
	v_mfma_f32_16x16x32_bf16 v[66:69], v[62:65], v[222:225], v[78:81]
	v_mfma_f32_16x16x32_bf16 v[98:101], v[202:205], v[226:229], v[66:69]
	v_mfma_f32_16x16x32_bf16 v[66:69], v[26:29], v[230:233], v[82:85]
	v_mfma_f32_16x16x32_bf16 v[86:89], v[30:33], v[234:237], v[66:69]
	v_mfma_f32_16x16x32_bf16 v[66:69], v[62:65], v[230:233], v[90:93]
	v_mfma_f32_16x16x32_bf16 v[82:85], v[202:205], v[234:237], v[66:69]
	v_mfma_f32_16x16x32_bf16 v[66:69], v[26:29], v[238:241], v[94:97]
	v_mfma_f32_16x16x32_bf16 v[70:73], v[62:65], v[238:241], v[106:109]
	v_mfma_f32_16x16x32_bf16 v[66:69], v[30:33], v[242:245], v[66:69]
	v_mfma_f32_16x16x32_bf16 v[70:73], v[202:205], v[242:245], v[70:73]
	v_mfma_f32_16x16x32_bf16 v[74:77], v[206:209], v[18:21], v[110:113]
	v_mfma_f32_16x16x32_bf16 v[18:21], v[214:217], v[18:21], v[34:37]
	v_mfma_f32_16x16x32_bf16 v[122:125], v[218:221], v[22:25], v[18:21]
	v_mfma_f32_16x16x32_bf16 v[18:21], v[206:209], v[222:225], v[38:41]
	v_mfma_f32_16x16x32_bf16 v[110:113], v[210:213], v[226:229], v[18:21]
	v_mfma_f32_16x16x32_bf16 v[18:21], v[214:217], v[222:225], v[42:45]
	v_mfma_f32_16x16x32_bf16 v[106:109], v[218:221], v[226:229], v[18:21]
	v_mfma_f32_16x16x32_bf16 v[18:21], v[206:209], v[230:233], v[46:49]
	v_mfma_f32_16x16x32_bf16 v[94:97], v[210:213], v[234:237], v[18:21]
	v_mfma_f32_16x16x32_bf16 v[18:21], v[214:217], v[230:233], v[50:53]
	v_mfma_f32_16x16x32_bf16 v[90:93], v[218:221], v[234:237], v[18:21]
	v_mfma_f32_16x16x32_bf16 v[18:21], v[206:209], v[238:241], v[54:57]
	v_mfma_f32_16x16x32_bf16 v[126:129], v[210:213], v[22:25], v[74:77]
	v_mfma_f32_16x16x32_bf16 v[74:77], v[210:213], v[242:245], v[18:21]
	v_mfma_f32_16x16x32_bf16 v[18:21], v[214:217], v[238:241], v[58:61]
	v_mfma_f32_16x16x32_bf16 v[78:81], v[218:221], v[242:245], v[18:21]
	s_barrier
	s_add_i32 s41, s46, s88
	s_nop 4
	v_lshl_add_u64 v[18:19], v[154:155], 0, s[34:35]
	s_mov_b32 m0, s41
	s_add_i32 s50, s41, 0x2000
	ds_read_b128 v[42:45], v158 offset:49152
	ds_read_b128 v[46:49], v158 offset:50176
	ds_read_b128 v[222:225], v158 offset:51200
	ds_read_b128 v[226:229], v158 offset:52224
	ds_read_b128 v[230:233], v158 offset:53248
	ds_read_b128 v[234:237], v158 offset:54272
	ds_read_b128 v[238:241], v158 offset:55296
	ds_read_b128 v[242:245], v158 offset:56320
	global_load_lds_dwordx4 v[18:19], off
	v_lshl_add_u64 v[18:19], v[154:155], 0, s[36:37]
	s_mov_b32 m0, s50
	s_mov_b64 s[56:57], 0x80180
	s_add_i32 s51, s47, s88
	global_load_lds_dwordx4 v[18:19], off
	v_lshl_add_u64 v[18:19], v[154:155], 0, s[56:57]
	s_mov_b32 m0, s51
	s_mov_b64 s[56:57], 0xc0180
	s_add_i32 s33, s51, 0x2000
	global_load_lds_dwordx4 v[18:19], off
	v_lshl_add_u64 v[18:19], v[154:155], 0, s[56:57]
	s_mov_b32 m0, s33
	s_nop 0
	global_load_lds_dwordx4 v[18:19], off
	v_lshl_add_u64 v[18:19], v[138:139], 0, s[34:35]
	s_mov_b32 m0, s93
	s_nop 0
	global_load_lds_dwordx4 v[18:19], off
	v_lshl_add_u64 v[18:19], v[138:139], 0, s[36:37]
	s_mov_b32 m0, s94
	s_nop 0
	global_load_lds_dwordx4 v[18:19], off
	s_waitcnt vmcnt(8)
	s_waitcnt lgkmcnt(0)
	s_barrier
	s_waitcnt lgkmcnt(0)
	v_mfma_f32_16x16x32_bf16 v[18:21], v[26:29], v[42:45], v[130:133]
	v_mfma_f32_16x16x32_bf16 v[50:53], v[30:33], v[46:49], v[18:21]
	v_mfma_f32_16x16x32_bf16 v[18:21], v[62:65], v[42:45], v[134:137]
	v_mfma_f32_16x16x32_bf16 v[54:57], v[202:205], v[46:49], v[18:21]
	v_mfma_f32_16x16x32_bf16 v[18:21], v[26:29], v[222:225], v[150:153]
	v_mfma_f32_16x16x32_bf16 v[34:37], v[30:33], v[226:229], v[18:21]
	v_mfma_f32_16x16x32_bf16 v[18:21], v[62:65], v[222:225], v[166:169]
	v_mfma_f32_16x16x32_bf16 v[38:41], v[202:205], v[226:229], v[18:21]
	v_mfma_f32_16x16x32_bf16 v[18:21], v[26:29], v[230:233], v[170:173]
	v_mfma_f32_16x16x32_bf16 v[22:25], v[62:65], v[230:233], v[174:177]
	v_mfma_f32_16x16x32_bf16 v[2:5], v[26:29], v[238:241], v[2:5]
	v_mfma_f32_16x16x32_bf16 v[6:9], v[62:65], v[238:241], v[6:9]
	v_mfma_f32_16x16x32_bf16 v[18:21], v[30:33], v[234:237], v[18:21]
	v_mfma_f32_16x16x32_bf16 v[22:25], v[202:205], v[234:237], v[22:25]
	v_mfma_f32_16x16x32_bf16 v[2:5], v[30:33], v[242:245], v[2:5]
	v_mfma_f32_16x16x32_bf16 v[6:9], v[202:205], v[242:245], v[6:9]
	v_mfma_f32_16x16x32_bf16 v[10:13], v[206:209], v[42:45], v[10:13]
	v_mfma_f32_16x16x32_bf16 v[58:61], v[210:213], v[46:49], v[10:13]
	v_mfma_f32_16x16x32_bf16 v[10:13], v[214:217], v[42:45], v[14:17]
	v_mfma_f32_16x16x32_bf16 v[62:65], v[218:221], v[46:49], v[10:13]
	v_mfma_f32_16x16x32_bf16 v[10:13], v[206:209], v[222:225], v[178:181]
	v_mfma_f32_16x16x32_bf16 v[42:45], v[210:213], v[226:229], v[10:13]
	v_mfma_f32_16x16x32_bf16 v[10:13], v[214:217], v[222:225], v[182:185]
	v_mfma_f32_16x16x32_bf16 v[46:49], v[218:221], v[226:229], v[10:13]
	v_mfma_f32_16x16x32_bf16 v[10:13], v[206:209], v[230:233], v[186:189]
	v_mfma_f32_16x16x32_bf16 v[26:29], v[210:213], v[234:237], v[10:13]
	v_mfma_f32_16x16x32_bf16 v[10:13], v[214:217], v[230:233], v[190:193]
	v_mfma_f32_16x16x32_bf16 v[30:33], v[218:221], v[234:237], v[10:13]
	v_mfma_f32_16x16x32_bf16 v[10:13], v[206:209], v[238:241], v[194:197]
	v_mfma_f32_16x16x32_bf16 v[14:17], v[214:217], v[238:241], v[198:201]
	v_mfma_f32_16x16x32_bf16 v[10:13], v[210:213], v[242:245], v[10:13]
	v_mfma_f32_16x16x32_bf16 v[14:17], v[218:221], v[242:245], v[14:17]
	s_barrier
	s_add_u32 s82, s82, 0x80180
	s_addc_u32 s83, s83, 0
	s_add_u32 s56, s80, 0x200
	s_addc_u32 s57, s81, 0
	s_mov_b32 s75, 0
	.p2align 6

; #define PG8_WAIT_V(n) asm volatile("s_waitcnt vmcnt(" #n ")" ::: "memory")
; template <class Epi, class Sched, bool ALIGN_EPI = true, bool SP2 = true, bool FULLLINE = false, bool NOSTAGE = false, bool FP8 = false>
; __device__ __forceinline__ void gemm_phase(PG8_LAS unsigned char* lds, const Gemm g, const Sched& S, const Epi& E) {
;     ...
;         const bool has_next = S.next(ui + 1, nxt);
;         const char* nA = has_next ? PG8_ABASE(nxt) : cA; const char* nB = has_next ? PG8_BBASE(nxt) : cB;
;     ...
;         static_assert(SP2, "only the SP2 loop is kept");
;         { const int t = 0; if constexpr (Epi::NST == 16) PG8_ITER(PG8_WAIT_V(24)); else if constexpr (Epi::NST == 8) PG8_ITER(PG8_WAIT_V(16)); else PG8_ITER(PG8_WAIT_V(8)); }
.LBB0_593:
	s_ashr_i32 s69, s68, 31
	s_lshl_b64 s[40:41], s[68:69], 21
	s_add_u32 s70, s42, s40
	ds_read_b128 v[2:5], v160
	ds_read_b128 v[6:9], v160 offset:1024
	ds_read_b128 v[10:13], v160 offset:2048
	ds_read_b128 v[14:17], v160 offset:3072
	ds_read_b128 v[18:21], v161
	ds_read_b128 v[22:25], v161 offset:1024
	ds_read_b128 v[26:29], v161 offset:2048
	ds_read_b128 v[30:33], v161 offset:3072
	s_addc_u32 s71, s43, s41
	s_ashr_i32 s67, s66, 31
	s_lshl_b64 s[40:41], s[66:67], 21
	s_add_u32 s72, s44, s40
	s_addc_u32 s73, s45, s41
	s_and_b64 s[40:41], s[8:9], exec
	s_cselect_b32 s67, s71, s79
	s_cselect_b32 s69, s70, s78
	s_cselect_b32 s92, s73, s77
	s_cselect_b32 s93, s72, s76
	v_lshl_add_u64 v[246:247], s[78:79], 0, v[146:147]
	s_mov_b32 m0, s88
	v_lshl_add_u64 v[66:67], v[246:247], 0, s[12:13]
	ds_read_b128 v[34:37], v162
	ds_read_b128 v[38:41], v162 offset:1024
	ds_read_b128 v[42:45], v162 offset:2048
	ds_read_b128 v[46:49], v162 offset:3072
	ds_read_b128 v[50:53], v162 offset:4096
	ds_read_b128 v[54:57], v162 offset:5120
	ds_read_b128 v[58:61], v162 offset:6144
	ds_read_b128 v[62:65], v162 offset:7168
	global_load_lds_dwordx4 v[66:67], off
	v_lshl_add_u64 v[66:67], v[246:247], 0, s[14:15]
	s_mov_b32 m0, s89
	s_nop 0
	global_load_lds_dwordx4 v[66:67], off
	s_waitcnt vmcnt(24)
	s_waitcnt lgkmcnt(0)
	s_barrier
	s_waitcnt lgkmcnt(0)
	v_mfma_f32_16x16x32_bf16 v[66:69], v[2:5], v[34:37], 0
	v_mfma_f32_16x16x32_bf16 v[70:73], v[10:13], v[34:37], 0
	v_mfma_f32_16x16x32_bf16 v[74:77], v[2:5], v[42:45], 0
	v_mfma_f32_16x16x32_bf16 v[78:81], v[10:13], v[42:45], 0
	v_mfma_f32_16x16x32_bf16 v[82:85], v[2:5], v[50:53], 0
	v_mfma_f32_16x16x32_bf16 v[86:89], v[10:13], v[50:53], 0
	v_mfma_f32_16x16x32_bf16 v[90:93], v[2:5], v[58:61], 0
	v_mfma_f32_16x16x32_bf16 v[94:97], v[10:13], v[58:61], 0
	v_mfma_f32_16x16x32_bf16 v[66:69], v[6:9], v[38:41], v[66:69]
	v_mfma_f32_16x16x32_bf16 v[70:73], v[14:17], v[38:41], v[70:73]
	v_mfma_f32_16x16x32_bf16 v[74:77], v[6:9], v[46:49], v[74:77]
	v_mfma_f32_16x16x32_bf16 v[78:81], v[14:17], v[46:49], v[78:81]
	v_mfma_f32_16x16x32_bf16 v[82:85], v[6:9], v[54:57], v[82:85]
	v_mfma_f32_16x16x32_bf16 v[86:89], v[14:17], v[54:57], v[86:89]
	v_mfma_f32_16x16x32_bf16 v[90:93], v[6:9], v[62:65], v[90:93]
	v_mfma_f32_16x16x32_bf16 v[94:97], v[14:17], v[62:65], v[94:97]
	v_mfma_f32_16x16x32_bf16 v[98:101], v[18:21], v[34:37], 0
	v_mfma_f32_16x16x32_bf16 v[34:37], v[26:29], v[34:37], 0
	v_mfma_f32_16x16x32_bf16 v[106:109], v[22:25], v[38:41], v[98:101]
	v_mfma_f32_16x16x32_bf16 v[34:37], v[30:33], v[38:41], v[34:37]
	v_mfma_f32_16x16x32_bf16 v[38:41], v[18:21], v[42:45], 0
	v_mfma_f32_16x16x32_bf16 v[42:45], v[26:29], v[42:45], 0
	v_mfma_f32_16x16x32_bf16 v[38:41], v[22:25], v[46:49], v[38:41]
	v_mfma_f32_16x16x32_bf16 v[42:45], v[30:33], v[46:49], v[42:45]
	v_mfma_f32_16x16x32_bf16 v[46:49], v[18:21], v[50:53], 0
	v_mfma_f32_16x16x32_bf16 v[50:53], v[26:29], v[50:53], 0
	v_mfma_f32_16x16x32_bf16 v[46:49], v[22:25], v[54:57], v[46:49]
	v_mfma_f32_16x16x32_bf16 v[50:53], v[30:33], v[54:57], v[50:53]
	v_mfma_f32_16x16x32_bf16 v[54:57], v[18:21], v[58:61], 0
	v_mfma_f32_16x16x32_bf16 v[58:61], v[26:29], v[58:61], 0
	v_mfma_f32_16x16x32_bf16 v[54:57], v[22:25], v[62:65], v[54:57]
	v_mfma_f32_16x16x32_bf16 v[58:61], v[30:33], v[62:65], v[58:61]
	s_barrier
	v_lshl_add_u64 v[248:249], s[76:77], 0, v[148:149]
	s_add_i32 s94, s85, s46
	v_lshl_add_u64 v[130:131], v[248:249], 0, s[16:17]
	s_mov_b32 m0, s94
	s_add_i32 s95, s94, 0x2000
	ds_read_b128 v[62:65], v162 offset:16384
	ds_read_b128 v[98:101], v162 offset:17408
	ds_read_b128 v[102:105], v162 offset:18432
	ds_read_b128 v[110:113], v162 offset:19456
	ds_read_b128 v[114:117], v162 offset:20480
	ds_read_b128 v[118:121], v162 offset:21504
	ds_read_b128 v[122:125], v162 offset:22528
	ds_read_b128 v[126:129], v162 offset:23552
	global_load_lds_dwordx4 v[130:131], off
	v_lshl_add_u64 v[130:131], v[248:249], 0, s[18:19]
	s_mov_b32 m0, s95
	s_add_i32 s96, s87, s46
	global_load_lds_dwordx4 v[130:131], off
	v_lshl_add_u64 v[130:131], v[248:249], 0, s[20:21]
	s_mov_b32 m0, s96
	s_add_i32 s40, s96, 0x2000
	global_load_lds_dwordx4 v[130:131], off
	v_lshl_add_u64 v[130:131], v[248:249], 0, s[22:23]
	s_mov_b32 m0, s40
	s_nop 0
	global_load_lds_dwordx4 v[130:131], off
	v_lshl_add_u64 v[130:131], v[246:247], 0, s[16:17]
	s_mov_b32 m0, s47
	s_nop 0
	global_load_lds_dwordx4 v[130:131], off
	v_lshl_add_u64 v[130:131], v[246:247], 0, s[18:19]
	s_mov_b32 m0, s52
	s_nop 0
	global_load_lds_dwordx4 v[130:131], off
	s_waitcnt vmcnt(24)
	s_waitcnt lgkmcnt(0)
	s_barrier
	s_waitcnt lgkmcnt(0)
	v_mfma_f32_16x16x32_bf16 v[130:133], v[2:5], v[62:65], 0
	v_mfma_f32_16x16x32_bf16 v[156:159], v[6:9], v[98:101], v[130:133]
	v_mfma_f32_16x16x32_bf16 v[130:133], v[10:13], v[62:65], 0
	v_mfma_f32_16x16x32_bf16 v[166:169], v[14:17], v[98:101], v[130:133]
	v_mfma_f32_16x16x32_bf16 v[130:133], v[2:5], v[102:105], 0
	v_mfma_f32_16x16x32_bf16 v[170:173], v[6:9], v[110:113], v[130:133]
	v_mfma_f32_16x16x32_bf16 v[130:133], v[10:13], v[102:105], 0
	v_mfma_f32_16x16x32_bf16 v[174:177], v[14:17], v[110:113], v[130:133]
	v_mfma_f32_16x16x32_bf16 v[130:133], v[2:5], v[114:117], 0
	v_mfma_f32_16x16x32_bf16 v[2:5], v[2:5], v[122:125], 0
	v_mfma_f32_16x16x32_bf16 v[178:181], v[6:9], v[118:121], v[130:133]
	v_mfma_f32_16x16x32_bf16 v[2:5], v[6:9], v[126:129], v[2:5]
	v_mfma_f32_16x16x32_bf16 v[6:9], v[10:13], v[122:125], 0
	v_mfma_f32_16x16x32_bf16 v[130:133], v[10:13], v[114:117], 0
	v_mfma_f32_16x16x32_bf16 v[6:9], v[14:17], v[126:129], v[6:9]
	v_mfma_f32_16x16x32_bf16 v[182:185], v[14:17], v[118:121], v[130:133]
	v_mfma_f32_16x16x32_bf16 v[10:13], v[18:21], v[62:65], 0
	v_mfma_f32_16x16x32_bf16 v[186:189], v[22:25], v[98:101], v[10:13]
	v_mfma_f32_16x16x32_bf16 v[10:13], v[26:29], v[62:65], 0
	v_mfma_f32_16x16x32_bf16 v[62:65], v[30:33], v[98:101], v[10:13]
	v_mfma_f32_16x16x32_bf16 v[10:13], v[18:21], v[102:105], 0
	v_mfma_f32_16x16x32_bf16 v[190:193], v[22:25], v[110:113], v[10:13]
	v_mfma_f32_16x16x32_bf16 v[10:13], v[26:29], v[102:105], 0
	v_mfma_f32_16x16x32_bf16 v[194:197], v[30:33], v[110:113], v[10:13]
	v_mfma_f32_16x16x32_bf16 v[10:13], v[18:21], v[114:117], 0
	v_mfma_f32_16x16x32_bf16 v[198:201], v[22:25], v[118:121], v[10:13]
	v_mfma_f32_16x16x32_bf16 v[10:13], v[26:29], v[114:117], 0
	v_mfma_f32_16x16x32_bf16 v[202:205], v[30:33], v[118:121], v[10:13]
	v_mfma_f32_16x16x32_bf16 v[10:13], v[18:21], v[122:125], 0
	v_mfma_f32_16x16x32_bf16 v[206:209], v[22:25], v[126:129], v[10:13]
	v_mfma_f32_16x16x32_bf16 v[10:13], v[26:29], v[122:125], 0
	v_mfma_f32_16x16x32_bf16 v[210:213], v[30:33], v[126:129], v[10:13]
	s_barrier
; #define PG8_WAIT_V(n) asm volatile("s_waitcnt vmcnt(" #n ")" ::: "memory")
; template <class Epi, class Sched, bool ALIGN_EPI = true, bool SP2 = true, bool FULLLINE = false, bool NOSTAGE = false, bool FP8 = false>
; __device__ __forceinline__ void gemm_phase(PG8_LAS unsigned char* lds, const Gemm g, const Sched& S, const Epi& E) {
;     ...
;         static_assert(SP2, "only the SP2 loop is kept");
;         { const int t = 0; if constexpr (Epi::NST == 16) PG8_ITER(PG8_WAIT_V(24)); else if constexpr (Epi::NST == 8) PG8_ITER(PG8_WAIT_V(16)); else PG8_ITER(PG8_WAIT_V(8)); }
;         for (int t = 2; t < nt; t += 2) PG8_ITER(PG8_WAIT_V(8));
	s_nop 5
	ds_read_b128 v[10:13], v163
	ds_read_b128 v[14:17], v163 offset:1024
	ds_read_b128 v[26:29], v163 offset:2048
	ds_read_b128 v[30:33], v163 offset:3072
	ds_read_b128 v[214:217], v164
	ds_read_b128 v[218:221], v164 offset:1024
	ds_read_b128 v[222:225], v164 offset:2048
	ds_read_b128 v[226:229], v164 offset:3072
	s_mov_b32 m0, s53
	v_lshl_add_u64 v[98:99], v[246:247], 0, s[20:21]
	ds_read_b128 v[18:21], v162 offset:32768
	ds_read_b128 v[22:25], v162 offset:33792
	ds_read_b128 v[110:113], v162 offset:34816
	ds_read_b128 v[122:125], v162 offset:35840
	ds_read_b128 v[230:233], v162 offset:36864
	ds_read_b128 v[234:237], v162 offset:37888
	ds_read_b128 v[238:241], v162 offset:38912
	ds_read_b128 v[242:245], v162 offset:39936
	global_load_lds_dwordx4 v[98:99], off
	v_lshl_add_u64 v[98:99], v[246:247], 0, s[22:23]
	s_mov_b32 m0, s54
	s_nop 0
	global_load_lds_dwordx4 v[98:99], off
	s_waitcnt vmcnt(8)
	s_waitcnt lgkmcnt(0)
	s_barrier
	s_waitcnt lgkmcnt(0)
	v_mfma_f32_16x16x32_bf16 v[66:69], v[10:13], v[18:21], v[66:69]
	v_mfma_f32_16x16x32_bf16 v[142:145], v[14:17], v[22:25], v[66:69]
	v_mfma_f32_16x16x32_bf16 v[66:69], v[26:29], v[18:21], v[70:73]
	v_mfma_f32_16x16x32_bf16 v[138:141], v[30:33], v[22:25], v[66:69]
	v_mfma_f32_16x16x32_bf16 v[66:69], v[10:13], v[110:113], v[74:77]
	v_mfma_f32_16x16x32_bf16 v[118:121], v[14:17], v[122:125], v[66:69]
	v_mfma_f32_16x16x32_bf16 v[66:69], v[26:29], v[110:113], v[78:81]
	v_mfma_f32_16x16x32_bf16 v[114:117], v[30:33], v[122:125], v[66:69]
	v_mfma_f32_16x16x32_bf16 v[66:69], v[10:13], v[230:233], v[82:85]
	v_mfma_f32_16x16x32_bf16 v[102:105], v[14:17], v[234:237], v[66:69]
	v_mfma_f32_16x16x32_bf16 v[66:69], v[26:29], v[230:233], v[86:89]
	v_mfma_f32_16x16x32_bf16 v[98:101], v[30:33], v[234:237], v[66:69]
	v_mfma_f32_16x16x32_bf16 v[66:69], v[10:13], v[238:241], v[90:93]
	v_mfma_f32_16x16x32_bf16 v[86:89], v[14:17], v[242:245], v[66:69]
	v_mfma_f32_16x16x32_bf16 v[66:69], v[26:29], v[238:241], v[94:97]
	v_mfma_f32_16x16x32_bf16 v[82:85], v[30:33], v[242:245], v[66:69]
	v_mfma_f32_16x16x32_bf16 v[66:69], v[214:217], v[18:21], v[106:109]
	v_mfma_f32_16x16x32_bf16 v[18:21], v[222:225], v[18:21], v[34:37]
	v_mfma_f32_16x16x32_bf16 v[130:133], v[226:229], v[22:25], v[18:21]
	v_mfma_f32_16x16x32_bf16 v[18:21], v[214:217], v[110:113], v[38:41]
	v_mfma_f32_16x16x32_bf16 v[126:129], v[218:221], v[122:125], v[18:21]
	v_mfma_f32_16x16x32_bf16 v[18:21], v[222:225], v[110:113], v[42:45]
	v_mfma_f32_16x16x32_bf16 v[122:125], v[226:229], v[122:125], v[18:21]
	v_mfma_f32_16x16x32_bf16 v[18:21], v[214:217], v[230:233], v[46:49]
	v_mfma_f32_16x16x32_bf16 v[110:113], v[218:221], v[234:237], v[18:21]
	v_mfma_f32_16x16x32_bf16 v[18:21], v[222:225], v[230:233], v[50:53]
	v_mfma_f32_16x16x32_bf16 v[106:109], v[226:229], v[234:237], v[18:21]
	v_mfma_f32_16x16x32_bf16 v[18:21], v[214:217], v[238:241], v[54:57]
	v_mfma_f32_16x16x32_bf16 v[94:97], v[218:221], v[242:245], v[18:21]
	v_mfma_f32_16x16x32_bf16 v[18:21], v[222:225], v[238:241], v[58:61]
	v_mfma_f32_16x16x32_bf16 v[134:137], v[218:221], v[22:25], v[66:69]
	v_mfma_f32_16x16x32_bf16 v[90:93], v[226:229], v[242:245], v[18:21]
	s_barrier
	s_add_i32 s41, s90, s46
	s_nop 3
	v_lshl_add_u64 v[18:19], v[248:249], 0, s[24:25]
	s_mov_b32 m0, s41
	s_add_i32 s50, s41, 0x2000
	ds_read_b128 v[34:37], v162 offset:49152
	ds_read_b128 v[38:41], v162 offset:50176
	ds_read_b128 v[42:45], v162 offset:51200
	ds_read_b128 v[46:49], v162 offset:52224
	ds_read_b128 v[230:233], v162 offset:53248
	ds_read_b128 v[234:237], v162 offset:54272
	ds_read_b128 v[238:241], v162 offset:55296
	ds_read_b128 v[242:245], v162 offset:56320
	global_load_lds_dwordx4 v[18:19], off
	v_lshl_add_u64 v[18:19], v[248:249], 0, s[26:27]
	s_mov_b32 m0, s50
	s_mov_b64 s[56:57], 0x100180
	s_add_i32 s51, s91, s46
	global_load_lds_dwordx4 v[18:19], off
	v_lshl_add_u64 v[18:19], v[248:249], 0, s[56:57]
	s_mov_b32 m0, s51
	s_mov_b64 s[56:57], 0x180180
	s_add_i32 s33, s51, 0x2000
	global_load_lds_dwordx4 v[18:19], off
	v_lshl_add_u64 v[18:19], v[248:249], 0, s[56:57]
	s_mov_b32 m0, s33
	s_nop 0
	global_load_lds_dwordx4 v[18:19], off
	v_lshl_add_u64 v[18:19], v[246:247], 0, s[24:25]
	s_mov_b32 m0, s55
	s_nop 0
	global_load_lds_dwordx4 v[18:19], off
	v_lshl_add_u64 v[18:19], v[246:247], 0, s[26:27]
	s_mov_b32 m0, s62
	s_nop 0
	global_load_lds_dwordx4 v[18:19], off
	s_waitcnt vmcnt(8)
	s_waitcnt lgkmcnt(0)
	s_barrier
	s_waitcnt lgkmcnt(0)
	v_mfma_f32_16x16x32_bf16 v[18:21], v[10:13], v[34:37], v[156:159]
	v_mfma_f32_16x16x32_bf16 v[70:73], v[14:17], v[38:41], v[18:21]
	v_mfma_f32_16x16x32_bf16 v[18:21], v[26:29], v[34:37], v[166:169]
	v_mfma_f32_16x16x32_bf16 v[66:69], v[30:33], v[38:41], v[18:21]
	v_mfma_f32_16x16x32_bf16 v[18:21], v[10:13], v[42:45], v[170:173]
	v_mfma_f32_16x16x32_bf16 v[54:57], v[14:17], v[46:49], v[18:21]
	v_mfma_f32_16x16x32_bf16 v[18:21], v[26:29], v[42:45], v[174:177]
	v_mfma_f32_16x16x32_bf16 v[50:53], v[30:33], v[46:49], v[18:21]
	v_mfma_f32_16x16x32_bf16 v[18:21], v[10:13], v[230:233], v[178:181]
	v_mfma_f32_16x16x32_bf16 v[2:5], v[10:13], v[238:241], v[2:5]
	v_mfma_f32_16x16x32_bf16 v[22:25], v[14:17], v[234:237], v[18:21]
	v_mfma_f32_16x16x32_bf16 v[18:21], v[26:29], v[230:233], v[182:185]
	v_mfma_f32_16x16x32_bf16 v[14:17], v[14:17], v[242:245], v[2:5]
	v_mfma_f32_16x16x32_bf16 v[2:5], v[26:29], v[238:241], v[6:9]
	v_mfma_f32_16x16x32_bf16 v[18:21], v[30:33], v[234:237], v[18:21]
	v_mfma_f32_16x16x32_bf16 v[10:13], v[30:33], v[242:245], v[2:5]
	v_mfma_f32_16x16x32_bf16 v[2:5], v[214:217], v[34:37], v[186:189]
	v_mfma_f32_16x16x32_bf16 v[78:81], v[218:221], v[38:41], v[2:5]
	v_mfma_f32_16x16x32_bf16 v[2:5], v[222:225], v[34:37], v[62:65]
	v_mfma_f32_16x16x32_bf16 v[74:77], v[226:229], v[38:41], v[2:5]
	v_mfma_f32_16x16x32_bf16 v[2:5], v[214:217], v[42:45], v[190:193]
	v_mfma_f32_16x16x32_bf16 v[62:65], v[218:221], v[46:49], v[2:5]
	v_mfma_f32_16x16x32_bf16 v[2:5], v[222:225], v[42:45], v[194:197]
	v_mfma_f32_16x16x32_bf16 v[58:61], v[226:229], v[46:49], v[2:5]
	v_mfma_f32_16x16x32_bf16 v[2:5], v[214:217], v[230:233], v[198:201]
	v_mfma_f32_16x16x32_bf16 v[30:33], v[218:221], v[234:237], v[2:5]
	v_mfma_f32_16x16x32_bf16 v[2:5], v[222:225], v[230:233], v[202:205]
	v_mfma_f32_16x16x32_bf16 v[26:29], v[226:229], v[234:237], v[2:5]
	v_mfma_f32_16x16x32_bf16 v[2:5], v[214:217], v[238:241], v[206:209]
	v_mfma_f32_16x16x32_bf16 v[6:9], v[218:221], v[242:245], v[2:5]
	v_mfma_f32_16x16x32_bf16 v[2:5], v[222:225], v[238:241], v[210:213]
	v_mfma_f32_16x16x32_bf16 v[2:5], v[226:229], v[242:245], v[2:5]
	s_barrier
	s_add_u32 s78, s78, 0x100180
	s_addc_u32 s79, s79, 0
	s_add_u32 s56, s76, 0x200
	s_addc_u32 s57, s77, 0
	s_mov_b32 s76, 0
	.p2align 6

; template <class Epi, class Sched, bool ALIGN_EPI = true, bool SP2 = true, bool FULLLINE = false, bool NOSTAGE = false, bool FP8 = false>
; __device__ __forceinline__ void gemm_phase(PG8_LAS unsigned char* lds, const Gemm g, const Sched& S, const Epi& E) {
;     ...
;         const bool has_next = S.next(ui + 1, nxt);
;         const char* nA = has_next ? PG8_ABASE(nxt) : cA; const char* nB = has_next ? PG8_BBASE(nxt) : cB;
.LBB0_766:
	s_ashr_i32 s69, s68, 31
	s_lshl_b64 s[40:41], s[68:69], 20
	s_add_u32 s70, s58, s40
	ds_read_b128 v[2:5], v1
	ds_read_b128 v[6:9], v1 offset:1024
	ds_read_b128 v[10:13], v1 offset:2048
	ds_read_b128 v[14:17], v1 offset:3072
	ds_read_b128 v[18:21], v142
	ds_read_b128 v[22:25], v142 offset:1024
	ds_read_b128 v[26:29], v142 offset:2048
	ds_read_b128 v[30:33], v142 offset:3072
	s_addc_u32 s71, s59, s41
	s_ashr_i32 s67, s66, 31
	s_lshl_b64 s[40:41], s[66:67], 20
	s_add_u32 s72, s3, s40
	s_addc_u32 s73, s42, s41
	s_and_b64 s[40:41], s[8:9], exec
	s_cselect_b32 s67, s71, s79
	s_cselect_b32 s69, s70, s78
	s_cselect_b32 s89, s73, s77
	s_cselect_b32 s90, s72, s76
	v_lshl_add_u64 v[140:141], s[78:79], 0, v[132:133]
	s_mov_b32 m0, s81
	v_lshl_add_u64 v[66:67], v[140:141], 0, s[12:13]
	ds_read_b128 v[34:37], v143
	ds_read_b128 v[38:41], v143 offset:1024
	ds_read_b128 v[42:45], v143 offset:2048
	ds_read_b128 v[46:49], v143 offset:3072
	ds_read_b128 v[50:53], v143 offset:4096
	ds_read_b128 v[54:57], v143 offset:5120
	ds_read_b128 v[58:61], v143 offset:6144
	ds_read_b128 v[62:65], v143 offset:7168
	global_load_lds_dwordx4 v[66:67], off
	v_lshl_add_u64 v[66:67], v[140:141], 0, s[14:15]
	s_mov_b32 m0, s82
	s_nop 0
	global_load_lds_dwordx4 v[66:67], off
	s_waitcnt vmcnt(16)
	s_waitcnt lgkmcnt(0)
	s_barrier
	s_waitcnt lgkmcnt(0)
	v_mfma_f32_16x16x32_bf16 v[86:89], v[10:13], v[50:53], 0
	v_mfma_f32_16x16x32_bf16 v[90:93], v[14:17], v[54:57], v[86:89]
	v_mfma_f32_16x16x32_bf16 v[86:89], v[2:5], v[58:61], 0
	v_mfma_f32_16x16x32_bf16 v[66:69], v[2:5], v[34:37], 0
	v_mfma_f32_16x16x32_bf16 v[70:73], v[10:13], v[34:37], 0
	v_mfma_f32_16x16x32_bf16 v[74:77], v[2:5], v[42:45], 0
	v_mfma_f32_16x16x32_bf16 v[78:81], v[10:13], v[42:45], 0
	v_mfma_f32_16x16x32_bf16 v[82:85], v[2:5], v[50:53], 0
	v_mfma_f32_16x16x32_bf16 v[94:97], v[6:9], v[62:65], v[86:89]
	v_mfma_f32_16x16x32_bf16 v[86:89], v[10:13], v[58:61], 0
	v_mfma_f32_16x16x32_bf16 v[66:69], v[6:9], v[38:41], v[66:69]
	v_mfma_f32_16x16x32_bf16 v[70:73], v[14:17], v[38:41], v[70:73]
	v_mfma_f32_16x16x32_bf16 v[74:77], v[6:9], v[46:49], v[74:77]
	v_mfma_f32_16x16x32_bf16 v[78:81], v[14:17], v[46:49], v[78:81]
	v_mfma_f32_16x16x32_bf16 v[82:85], v[6:9], v[54:57], v[82:85]
	v_mfma_f32_16x16x32_bf16 v[106:109], v[14:17], v[62:65], v[86:89]
	v_mfma_f32_16x16x32_bf16 v[86:89], v[18:21], v[34:37], 0
	v_mfma_f32_16x16x32_bf16 v[34:37], v[26:29], v[34:37], 0
	v_mfma_f32_16x16x32_bf16 v[110:113], v[22:25], v[38:41], v[86:89]
	v_mfma_f32_16x16x32_bf16 v[34:37], v[30:33], v[38:41], v[34:37]
	v_mfma_f32_16x16x32_bf16 v[38:41], v[18:21], v[42:45], 0
	v_mfma_f32_16x16x32_bf16 v[42:45], v[26:29], v[42:45], 0
	v_mfma_f32_16x16x32_bf16 v[38:41], v[22:25], v[46:49], v[38:41]
	v_mfma_f32_16x16x32_bf16 v[42:45], v[30:33], v[46:49], v[42:45]
	v_mfma_f32_16x16x32_bf16 v[46:49], v[18:21], v[50:53], 0
	v_mfma_f32_16x16x32_bf16 v[50:53], v[26:29], v[50:53], 0
	v_mfma_f32_16x16x32_bf16 v[46:49], v[22:25], v[54:57], v[46:49]
	v_mfma_f32_16x16x32_bf16 v[50:53], v[30:33], v[54:57], v[50:53]
	v_mfma_f32_16x16x32_bf16 v[54:57], v[18:21], v[58:61], 0
	v_mfma_f32_16x16x32_bf16 v[58:61], v[26:29], v[58:61], 0
	v_mfma_f32_16x16x32_bf16 v[54:57], v[22:25], v[62:65], v[54:57]
	v_mfma_f32_16x16x32_bf16 v[58:61], v[30:33], v[62:65], v[58:61]
	s_barrier
	v_lshl_add_u64 v[238:239], s[76:77], 0, v[130:131]
	s_mov_b32 m0, s83
	v_lshl_add_u64 v[146:147], v[238:239], 0, s[16:17]
	s_add_i32 s91, s83, 0x2000
	ds_read_b128 v[62:65], v143 offset:16384
	ds_read_b128 v[86:89], v143 offset:17408
	ds_read_b128 v[98:101], v143 offset:18432
	ds_read_b128 v[102:105], v143 offset:19456
	ds_read_b128 v[114:117], v143 offset:20480
	ds_read_b128 v[118:121], v143 offset:21504
	ds_read_b128 v[122:125], v143 offset:22528
	ds_read_b128 v[126:129], v143 offset:23552
	global_load_lds_dwordx4 v[146:147], off
	v_lshl_add_u64 v[146:147], v[238:239], 0, s[18:19]
	s_mov_b32 m0, s91
	s_add_i32 s92, s80, s43
	global_load_lds_dwordx4 v[146:147], off
	v_lshl_add_u64 v[146:147], v[238:239], 0, s[20:21]
	s_mov_b32 m0, s92
	s_add_i32 s40, s92, 0x2000
	global_load_lds_dwordx4 v[146:147], off
	v_lshl_add_u64 v[146:147], v[238:239], 0, s[22:23]
	s_mov_b32 m0, s40
	s_nop 0
	global_load_lds_dwordx4 v[146:147], off
	v_lshl_add_u64 v[146:147], v[140:141], 0, s[16:17]
	s_mov_b32 m0, s45
	s_nop 0
	global_load_lds_dwordx4 v[146:147], off
	v_lshl_add_u64 v[146:147], v[140:141], 0, s[18:19]
	s_mov_b32 m0, s46
	s_nop 0
	global_load_lds_dwordx4 v[146:147], off
	s_waitcnt vmcnt(16)
	s_waitcnt lgkmcnt(0)
	s_barrier
	s_waitcnt lgkmcnt(0)
	v_mfma_f32_16x16x32_bf16 v[146:149], v[2:5], v[62:65], 0
	v_mfma_f32_16x16x32_bf16 v[154:157], v[2:5], v[98:101], 0
	v_mfma_f32_16x16x32_bf16 v[162:165], v[2:5], v[114:117], 0
	v_mfma_f32_16x16x32_bf16 v[2:5], v[2:5], v[122:125], 0
	v_mfma_f32_16x16x32_bf16 v[146:149], v[6:9], v[86:89], v[146:149]
	v_mfma_f32_16x16x32_bf16 v[154:157], v[6:9], v[102:105], v[154:157]
	v_mfma_f32_16x16x32_bf16 v[162:165], v[6:9], v[118:121], v[162:165]
	v_mfma_f32_16x16x32_bf16 v[2:5], v[6:9], v[126:129], v[2:5]
	v_mfma_f32_16x16x32_bf16 v[6:9], v[10:13], v[122:125], 0
	v_mfma_f32_16x16x32_bf16 v[150:153], v[10:13], v[62:65], 0
	v_mfma_f32_16x16x32_bf16 v[158:161], v[10:13], v[98:101], 0
	v_mfma_f32_16x16x32_bf16 v[166:169], v[10:13], v[114:117], 0
	v_mfma_f32_16x16x32_bf16 v[10:13], v[14:17], v[126:129], v[6:9]
	v_mfma_f32_16x16x32_bf16 v[150:153], v[14:17], v[86:89], v[150:153]
	v_mfma_f32_16x16x32_bf16 v[158:161], v[14:17], v[102:105], v[158:161]
	v_mfma_f32_16x16x32_bf16 v[166:169], v[14:17], v[118:121], v[166:169]
	v_mfma_f32_16x16x32_bf16 v[6:9], v[18:21], v[62:65], 0
	v_mfma_f32_16x16x32_bf16 v[14:17], v[22:25], v[86:89], v[6:9]
	v_mfma_f32_16x16x32_bf16 v[6:9], v[26:29], v[62:65], 0
	v_mfma_f32_16x16x32_bf16 v[170:173], v[30:33], v[86:89], v[6:9]
	v_mfma_f32_16x16x32_bf16 v[6:9], v[18:21], v[98:101], 0
	v_mfma_f32_16x16x32_bf16 v[174:177], v[22:25], v[102:105], v[6:9]
	v_mfma_f32_16x16x32_bf16 v[6:9], v[26:29], v[98:101], 0
	v_mfma_f32_16x16x32_bf16 v[178:181], v[30:33], v[102:105], v[6:9]
	v_mfma_f32_16x16x32_bf16 v[6:9], v[18:21], v[114:117], 0
	v_mfma_f32_16x16x32_bf16 v[182:185], v[22:25], v[118:121], v[6:9]
	v_mfma_f32_16x16x32_bf16 v[6:9], v[26:29], v[114:117], 0
	v_mfma_f32_16x16x32_bf16 v[186:189], v[30:33], v[118:121], v[6:9]
	v_mfma_f32_16x16x32_bf16 v[6:9], v[18:21], v[122:125], 0
	v_mfma_f32_16x16x32_bf16 v[190:193], v[22:25], v[126:129], v[6:9]
	v_mfma_f32_16x16x32_bf16 v[6:9], v[26:29], v[122:125], 0
	v_mfma_f32_16x16x32_bf16 v[194:197], v[30:33], v[126:129], v[6:9]
	s_barrier
; #define PG8_WAIT_V(n) asm volatile("s_waitcnt vmcnt(" #n ")" ::: "memory")
; template <class Epi, class Sched, bool ALIGN_EPI = true, bool SP2 = true, bool FULLLINE = false, bool NOSTAGE = false, bool FP8 = false>
; __device__ __forceinline__ void gemm_phase(PG8_LAS unsigned char* lds, const Gemm g, const Sched& S, const Epi& E) {
;     ...
;         static_assert(SP2, "only the SP2 loop is kept");
;         { const int t = 0; if constexpr (Epi::NST == 16) PG8_ITER(PG8_WAIT_V(24)); else if constexpr (Epi::NST == 8) PG8_ITER(PG8_WAIT_V(16)); else PG8_ITER(PG8_WAIT_V(8)); }
;         for (int t = 2; t < nt; t += 2) PG8_ITER(PG8_WAIT_V(8));
	s_nop 5
	ds_read_b128 v[6:9], v144
	ds_read_b128 v[26:29], v144 offset:1024
	ds_read_b128 v[30:33], v144 offset:2048
	ds_read_b128 v[62:65], v144 offset:3072
	ds_read_b128 v[198:201], v145
	ds_read_b128 v[202:205], v145 offset:1024
	ds_read_b128 v[206:209], v145 offset:2048
	ds_read_b128 v[210:213], v145 offset:3072
	s_mov_b32 m0, s47
	v_lshl_add_u64 v[86:87], v[140:141], 0, s[20:21]
	ds_read_b128 v[18:21], v143 offset:32768
	ds_read_b128 v[22:25], v143 offset:33792
	ds_read_b128 v[214:217], v143 offset:34816
	ds_read_b128 v[218:221], v143 offset:35840
	ds_read_b128 v[222:225], v143 offset:36864
	ds_read_b128 v[226:229], v143 offset:37888
	ds_read_b128 v[230:233], v143 offset:38912
	ds_read_b128 v[234:237], v143 offset:39936
	global_load_lds_dwordx4 v[86:87], off
	v_lshl_add_u64 v[86:87], v[140:141], 0, s[22:23]
	s_mov_b32 m0, s52
	s_nop 0
	global_load_lds_dwordx4 v[86:87], off
	s_waitcnt vmcnt(8)
	s_waitcnt lgkmcnt(0)
	s_barrier
	s_waitcnt lgkmcnt(0)
	v_mfma_f32_16x16x32_bf16 v[66:69], v[6:9], v[18:21], v[66:69]
	v_mfma_f32_16x16x32_bf16 v[118:121], v[26:29], v[22:25], v[66:69]
	v_mfma_f32_16x16x32_bf16 v[66:69], v[30:33], v[18:21], v[70:73]
	v_mfma_f32_16x16x32_bf16 v[114:117], v[62:65], v[22:25], v[66:69]
	v_mfma_f32_16x16x32_bf16 v[66:69], v[6:9], v[214:217], v[74:77]
	v_mfma_f32_16x16x32_bf16 v[102:105], v[26:29], v[218:221], v[66:69]
	v_mfma_f32_16x16x32_bf16 v[66:69], v[30:33], v[214:217], v[78:81]
	v_mfma_f32_16x16x32_bf16 v[98:101], v[62:65], v[218:221], v[66:69]
	v_mfma_f32_16x16x32_bf16 v[66:69], v[6:9], v[222:225], v[82:85]
	v_mfma_f32_16x16x32_bf16 v[86:89], v[26:29], v[226:229], v[66:69]
	v_mfma_f32_16x16x32_bf16 v[66:69], v[30:33], v[222:225], v[90:93]
	v_mfma_f32_16x16x32_bf16 v[82:85], v[62:65], v[226:229], v[66:69]
	v_mfma_f32_16x16x32_bf16 v[66:69], v[6:9], v[230:233], v[94:97]
	v_mfma_f32_16x16x32_bf16 v[70:73], v[26:29], v[234:237], v[66:69]
	v_mfma_f32_16x16x32_bf16 v[66:69], v[30:33], v[230:233], v[106:109]
	v_mfma_f32_16x16x32_bf16 v[66:69], v[62:65], v[234:237], v[66:69]
	v_mfma_f32_16x16x32_bf16 v[74:77], v[198:201], v[18:21], v[110:113]
	v_mfma_f32_16x16x32_bf16 v[18:21], v[206:209], v[18:21], v[34:37]
	v_mfma_f32_16x16x32_bf16 v[122:125], v[210:213], v[22:25], v[18:21]
	v_mfma_f32_16x16x32_bf16 v[18:21], v[198:201], v[214:217], v[38:41]
	v_mfma_f32_16x16x32_bf16 v[110:113], v[202:205], v[218:221], v[18:21]
	v_mfma_f32_16x16x32_bf16 v[18:21], v[206:209], v[214:217], v[42:45]
	v_mfma_f32_16x16x32_bf16 v[106:109], v[210:213], v[218:221], v[18:21]
	v_mfma_f32_16x16x32_bf16 v[18:21], v[198:201], v[222:225], v[46:49]
	v_mfma_f32_16x16x32_bf16 v[94:97], v[202:205], v[226:229], v[18:21]
	v_mfma_f32_16x16x32_bf16 v[18:21], v[206:209], v[222:225], v[50:53]
	v_mfma_f32_16x16x32_bf16 v[90:93], v[210:213], v[226:229], v[18:21]
	v_mfma_f32_16x16x32_bf16 v[18:21], v[198:201], v[230:233], v[54:57]
	v_mfma_f32_16x16x32_bf16 v[78:81], v[202:205], v[234:237], v[18:21]
	v_mfma_f32_16x16x32_bf16 v[18:21], v[206:209], v[230:233], v[58:61]
	v_mfma_f32_16x16x32_bf16 v[126:129], v[202:205], v[22:25], v[74:77]
	v_mfma_f32_16x16x32_bf16 v[74:77], v[210:213], v[234:237], v[18:21]
	s_barrier
	s_add_i32 s41, s84, s43
	s_nop 3
	v_lshl_add_u64 v[18:19], v[238:239], 0, s[24:25]
	s_mov_b32 m0, s41
	s_add_i32 s50, s41, 0x2000
	ds_read_b128 v[42:45], v143 offset:49152
	ds_read_b128 v[46:49], v143 offset:50176
	ds_read_b128 v[214:217], v143 offset:51200
	ds_read_b128 v[218:221], v143 offset:52224
	ds_read_b128 v[222:225], v143 offset:53248
	ds_read_b128 v[226:229], v143 offset:54272
	ds_read_b128 v[230:233], v143 offset:55296
	ds_read_b128 v[234:237], v143 offset:56320
	global_load_lds_dwordx4 v[18:19], off
	v_lshl_add_u64 v[18:19], v[238:239], 0, s[26:27]
	s_mov_b32 m0, s50
	s_mov_b64 s[56:57], 0x80180
	s_add_i32 s51, s85, s43
	global_load_lds_dwordx4 v[18:19], off
	v_lshl_add_u64 v[18:19], v[238:239], 0, s[56:57]
	s_mov_b32 m0, s51
	s_mov_b64 s[56:57], 0xc0180
	s_add_i32 s33, s51, 0x2000
	global_load_lds_dwordx4 v[18:19], off
	v_lshl_add_u64 v[18:19], v[238:239], 0, s[56:57]
	s_mov_b32 m0, s33
	s_nop 0
	global_load_lds_dwordx4 v[18:19], off
	v_lshl_add_u64 v[18:19], v[140:141], 0, s[24:25]
	s_mov_b32 m0, s53
	s_nop 0
	global_load_lds_dwordx4 v[18:19], off
	v_lshl_add_u64 v[18:19], v[140:141], 0, s[26:27]
	s_mov_b32 m0, s54
	s_nop 0
	global_load_lds_dwordx4 v[18:19], off
	s_waitcnt vmcnt(8)
	s_waitcnt lgkmcnt(0)
	s_barrier
	s_waitcnt lgkmcnt(0)
	v_mfma_f32_16x16x32_bf16 v[18:21], v[6:9], v[42:45], v[146:149]
	v_mfma_f32_16x16x32_bf16 v[54:57], v[26:29], v[46:49], v[18:21]
	v_mfma_f32_16x16x32_bf16 v[18:21], v[30:33], v[42:45], v[150:153]
	v_mfma_f32_16x16x32_bf16 v[50:53], v[62:65], v[46:49], v[18:21]
	v_mfma_f32_16x16x32_bf16 v[18:21], v[6:9], v[214:217], v[154:157]
	v_mfma_f32_16x16x32_bf16 v[38:41], v[26:29], v[218:221], v[18:21]
	v_mfma_f32_16x16x32_bf16 v[18:21], v[30:33], v[214:217], v[158:161]
	v_mfma_f32_16x16x32_bf16 v[34:37], v[62:65], v[218:221], v[18:21]
	v_mfma_f32_16x16x32_bf16 v[18:21], v[6:9], v[222:225], v[162:165]
	v_mfma_f32_16x16x32_bf16 v[2:5], v[6:9], v[230:233], v[2:5]
	v_mfma_f32_16x16x32_bf16 v[22:25], v[26:29], v[226:229], v[18:21]
	v_mfma_f32_16x16x32_bf16 v[18:21], v[30:33], v[222:225], v[166:169]
	v_mfma_f32_16x16x32_bf16 v[6:9], v[26:29], v[234:237], v[2:5]
	v_mfma_f32_16x16x32_bf16 v[2:5], v[30:33], v[230:233], v[10:13]
	v_mfma_f32_16x16x32_bf16 v[18:21], v[62:65], v[226:229], v[18:21]
	v_mfma_f32_16x16x32_bf16 v[2:5], v[62:65], v[234:237], v[2:5]
	v_mfma_f32_16x16x32_bf16 v[10:13], v[198:201], v[42:45], v[14:17]
	v_mfma_f32_16x16x32_bf16 v[62:65], v[202:205], v[46:49], v[10:13]
	v_mfma_f32_16x16x32_bf16 v[10:13], v[206:209], v[42:45], v[170:173]
	v_mfma_f32_16x16x32_bf16 v[58:61], v[210:213], v[46:49], v[10:13]
	v_mfma_f32_16x16x32_bf16 v[10:13], v[198:201], v[214:217], v[174:177]
	v_mfma_f32_16x16x32_bf16 v[46:49], v[202:205], v[218:221], v[10:13]
	v_mfma_f32_16x16x32_bf16 v[10:13], v[206:209], v[214:217], v[178:181]
	v_mfma_f32_16x16x32_bf16 v[42:45], v[210:213], v[218:221], v[10:13]
	v_mfma_f32_16x16x32_bf16 v[10:13], v[198:201], v[222:225], v[182:185]
	v_mfma_f32_16x16x32_bf16 v[30:33], v[202:205], v[226:229], v[10:13]
	v_mfma_f32_16x16x32_bf16 v[10:13], v[206:209], v[222:225], v[186:189]
	v_mfma_f32_16x16x32_bf16 v[26:29], v[210:213], v[226:229], v[10:13]
	v_mfma_f32_16x16x32_bf16 v[10:13], v[198:201], v[230:233], v[190:193]
	v_mfma_f32_16x16x32_bf16 v[14:17], v[202:205], v[234:237], v[10:13]
	v_mfma_f32_16x16x32_bf16 v[10:13], v[206:209], v[230:233], v[194:197]
	v_mfma_f32_16x16x32_bf16 v[10:13], v[210:213], v[234:237], v[10:13]
	s_barrier
	s_add_u32 s78, s78, 0x80180
	s_addc_u32 s79, s79, 0
	s_add_u32 s56, s76, 0x200
	s_addc_u32 s57, s77, 0
	s_mov_b32 s76, 0
	.p2align 6

.LBB0_869:
	ds_read_b128 v[2:5], v1
	ds_read_b128 v[6:9], v1 offset:1024
	ds_read_b128 v[10:13], v1 offset:2048
	ds_read_b128 v[14:17], v1 offset:3072
	ds_read_b128 v[18:21], v192
	ds_read_b128 v[22:25], v192 offset:1024
	ds_read_b128 v[26:29], v192 offset:2048
	ds_read_b128 v[30:33], v192 offset:3072
	v_lshl_add_u64 v[248:249], s[70:71], 0, v[170:171]
	s_add_i32 s85, s45, 0xc000
	v_lshl_add_u64 v[66:67], v[248:249], 0, s[14:15]
	s_mov_b32 m0, s85
	s_add_i32 s87, s45, 0xe000
	ds_read_b128 v[34:37], v193
	ds_read_b128 v[38:41], v193 offset:1024
	ds_read_b128 v[42:45], v193 offset:2048
	ds_read_b128 v[46:49], v193 offset:3072
	ds_read_b128 v[50:53], v193 offset:4096
	ds_read_b128 v[54:57], v193 offset:5120
	ds_read_b128 v[58:61], v193 offset:6144
	ds_read_b128 v[62:65], v193 offset:7168
	global_load_lds_dwordx4 v[66:67], off
	v_lshl_add_u64 v[66:67], v[248:249], 0, s[16:17]
	s_mov_b32 m0, s87
	s_nop 0
	global_load_lds_dwordx4 v[66:67], off
	s_waitcnt vmcnt(24)
	s_waitcnt lgkmcnt(0)
	s_barrier
	s_waitcnt lgkmcnt(0)
	v_mfma_f32_16x16x32_bf16 v[66:69], v[2:5], v[34:37], 0
	v_mfma_f32_16x16x32_bf16 v[70:73], v[10:13], v[34:37], 0
	v_mfma_f32_16x16x32_bf16 v[78:81], v[10:13], v[42:45], 0
	v_mfma_f32_16x16x32_bf16 v[86:89], v[10:13], v[50:53], 0
	v_mfma_f32_16x16x32_bf16 v[66:69], v[6:9], v[38:41], v[66:69]
	v_mfma_f32_16x16x32_bf16 v[70:73], v[14:17], v[38:41], v[70:73]
	v_mfma_f32_16x16x32_bf16 v[74:77], v[2:5], v[42:45], 0
	v_mfma_f32_16x16x32_bf16 v[78:81], v[14:17], v[46:49], v[78:81]
	v_mfma_f32_16x16x32_bf16 v[82:85], v[2:5], v[50:53], 0
	v_mfma_f32_16x16x32_bf16 v[86:89], v[14:17], v[54:57], v[86:89]
	v_mfma_f32_16x16x32_bf16 v[90:93], v[2:5], v[58:61], 0
	v_mfma_f32_16x16x32_bf16 v[94:97], v[10:13], v[58:61], 0
	v_mfma_f32_16x16x32_bf16 v[74:77], v[6:9], v[46:49], v[74:77]
	v_mfma_f32_16x16x32_bf16 v[82:85], v[6:9], v[54:57], v[82:85]
	v_mfma_f32_16x16x32_bf16 v[90:93], v[6:9], v[62:65], v[90:93]
	v_mfma_f32_16x16x32_bf16 v[94:97], v[14:17], v[62:65], v[94:97]
	v_mfma_f32_16x16x32_bf16 v[98:101], v[18:21], v[34:37], 0
	v_mfma_f32_16x16x32_bf16 v[34:37], v[26:29], v[34:37], 0
	v_mfma_f32_16x16x32_bf16 v[98:101], v[22:25], v[38:41], v[98:101]
	v_mfma_f32_16x16x32_bf16 v[34:37], v[30:33], v[38:41], v[34:37]
	v_mfma_f32_16x16x32_bf16 v[38:41], v[18:21], v[42:45], 0
	v_mfma_f32_16x16x32_bf16 v[42:45], v[26:29], v[42:45], 0
	v_mfma_f32_16x16x32_bf16 v[38:41], v[22:25], v[46:49], v[38:41]
	v_mfma_f32_16x16x32_bf16 v[42:45], v[30:33], v[46:49], v[42:45]
	v_mfma_f32_16x16x32_bf16 v[46:49], v[18:21], v[50:53], 0
	v_mfma_f32_16x16x32_bf16 v[50:53], v[26:29], v[50:53], 0
	v_mfma_f32_16x16x32_bf16 v[46:49], v[22:25], v[54:57], v[46:49]
	v_mfma_f32_16x16x32_bf16 v[50:53], v[30:33], v[54:57], v[50:53]
	v_mfma_f32_16x16x32_bf16 v[54:57], v[18:21], v[58:61], 0
	v_mfma_f32_16x16x32_bf16 v[58:61], v[26:29], v[58:61], 0
	v_mfma_f32_16x16x32_bf16 v[54:57], v[22:25], v[62:65], v[54:57]
	v_mfma_f32_16x16x32_bf16 v[58:61], v[30:33], v[62:65], v[58:61]
	s_barrier
	v_lshl_add_u64 v[250:251], s[72:73], 0, v[172:173]
	s_add_i32 s88, s77, s44
	v_lshl_add_u64 v[130:131], v[250:251], 0, s[18:19]
	s_mov_b32 m0, s88
	s_add_i32 s89, s88, 0x2000
	ds_read_b128 v[62:65], v193 offset:16384
	ds_read_b128 v[102:105], v193 offset:17408
	ds_read_b128 v[106:109], v193 offset:18432
	ds_read_b128 v[110:113], v193 offset:19456
	ds_read_b128 v[114:117], v193 offset:20480
	ds_read_b128 v[118:121], v193 offset:21504
	ds_read_b128 v[122:125], v193 offset:22528
	ds_read_b128 v[126:129], v193 offset:23552
	global_load_lds_dwordx4 v[130:131], off
	v_lshl_add_u64 v[130:131], v[250:251], 0, s[20:21]
	s_mov_b32 m0, s89
	s_add_i32 s90, s78, s44
	global_load_lds_dwordx4 v[130:131], off
	v_lshl_add_u64 v[130:131], v[250:251], 0, s[22:23]
	s_mov_b32 m0, s90
	s_add_i32 s40, s90, 0x2000
	global_load_lds_dwordx4 v[130:131], off
	v_lshl_add_u64 v[130:131], v[250:251], 0, s[24:25]
	s_mov_b32 m0, s40
	s_nop 0
	global_load_lds_dwordx4 v[130:131], off
	v_lshl_add_u64 v[130:131], v[248:249], 0, s[18:19]
	s_mov_b32 m0, s45
	s_nop 0
	global_load_lds_dwordx4 v[130:131], off
	v_lshl_add_u64 v[130:131], v[248:249], 0, s[20:21]
	s_mov_b32 m0, s46
	s_nop 0
	global_load_lds_dwordx4 v[130:131], off
	s_waitcnt vmcnt(24)
	s_waitcnt lgkmcnt(0)
	s_barrier
	s_waitcnt lgkmcnt(0)
	v_mfma_f32_16x16x32_bf16 v[130:133], v[2:5], v[62:65], 0
	v_mfma_f32_16x16x32_bf16 v[138:141], v[6:9], v[102:105], v[130:133]
	v_mfma_f32_16x16x32_bf16 v[130:133], v[10:13], v[62:65], 0
	v_mfma_f32_16x16x32_bf16 v[150:153], v[14:17], v[102:105], v[130:133]
	v_mfma_f32_16x16x32_bf16 v[130:133], v[2:5], v[106:109], 0
	v_mfma_f32_16x16x32_bf16 v[154:157], v[6:9], v[110:113], v[130:133]
	v_mfma_f32_16x16x32_bf16 v[130:133], v[10:13], v[106:109], 0
	v_mfma_f32_16x16x32_bf16 v[158:161], v[14:17], v[110:113], v[130:133]
	v_mfma_f32_16x16x32_bf16 v[130:133], v[2:5], v[114:117], 0
	v_mfma_f32_16x16x32_bf16 v[2:5], v[2:5], v[122:125], 0
	v_mfma_f32_16x16x32_bf16 v[162:165], v[6:9], v[118:121], v[130:133]
	v_mfma_f32_16x16x32_bf16 v[2:5], v[6:9], v[126:129], v[2:5]
	v_mfma_f32_16x16x32_bf16 v[6:9], v[10:13], v[122:125], 0
	v_mfma_f32_16x16x32_bf16 v[130:133], v[10:13], v[114:117], 0
	v_mfma_f32_16x16x32_bf16 v[6:9], v[14:17], v[126:129], v[6:9]
	v_mfma_f32_16x16x32_bf16 v[166:169], v[14:17], v[118:121], v[130:133]
	v_mfma_f32_16x16x32_bf16 v[10:13], v[18:21], v[62:65], 0
	v_mfma_f32_16x16x32_bf16 v[180:183], v[22:25], v[102:105], v[10:13]
	v_mfma_f32_16x16x32_bf16 v[10:13], v[26:29], v[62:65], 0
	v_mfma_f32_16x16x32_bf16 v[184:187], v[30:33], v[102:105], v[10:13]
	v_mfma_f32_16x16x32_bf16 v[10:13], v[18:21], v[106:109], 0
	v_mfma_f32_16x16x32_bf16 v[188:191], v[22:25], v[110:113], v[10:13]
	v_mfma_f32_16x16x32_bf16 v[10:13], v[26:29], v[106:109], 0
	v_mfma_f32_16x16x32_bf16 v[196:199], v[30:33], v[110:113], v[10:13]
	v_mfma_f32_16x16x32_bf16 v[10:13], v[18:21], v[114:117], 0
	v_mfma_f32_16x16x32_bf16 v[200:203], v[22:25], v[118:121], v[10:13]
	v_mfma_f32_16x16x32_bf16 v[10:13], v[26:29], v[114:117], 0
	v_mfma_f32_16x16x32_bf16 v[204:207], v[30:33], v[118:121], v[10:13]
	v_mfma_f32_16x16x32_bf16 v[10:13], v[18:21], v[122:125], 0
	v_mfma_f32_16x16x32_bf16 v[208:211], v[22:25], v[126:129], v[10:13]
	v_mfma_f32_16x16x32_bf16 v[10:13], v[26:29], v[122:125], 0
	v_mfma_f32_16x16x32_bf16 v[212:215], v[30:33], v[126:129], v[10:13]
	s_barrier
; #define PG8_WAIT_V(n) asm volatile("s_waitcnt vmcnt(" #n ")" ::: "memory")
; template <class Epi, class Sched, bool ALIGN_EPI = true, bool SP2 = true, bool FULLLINE = false, bool NOSTAGE = false, bool FP8 = false>
; __device__ __forceinline__ void gemm_phase(PG8_LAS unsigned char* lds, const Gemm g, const Sched& S, const Epi& E) {
;     ...
;         static_assert(SP2, "only the SP2 loop is kept");
;         { const int t = 0; if constexpr (Epi::NST == 16) PG8_ITER(PG8_WAIT_V(24)); else if constexpr (Epi::NST == 8) PG8_ITER(PG8_WAIT_V(16)); else PG8_ITER(PG8_WAIT_V(8)); }
;         for (int t = 2; t < nt; t += 2) PG8_ITER(PG8_WAIT_V(8));
	s_nop 5
	ds_read_b128 v[10:13], v194
	ds_read_b128 v[14:17], v194 offset:1024
	ds_read_b128 v[18:21], v194 offset:2048
	ds_read_b128 v[22:25], v194 offset:3072
	ds_read_b128 v[216:219], v195
	ds_read_b128 v[220:223], v195 offset:1024
	ds_read_b128 v[224:227], v195 offset:2048
	ds_read_b128 v[228:231], v195 offset:3072
	s_mov_b32 m0, s47
	v_lshl_add_u64 v[106:107], v[248:249], 0, s[22:23]
	ds_read_b128 v[26:29], v193 offset:32768
	ds_read_b128 v[30:33], v193 offset:33792
	ds_read_b128 v[62:65], v193 offset:34816
	ds_read_b128 v[102:105], v193 offset:35840
	ds_read_b128 v[232:235], v193 offset:36864
	ds_read_b128 v[236:239], v193 offset:37888
	ds_read_b128 v[240:243], v193 offset:38912
	ds_read_b128 v[244:247], v193 offset:39936
	global_load_lds_dwordx4 v[106:107], off
	v_lshl_add_u64 v[106:107], v[248:249], 0, s[24:25]
	s_mov_b32 m0, s52
	s_nop 0
	global_load_lds_dwordx4 v[106:107], off
	s_waitcnt vmcnt(8)
	s_waitcnt lgkmcnt(0)
	s_barrier
	s_waitcnt lgkmcnt(0)
	v_mfma_f32_16x16x32_bf16 v[66:69], v[10:13], v[26:29], v[66:69]
	v_mfma_f32_16x16x32_bf16 v[146:149], v[14:17], v[30:33], v[66:69]
	v_mfma_f32_16x16x32_bf16 v[66:69], v[18:21], v[26:29], v[70:73]
	v_mfma_f32_16x16x32_bf16 v[142:145], v[22:25], v[30:33], v[66:69]
	v_mfma_f32_16x16x32_bf16 v[66:69], v[10:13], v[62:65], v[74:77]
	v_mfma_f32_16x16x32_bf16 v[126:129], v[14:17], v[102:105], v[66:69]
	v_mfma_f32_16x16x32_bf16 v[66:69], v[18:21], v[62:65], v[78:81]
	v_mfma_f32_16x16x32_bf16 v[122:125], v[22:25], v[102:105], v[66:69]
	v_mfma_f32_16x16x32_bf16 v[66:69], v[10:13], v[232:235], v[82:85]
	v_mfma_f32_16x16x32_bf16 v[110:113], v[14:17], v[236:239], v[66:69]
	v_mfma_f32_16x16x32_bf16 v[66:69], v[18:21], v[232:235], v[86:89]
	v_mfma_f32_16x16x32_bf16 v[106:109], v[22:25], v[236:239], v[66:69]
	v_mfma_f32_16x16x32_bf16 v[66:69], v[10:13], v[240:243], v[90:93]
	v_mfma_f32_16x16x32_bf16 v[86:89], v[14:17], v[244:247], v[66:69]
	v_mfma_f32_16x16x32_bf16 v[66:69], v[18:21], v[240:243], v[94:97]
	v_mfma_f32_16x16x32_bf16 v[78:81], v[22:25], v[244:247], v[66:69]
	v_mfma_f32_16x16x32_bf16 v[66:69], v[216:219], v[26:29], v[98:101]
	v_mfma_f32_16x16x32_bf16 v[26:29], v[224:227], v[26:29], v[34:37]
	v_mfma_f32_16x16x32_bf16 v[130:133], v[228:231], v[30:33], v[26:29]
	v_mfma_f32_16x16x32_bf16 v[26:29], v[216:219], v[62:65], v[38:41]
	v_mfma_f32_16x16x32_bf16 v[118:121], v[220:223], v[102:105], v[26:29]
	v_mfma_f32_16x16x32_bf16 v[26:29], v[224:227], v[62:65], v[42:45]
	v_mfma_f32_16x16x32_bf16 v[114:117], v[228:231], v[102:105], v[26:29]
	v_mfma_f32_16x16x32_bf16 v[26:29], v[216:219], v[232:235], v[46:49]
	v_mfma_f32_16x16x32_bf16 v[102:105], v[220:223], v[236:239], v[26:29]
	v_mfma_f32_16x16x32_bf16 v[26:29], v[224:227], v[232:235], v[50:53]
	v_mfma_f32_16x16x32_bf16 v[98:101], v[228:231], v[236:239], v[26:29]
	v_mfma_f32_16x16x32_bf16 v[26:29], v[216:219], v[240:243], v[54:57]
	v_mfma_f32_16x16x32_bf16 v[70:73], v[220:223], v[244:247], v[26:29]
	v_mfma_f32_16x16x32_bf16 v[26:29], v[224:227], v[240:243], v[58:61]
	v_mfma_f32_16x16x32_bf16 v[134:137], v[220:223], v[30:33], v[66:69]
	v_mfma_f32_16x16x32_bf16 v[66:69], v[228:231], v[244:247], v[26:29]
	s_barrier
	s_add_i32 s41, s79, s44
	s_nop 3
	v_lshl_add_u64 v[26:27], v[250:251], 0, s[26:27]
	s_mov_b32 m0, s41
	s_add_i32 s50, s41, 0x2000
	ds_read_b128 v[34:37], v193 offset:49152
	ds_read_b128 v[38:41], v193 offset:50176
	ds_read_b128 v[74:77], v193 offset:51200
	ds_read_b128 v[82:85], v193 offset:52224
	ds_read_b128 v[90:93], v193 offset:53248
	ds_read_b128 v[94:97], v193 offset:54272
	ds_read_b128 v[232:235], v193 offset:55296
	ds_read_b128 v[236:239], v193 offset:56320
	global_load_lds_dwordx4 v[26:27], off
	v_lshl_add_u64 v[26:27], v[250:251], 0, s[28:29]
	s_mov_b32 m0, s50
	s_mov_b64 s[56:57], 0x160180
	s_add_i32 s51, s80, s44
	global_load_lds_dwordx4 v[26:27], off
	v_lshl_add_u64 v[26:27], v[250:251], 0, s[56:57]
	s_mov_b32 m0, s51
	s_mov_b64 s[56:57], 0x210180
	s_add_i32 s33, s51, 0x2000
	global_load_lds_dwordx4 v[26:27], off
	v_lshl_add_u64 v[26:27], v[250:251], 0, s[56:57]
	s_mov_b32 m0, s33
	s_nop 0
	global_load_lds_dwordx4 v[26:27], off
	v_lshl_add_u64 v[26:27], v[248:249], 0, s[26:27]
	s_mov_b32 m0, s53
	s_nop 0
	global_load_lds_dwordx4 v[26:27], off
	v_lshl_add_u64 v[26:27], v[248:249], 0, s[28:29]
	s_mov_b32 m0, s54
	s_nop 0
	global_load_lds_dwordx4 v[26:27], off
	s_waitcnt vmcnt(8)
	s_waitcnt lgkmcnt(0)
	s_barrier
	s_waitcnt lgkmcnt(0)
	v_mfma_f32_16x16x32_bf16 v[26:29], v[10:13], v[34:37], v[138:141]
	v_mfma_f32_16x16x32_bf16 v[62:65], v[14:17], v[38:41], v[26:29]
	v_mfma_f32_16x16x32_bf16 v[26:29], v[18:21], v[34:37], v[150:153]
	v_mfma_f32_16x16x32_bf16 v[58:61], v[22:25], v[38:41], v[26:29]
	v_mfma_f32_16x16x32_bf16 v[26:29], v[10:13], v[74:77], v[154:157]
	v_mfma_f32_16x16x32_bf16 v[46:49], v[14:17], v[82:85], v[26:29]
	v_mfma_f32_16x16x32_bf16 v[26:29], v[18:21], v[74:77], v[158:161]
	v_mfma_f32_16x16x32_bf16 v[42:45], v[22:25], v[82:85], v[26:29]
	v_mfma_f32_16x16x32_bf16 v[26:29], v[10:13], v[90:93], v[162:165]
	v_mfma_f32_16x16x32_bf16 v[2:5], v[10:13], v[232:235], v[2:5]
	v_mfma_f32_16x16x32_bf16 v[30:33], v[14:17], v[94:97], v[26:29]
	v_mfma_f32_16x16x32_bf16 v[26:29], v[18:21], v[90:93], v[166:169]
	v_mfma_f32_16x16x32_bf16 v[14:17], v[14:17], v[236:239], v[2:5]
	v_mfma_f32_16x16x32_bf16 v[2:5], v[18:21], v[232:235], v[6:9]
	v_mfma_f32_16x16x32_bf16 v[26:29], v[22:25], v[94:97], v[26:29]
	v_mfma_f32_16x16x32_bf16 v[10:13], v[22:25], v[236:239], v[2:5]
	v_mfma_f32_16x16x32_bf16 v[2:5], v[216:219], v[34:37], v[180:183]
	v_mfma_f32_16x16x32_bf16 v[54:57], v[220:223], v[38:41], v[2:5]
	v_mfma_f32_16x16x32_bf16 v[2:5], v[224:227], v[34:37], v[184:187]
	v_mfma_f32_16x16x32_bf16 v[50:53], v[228:231], v[38:41], v[2:5]
	v_mfma_f32_16x16x32_bf16 v[2:5], v[216:219], v[74:77], v[188:191]
	v_mfma_f32_16x16x32_bf16 v[38:41], v[220:223], v[82:85], v[2:5]
	v_mfma_f32_16x16x32_bf16 v[2:5], v[224:227], v[74:77], v[196:199]
	v_mfma_f32_16x16x32_bf16 v[34:37], v[228:231], v[82:85], v[2:5]
	v_mfma_f32_16x16x32_bf16 v[2:5], v[216:219], v[90:93], v[200:203]
	v_mfma_f32_16x16x32_bf16 v[22:25], v[220:223], v[94:97], v[2:5]
	v_mfma_f32_16x16x32_bf16 v[2:5], v[224:227], v[90:93], v[204:207]
	v_mfma_f32_16x16x32_bf16 v[18:21], v[228:231], v[94:97], v[2:5]
	v_mfma_f32_16x16x32_bf16 v[2:5], v[216:219], v[232:235], v[208:211]
	v_mfma_f32_16x16x32_bf16 v[6:9], v[220:223], v[236:239], v[2:5]
	v_mfma_f32_16x16x32_bf16 v[2:5], v[224:227], v[232:235], v[212:215]
	v_mfma_f32_16x16x32_bf16 v[2:5], v[228:231], v[236:239], v[2:5]
	s_barrier
	s_add_u32 s70, s70, 0x160180
	s_addc_u32 s71, s71, 0
	s_add_u32 s56, s72, 0x200
	s_addc_u32 s57, s73, 0
	s_mov_b32 s72, 0
	.p2align 6

; template <class Epi, class Sched, bool ALIGN_EPI = true, bool SP2 = true, bool FULLLINE = false, bool NOSTAGE = false, bool FP8 = false>
; __device__ __forceinline__ void gemm_phase(PG8_LAS unsigned char* lds, const Gemm g, const Sched& S, const Epi& E) {
;     ...
;         const bool has_next = S.next(ui + 1, nxt);
;         const char* nA = has_next ? PG8_ABASE(nxt) : cA; const char* nB = has_next ? PG8_BBASE(nxt) : cB;
.LBB0_1024:
	s_ashr_i32 s75, s74, 31
	s_lshl_b64 s[40:41], s[74:75], 20
	s_add_u32 s76, s58, s40
	ds_read_b128 v[2:5], v1
	ds_read_b128 v[6:9], v1 offset:1024
	ds_read_b128 v[10:13], v1 offset:2048
	ds_read_b128 v[14:17], v1 offset:3072
	ds_read_b128 v[18:21], v152
	ds_read_b128 v[22:25], v152 offset:1024
	ds_read_b128 v[26:29], v152 offset:2048
	ds_read_b128 v[30:33], v152 offset:3072
	s_addc_u32 s77, s59, s41
	s_ashr_i32 s73, s72, 31
	s_lshl_b64 s[40:41], s[72:73], 20
	s_add_u32 s78, s3, s40
	s_addc_u32 s79, s42, s41
	s_and_b64 s[40:41], s[8:9], exec
	s_cselect_b32 s73, s77, s83
	s_cselect_b32 s75, s76, s82
	s_cselect_b32 s96, s79, s81
	s_cselect_b32 s97, s78, s80
	v_lshl_add_u64 v[244:245], s[82:83], 0, v[132:133]
	s_mov_b32 m0, s87
	v_lshl_add_u64 v[66:67], v[244:245], 0, s[18:19]
	ds_read_b128 v[34:37], v153
	ds_read_b128 v[38:41], v153 offset:1024
	ds_read_b128 v[42:45], v153 offset:2048
	ds_read_b128 v[46:49], v153 offset:3072
	ds_read_b128 v[50:53], v153 offset:4096
	ds_read_b128 v[54:57], v153 offset:5120
	ds_read_b128 v[58:61], v153 offset:6144
	ds_read_b128 v[62:65], v153 offset:7168
	global_load_lds_dwordx4 v[66:67], off
	v_lshl_add_u64 v[66:67], v[244:245], 0, s[20:21]
	s_mov_b32 m0, s88
	s_nop 0
	global_load_lds_dwordx4 v[66:67], off
	s_waitcnt vmcnt(16)
	s_waitcnt lgkmcnt(0)
	s_barrier
	s_waitcnt lgkmcnt(0)
	v_mfma_f32_16x16x32_bf16 v[90:93], v[2:5], v[58:61], 0
	v_mfma_f32_16x16x32_bf16 v[66:69], v[2:5], v[34:37], 0
	v_mfma_f32_16x16x32_bf16 v[70:73], v[10:13], v[34:37], 0
	v_mfma_f32_16x16x32_bf16 v[74:77], v[2:5], v[42:45], 0
	v_mfma_f32_16x16x32_bf16 v[78:81], v[10:13], v[42:45], 0
	v_mfma_f32_16x16x32_bf16 v[82:85], v[2:5], v[50:53], 0
	v_mfma_f32_16x16x32_bf16 v[86:89], v[10:13], v[50:53], 0
	v_mfma_f32_16x16x32_bf16 v[94:97], v[6:9], v[62:65], v[90:93]
	v_mfma_f32_16x16x32_bf16 v[90:93], v[10:13], v[58:61], 0
	v_mfma_f32_16x16x32_bf16 v[66:69], v[6:9], v[38:41], v[66:69]
	v_mfma_f32_16x16x32_bf16 v[70:73], v[14:17], v[38:41], v[70:73]
	v_mfma_f32_16x16x32_bf16 v[74:77], v[6:9], v[46:49], v[74:77]
	v_mfma_f32_16x16x32_bf16 v[78:81], v[14:17], v[46:49], v[78:81]
	v_mfma_f32_16x16x32_bf16 v[82:85], v[6:9], v[54:57], v[82:85]
	v_mfma_f32_16x16x32_bf16 v[86:89], v[14:17], v[54:57], v[86:89]
	v_mfma_f32_16x16x32_bf16 v[102:105], v[14:17], v[62:65], v[90:93]
	v_mfma_f32_16x16x32_bf16 v[90:93], v[18:21], v[34:37], 0
	v_mfma_f32_16x16x32_bf16 v[34:37], v[26:29], v[34:37], 0
	v_mfma_f32_16x16x32_bf16 v[110:113], v[22:25], v[38:41], v[90:93]
	v_mfma_f32_16x16x32_bf16 v[34:37], v[30:33], v[38:41], v[34:37]
	v_mfma_f32_16x16x32_bf16 v[38:41], v[18:21], v[42:45], 0
	v_mfma_f32_16x16x32_bf16 v[42:45], v[26:29], v[42:45], 0
	v_mfma_f32_16x16x32_bf16 v[38:41], v[22:25], v[46:49], v[38:41]
	v_mfma_f32_16x16x32_bf16 v[42:45], v[30:33], v[46:49], v[42:45]
	v_mfma_f32_16x16x32_bf16 v[46:49], v[18:21], v[50:53], 0
	v_mfma_f32_16x16x32_bf16 v[50:53], v[26:29], v[50:53], 0
	v_mfma_f32_16x16x32_bf16 v[46:49], v[22:25], v[54:57], v[46:49]
	v_mfma_f32_16x16x32_bf16 v[54:57], v[30:33], v[54:57], v[50:53]
	v_mfma_f32_16x16x32_bf16 v[50:53], v[18:21], v[58:61], 0
	v_mfma_f32_16x16x32_bf16 v[140:143], v[22:25], v[62:65], v[50:53]
	v_mfma_f32_16x16x32_bf16 v[50:53], v[26:29], v[58:61], 0
	v_mfma_f32_16x16x32_bf16 v[144:147], v[30:33], v[62:65], v[50:53]
	s_barrier
	v_lshl_add_u64 v[246:247], s[80:81], 0, v[130:131]
	s_add_i32 vcc_lo, s84, s43
	v_lshl_add_u64 v[122:123], v[246:247], 0, s[22:23]
	s_mov_b32 m0, vcc_lo
	s_add_i32 vcc_hi, vcc_lo, 0x2000
	s_nop 0
	ds_read_b128 v[50:53], v153 offset:16384
	ds_read_b128 v[58:61], v153 offset:17408
	ds_read_b128 v[62:65], v153 offset:18432
	ds_read_b128 v[90:93], v153 offset:19456
	ds_read_b128 v[98:101], v153 offset:20480
	ds_read_b128 v[106:109], v153 offset:21504
	ds_read_b128 v[114:117], v153 offset:22528
	ds_read_b128 v[118:121], v153 offset:23552
	global_load_lds_dwordx4 v[122:123], off
	v_lshl_add_u64 v[122:123], v[246:247], 0, s[24:25]
	s_mov_b32 m0, vcc_hi
	s_add_i32 s40, s85, s43
	global_load_lds_dwordx4 v[122:123], off
	v_lshl_add_u64 v[122:123], v[246:247], 0, s[26:27]
	s_mov_b32 m0, s40
	s_add_i32 s41, s40, 0x2000
	global_load_lds_dwordx4 v[122:123], off
	v_lshl_add_u64 v[122:123], v[246:247], 0, s[28:29]
	s_mov_b32 m0, s41
	s_nop 0
	global_load_lds_dwordx4 v[122:123], off
	v_lshl_add_u64 v[122:123], v[244:245], 0, s[22:23]
	s_mov_b32 m0, s45
	s_nop 0
	global_load_lds_dwordx4 v[122:123], off
	v_lshl_add_u64 v[122:123], v[244:245], 0, s[24:25]
	s_mov_b32 m0, s46
	s_nop 0
	global_load_lds_dwordx4 v[122:123], off
	s_waitcnt vmcnt(16)
	s_waitcnt lgkmcnt(0)
	s_barrier
	s_waitcnt lgkmcnt(0)
	v_mfma_f32_16x16x32_bf16 v[122:125], v[2:5], v[50:53], 0
	v_mfma_f32_16x16x32_bf16 v[148:151], v[6:9], v[58:61], v[122:125]
	v_mfma_f32_16x16x32_bf16 v[122:125], v[10:13], v[50:53], 0
	v_mfma_f32_16x16x32_bf16 v[156:159], v[14:17], v[58:61], v[122:125]
	v_mfma_f32_16x16x32_bf16 v[122:125], v[2:5], v[62:65], 0
	v_mfma_f32_16x16x32_bf16 v[160:163], v[6:9], v[90:93], v[122:125]
	v_mfma_f32_16x16x32_bf16 v[122:125], v[10:13], v[62:65], 0
	v_mfma_f32_16x16x32_bf16 v[164:167], v[14:17], v[90:93], v[122:125]
	v_mfma_f32_16x16x32_bf16 v[122:125], v[2:5], v[98:101], 0
	v_mfma_f32_16x16x32_bf16 v[2:5], v[2:5], v[114:117], 0
	v_mfma_f32_16x16x32_bf16 v[168:171], v[6:9], v[106:109], v[122:125]
	v_mfma_f32_16x16x32_bf16 v[2:5], v[6:9], v[118:121], v[2:5]
	v_mfma_f32_16x16x32_bf16 v[6:9], v[10:13], v[114:117], 0
	v_mfma_f32_16x16x32_bf16 v[122:125], v[10:13], v[98:101], 0
	v_mfma_f32_16x16x32_bf16 v[6:9], v[14:17], v[118:121], v[6:9]
	v_mfma_f32_16x16x32_bf16 v[172:175], v[14:17], v[106:109], v[122:125]
	v_mfma_f32_16x16x32_bf16 v[10:13], v[18:21], v[50:53], 0
	v_mfma_f32_16x16x32_bf16 v[176:179], v[22:25], v[58:61], v[10:13]
	v_mfma_f32_16x16x32_bf16 v[10:13], v[26:29], v[50:53], 0
	v_mfma_f32_16x16x32_bf16 v[180:183], v[30:33], v[58:61], v[10:13]
	v_mfma_f32_16x16x32_bf16 v[10:13], v[18:21], v[62:65], 0
	v_mfma_f32_16x16x32_bf16 v[184:187], v[22:25], v[90:93], v[10:13]
	v_mfma_f32_16x16x32_bf16 v[10:13], v[26:29], v[62:65], 0
	v_mfma_f32_16x16x32_bf16 v[188:191], v[30:33], v[90:93], v[10:13]
	v_mfma_f32_16x16x32_bf16 v[10:13], v[18:21], v[98:101], 0
	v_mfma_f32_16x16x32_bf16 v[192:195], v[22:25], v[106:109], v[10:13]
	v_mfma_f32_16x16x32_bf16 v[10:13], v[26:29], v[98:101], 0
	v_mfma_f32_16x16x32_bf16 v[196:199], v[30:33], v[106:109], v[10:13]
	v_mfma_f32_16x16x32_bf16 v[10:13], v[18:21], v[114:117], 0
	v_mfma_f32_16x16x32_bf16 v[200:203], v[22:25], v[118:121], v[10:13]
	v_mfma_f32_16x16x32_bf16 v[10:13], v[26:29], v[114:117], 0
	v_mfma_f32_16x16x32_bf16 v[204:207], v[30:33], v[118:121], v[10:13]
	s_barrier
; #define PG8_WAIT_V(n) asm volatile("s_waitcnt vmcnt(" #n ")" ::: "memory")
; template <class Epi, class Sched, bool ALIGN_EPI = true, bool SP2 = true, bool FULLLINE = false, bool NOSTAGE = false, bool FP8 = false>
; __device__ __forceinline__ void gemm_phase(PG8_LAS unsigned char* lds, const Gemm g, const Sched& S, const Epi& E) {
;     ...
;         static_assert(SP2, "only the SP2 loop is kept");
;         { const int t = 0; if constexpr (Epi::NST == 16) PG8_ITER(PG8_WAIT_V(24)); else if constexpr (Epi::NST == 8) PG8_ITER(PG8_WAIT_V(16)); else PG8_ITER(PG8_WAIT_V(8)); }
;         for (int t = 2; t < nt; t += 2) PG8_ITER(PG8_WAIT_V(8));
	s_nop 5
	ds_read_b128 v[10:13], v154
	ds_read_b128 v[14:17], v154 offset:1024
	ds_read_b128 v[18:21], v154 offset:2048
	ds_read_b128 v[26:29], v154 offset:3072
	ds_read_b128 v[208:211], v155
	ds_read_b128 v[212:215], v155 offset:1024
	ds_read_b128 v[216:219], v155 offset:2048
	ds_read_b128 v[220:223], v155 offset:3072
	s_mov_b32 m0, s47
	v_lshl_add_u64 v[50:51], v[244:245], 0, s[26:27]
	ds_read_b128 v[22:25], v153 offset:32768
	ds_read_b128 v[30:33], v153 offset:33792
	ds_read_b128 v[62:65], v153 offset:34816
	ds_read_b128 v[224:227], v153 offset:35840
	ds_read_b128 v[228:231], v153 offset:36864
	ds_read_b128 v[232:235], v153 offset:37888
	ds_read_b128 v[236:239], v153 offset:38912
	ds_read_b128 v[240:243], v153 offset:39936
	global_load_lds_dwordx4 v[50:51], off
	v_lshl_add_u64 v[50:51], v[244:245], 0, s[28:29]
	s_mov_b32 m0, s52
	s_nop 0
	global_load_lds_dwordx4 v[50:51], off
	s_waitcnt vmcnt(8)
	s_waitcnt lgkmcnt(0)
	s_barrier
	s_waitcnt lgkmcnt(0)
	v_mfma_f32_16x16x32_bf16 v[50:53], v[10:13], v[22:25], v[66:69]
	v_mfma_f32_16x16x32_bf16 v[122:125], v[14:17], v[30:33], v[50:53]
	v_mfma_f32_16x16x32_bf16 v[50:53], v[18:21], v[22:25], v[70:73]
	v_mfma_f32_16x16x32_bf16 v[114:117], v[26:29], v[30:33], v[50:53]
	v_mfma_f32_16x16x32_bf16 v[50:53], v[10:13], v[62:65], v[74:77]
	v_mfma_f32_16x16x32_bf16 v[106:109], v[14:17], v[224:227], v[50:53]
	v_mfma_f32_16x16x32_bf16 v[50:53], v[18:21], v[62:65], v[78:81]
	v_mfma_f32_16x16x32_bf16 v[98:101], v[26:29], v[224:227], v[50:53]
	v_mfma_f32_16x16x32_bf16 v[50:53], v[10:13], v[228:231], v[82:85]
	v_mfma_f32_16x16x32_bf16 v[90:93], v[14:17], v[232:235], v[50:53]
	v_mfma_f32_16x16x32_bf16 v[50:53], v[18:21], v[228:231], v[86:89]
	v_mfma_f32_16x16x32_bf16 v[82:85], v[26:29], v[232:235], v[50:53]
	v_mfma_f32_16x16x32_bf16 v[50:53], v[10:13], v[236:239], v[94:97]
	v_mfma_f32_16x16x32_bf16 v[58:61], v[14:17], v[240:243], v[50:53]
	v_mfma_f32_16x16x32_bf16 v[50:53], v[18:21], v[236:239], v[102:105]
	v_mfma_f32_16x16x32_bf16 v[50:53], v[26:29], v[240:243], v[50:53]
	v_mfma_f32_16x16x32_bf16 v[66:69], v[208:211], v[22:25], v[110:113]
	v_mfma_f32_16x16x32_bf16 v[22:25], v[216:219], v[22:25], v[34:37]
	v_mfma_f32_16x16x32_bf16 v[118:121], v[220:223], v[30:33], v[22:25]
	v_mfma_f32_16x16x32_bf16 v[22:25], v[208:211], v[62:65], v[38:41]
	v_mfma_f32_16x16x32_bf16 v[110:113], v[212:215], v[224:227], v[22:25]
	v_mfma_f32_16x16x32_bf16 v[22:25], v[216:219], v[62:65], v[42:45]
	v_mfma_f32_16x16x32_bf16 v[102:105], v[220:223], v[224:227], v[22:25]
	v_mfma_f32_16x16x32_bf16 v[22:25], v[208:211], v[228:231], v[46:49]
	v_mfma_f32_16x16x32_bf16 v[94:97], v[212:215], v[232:235], v[22:25]
	v_mfma_f32_16x16x32_bf16 v[22:25], v[216:219], v[228:231], v[54:57]
	v_mfma_f32_16x16x32_bf16 v[86:89], v[220:223], v[232:235], v[22:25]
	v_mfma_f32_16x16x32_bf16 v[22:25], v[208:211], v[236:239], v[140:143]
	v_mfma_f32_16x16x32_bf16 v[62:65], v[212:215], v[240:243], v[22:25]
	v_mfma_f32_16x16x32_bf16 v[22:25], v[216:219], v[236:239], v[144:147]
	v_mfma_f32_16x16x32_bf16 v[126:129], v[212:215], v[30:33], v[66:69]
	v_mfma_f32_16x16x32_bf16 v[54:57], v[220:223], v[240:243], v[22:25]
	s_barrier
	s_add_i32 s50, s89, s43
	s_nop 3
	v_lshl_add_u64 v[22:23], v[246:247], 0, s[30:31]
	s_mov_b32 m0, s50
	s_add_i32 s51, s50, 0x2000
	ds_read_b128 v[34:37], v153 offset:49152
	ds_read_b128 v[42:45], v153 offset:50176
	ds_read_b128 v[140:143], v153 offset:51200
	ds_read_b128 v[144:147], v153 offset:52224
	ds_read_b128 v[224:227], v153 offset:53248
	ds_read_b128 v[228:231], v153 offset:54272
	ds_read_b128 v[232:235], v153 offset:55296
	ds_read_b128 v[236:239], v153 offset:56320
	global_load_lds_dwordx4 v[22:23], off
	v_lshl_add_u64 v[22:23], v[246:247], 0, s[34:35]
	s_mov_b32 m0, s51
	s_mov_b64 s[56:57], 0x80180
	s_add_i32 s33, s90, s43
	global_load_lds_dwordx4 v[22:23], off
	v_lshl_add_u64 v[22:23], v[246:247], 0, s[56:57]
	s_mov_b32 m0, s33
	s_mov_b64 s[56:57], 0xc0180
	global_load_lds_dwordx4 v[22:23], off
	v_lshl_add_u64 v[22:23], v[246:247], 0, s[56:57]
	s_add_i32 s56, s33, 0x2000
	s_mov_b32 m0, s56
	s_nop 0
	global_load_lds_dwordx4 v[22:23], off
	v_lshl_add_u64 v[22:23], v[244:245], 0, s[30:31]
	s_mov_b32 m0, s53
	s_nop 0
	global_load_lds_dwordx4 v[22:23], off
	v_lshl_add_u64 v[22:23], v[244:245], 0, s[34:35]
	s_mov_b32 m0, s54
	s_nop 0
	global_load_lds_dwordx4 v[22:23], off
	s_waitcnt vmcnt(8)
	s_waitcnt lgkmcnt(0)
	s_barrier
	s_waitcnt lgkmcnt(0)
	v_mfma_f32_16x16x32_bf16 v[22:25], v[10:13], v[34:37], v[148:151]
	v_mfma_f32_16x16x32_bf16 v[78:81], v[14:17], v[42:45], v[22:25]
	v_mfma_f32_16x16x32_bf16 v[22:25], v[18:21], v[34:37], v[156:159]
	v_mfma_f32_16x16x32_bf16 v[70:73], v[26:29], v[42:45], v[22:25]
	v_mfma_f32_16x16x32_bf16 v[22:25], v[10:13], v[140:143], v[160:163]
	v_mfma_f32_16x16x32_bf16 v[46:49], v[14:17], v[144:147], v[22:25]
	v_mfma_f32_16x16x32_bf16 v[22:25], v[18:21], v[140:143], v[164:167]
	v_mfma_f32_16x16x32_bf16 v[38:41], v[26:29], v[144:147], v[22:25]
	v_mfma_f32_16x16x32_bf16 v[22:25], v[10:13], v[224:227], v[168:171]
	v_mfma_f32_16x16x32_bf16 v[2:5], v[10:13], v[232:235], v[2:5]
	v_mfma_f32_16x16x32_bf16 v[30:33], v[14:17], v[228:231], v[22:25]
	v_mfma_f32_16x16x32_bf16 v[22:25], v[18:21], v[224:227], v[172:175]
	v_mfma_f32_16x16x32_bf16 v[14:17], v[14:17], v[236:239], v[2:5]
	v_mfma_f32_16x16x32_bf16 v[2:5], v[18:21], v[232:235], v[6:9]
	v_mfma_f32_16x16x32_bf16 v[22:25], v[26:29], v[228:231], v[22:25]
	v_mfma_f32_16x16x32_bf16 v[10:13], v[26:29], v[236:239], v[2:5]
	v_mfma_f32_16x16x32_bf16 v[2:5], v[208:211], v[34:37], v[176:179]
	v_mfma_f32_16x16x32_bf16 v[74:77], v[212:215], v[42:45], v[2:5]
	v_mfma_f32_16x16x32_bf16 v[2:5], v[216:219], v[34:37], v[180:183]
	v_mfma_f32_16x16x32_bf16 v[66:69], v[220:223], v[42:45], v[2:5]
	v_mfma_f32_16x16x32_bf16 v[2:5], v[208:211], v[140:143], v[184:187]
	v_mfma_f32_16x16x32_bf16 v[42:45], v[212:215], v[144:147], v[2:5]
	v_mfma_f32_16x16x32_bf16 v[2:5], v[216:219], v[140:143], v[188:191]
	v_mfma_f32_16x16x32_bf16 v[34:37], v[220:223], v[144:147], v[2:5]
	v_mfma_f32_16x16x32_bf16 v[2:5], v[208:211], v[224:227], v[192:195]
	v_mfma_f32_16x16x32_bf16 v[26:29], v[212:215], v[228:231], v[2:5]
	v_mfma_f32_16x16x32_bf16 v[2:5], v[216:219], v[224:227], v[196:199]
	v_mfma_f32_16x16x32_bf16 v[18:21], v[220:223], v[228:231], v[2:5]
	v_mfma_f32_16x16x32_bf16 v[2:5], v[208:211], v[232:235], v[200:203]
	v_mfma_f32_16x16x32_bf16 v[6:9], v[212:215], v[236:239], v[2:5]
	v_mfma_f32_16x16x32_bf16 v[2:5], v[216:219], v[232:235], v[204:207]
	v_mfma_f32_16x16x32_bf16 v[2:5], v[220:223], v[236:239], v[2:5]
	s_barrier
	s_add_u32 s82, s82, 0x80180
	s_addc_u32 s83, s83, 0
	s_add_u32 s57, s80, 0x200
	s_addc_u32 s80, s81, 0
	s_mov_b32 s81, 0
	.p2align 6

; template <class Epi, class Sched, bool ALIGN_EPI = true, bool SP2 = true, bool FULLLINE = false, bool NOSTAGE = false, bool FP8 = false>
; __device__ __forceinline__ void gemm_phase(PG8_LAS unsigned char* lds, const Gemm g, const Sched& S, const Epi& E) {
;     ...
;         const bool has_next = S.next(ui + 1, nxt);
;         const char* nA = has_next ? PG8_ABASE(nxt) : cA; const char* nB = has_next ? PG8_BBASE(nxt) : cB;
.LBB0_1207:
	s_ashr_i32 s69, s68, 31
	ds_read_b128 v[2:5], v1
	ds_read_b128 v[6:9], v1 offset:1024
	ds_read_b128 v[10:13], v1 offset:2048
	ds_read_b128 v[14:17], v1 offset:3072
	ds_read_b128 v[18:21], v192
	ds_read_b128 v[22:25], v192 offset:1024
	ds_read_b128 v[26:29], v192 offset:2048
	ds_read_b128 v[30:33], v192 offset:3072
	s_lshl_b64 s[0:1], s[68:69], 20
	s_add_u32 s70, s42, s0
	s_addc_u32 s71, s43, s1
	s_and_b64 s[0:1], s[8:9], exec
	s_cselect_b32 s69, s71, s77
	s_cselect_b32 s92, s70, s76
	s_ashr_i32 s67, s66, 31
	s_lshl_b64 s[0:1], s[66:67], 20
	s_add_u32 s72, s44, s0
	s_addc_u32 s73, s45, s1
	s_and_b64 s[0:1], s[8:9], exec
	s_cselect_b32 s67, s73, s79
	s_cselect_b32 s93, s72, s78
	v_lshl_add_u64 v[248:249], s[76:77], 0, v[170:171]
	s_mov_b32 m0, s88
	v_lshl_add_u64 v[66:67], v[248:249], 0, s[12:13]
	ds_read_b128 v[34:37], v193
	ds_read_b128 v[38:41], v193 offset:1024
	ds_read_b128 v[42:45], v193 offset:2048
	ds_read_b128 v[46:49], v193 offset:3072
	ds_read_b128 v[50:53], v193 offset:4096
	ds_read_b128 v[54:57], v193 offset:5120
	ds_read_b128 v[58:61], v193 offset:6144
	ds_read_b128 v[62:65], v193 offset:7168
	global_load_lds_dwordx4 v[66:67], off
	v_lshl_add_u64 v[66:67], v[248:249], 0, s[14:15]
	s_mov_b32 m0, s89
	s_nop 0
	global_load_lds_dwordx4 v[66:67], off
	s_waitcnt vmcnt(24)
	s_waitcnt lgkmcnt(0)
	s_barrier
	s_waitcnt lgkmcnt(0)
	v_mfma_f32_16x16x32_bf16 v[66:69], v[2:5], v[34:37], 0
	v_mfma_f32_16x16x32_bf16 v[70:73], v[10:13], v[34:37], 0
	v_mfma_f32_16x16x32_bf16 v[78:81], v[10:13], v[42:45], 0
	v_mfma_f32_16x16x32_bf16 v[86:89], v[10:13], v[50:53], 0
	v_mfma_f32_16x16x32_bf16 v[66:69], v[6:9], v[38:41], v[66:69]
	v_mfma_f32_16x16x32_bf16 v[70:73], v[14:17], v[38:41], v[70:73]
	v_mfma_f32_16x16x32_bf16 v[74:77], v[2:5], v[42:45], 0
	v_mfma_f32_16x16x32_bf16 v[78:81], v[14:17], v[46:49], v[78:81]
	v_mfma_f32_16x16x32_bf16 v[82:85], v[2:5], v[50:53], 0
	v_mfma_f32_16x16x32_bf16 v[86:89], v[14:17], v[54:57], v[86:89]
	v_mfma_f32_16x16x32_bf16 v[90:93], v[2:5], v[58:61], 0
	v_mfma_f32_16x16x32_bf16 v[94:97], v[10:13], v[58:61], 0
	v_mfma_f32_16x16x32_bf16 v[74:77], v[6:9], v[46:49], v[74:77]
	v_mfma_f32_16x16x32_bf16 v[82:85], v[6:9], v[54:57], v[82:85]
	v_mfma_f32_16x16x32_bf16 v[90:93], v[6:9], v[62:65], v[90:93]
	v_mfma_f32_16x16x32_bf16 v[94:97], v[14:17], v[62:65], v[94:97]
	v_mfma_f32_16x16x32_bf16 v[98:101], v[18:21], v[34:37], 0
	v_mfma_f32_16x16x32_bf16 v[34:37], v[26:29], v[34:37], 0
	v_mfma_f32_16x16x32_bf16 v[98:101], v[22:25], v[38:41], v[98:101]
	v_mfma_f32_16x16x32_bf16 v[34:37], v[30:33], v[38:41], v[34:37]
	v_mfma_f32_16x16x32_bf16 v[38:41], v[18:21], v[42:45], 0
	v_mfma_f32_16x16x32_bf16 v[42:45], v[26:29], v[42:45], 0
	v_mfma_f32_16x16x32_bf16 v[38:41], v[22:25], v[46:49], v[38:41]
	v_mfma_f32_16x16x32_bf16 v[42:45], v[30:33], v[46:49], v[42:45]
	v_mfma_f32_16x16x32_bf16 v[46:49], v[18:21], v[50:53], 0
	v_mfma_f32_16x16x32_bf16 v[50:53], v[26:29], v[50:53], 0
	v_mfma_f32_16x16x32_bf16 v[46:49], v[22:25], v[54:57], v[46:49]
	v_mfma_f32_16x16x32_bf16 v[50:53], v[30:33], v[54:57], v[50:53]
	v_mfma_f32_16x16x32_bf16 v[54:57], v[18:21], v[58:61], 0
	v_mfma_f32_16x16x32_bf16 v[58:61], v[26:29], v[58:61], 0
	v_mfma_f32_16x16x32_bf16 v[54:57], v[22:25], v[62:65], v[54:57]
	v_mfma_f32_16x16x32_bf16 v[58:61], v[30:33], v[62:65], v[58:61]
	s_barrier
	v_lshl_add_u64 v[250:251], s[78:79], 0, v[172:173]
	s_add_i32 s94, s85, s46
	v_lshl_add_u64 v[130:131], v[250:251], 0, s[16:17]
	s_mov_b32 m0, s94
	s_add_i32 s95, s94, 0x2000
	ds_read_b128 v[62:65], v193 offset:16384
	ds_read_b128 v[102:105], v193 offset:17408
	ds_read_b128 v[106:109], v193 offset:18432
	ds_read_b128 v[110:113], v193 offset:19456
	ds_read_b128 v[114:117], v193 offset:20480
	ds_read_b128 v[118:121], v193 offset:21504
	ds_read_b128 v[122:125], v193 offset:22528
	ds_read_b128 v[126:129], v193 offset:23552
	global_load_lds_dwordx4 v[130:131], off
	v_lshl_add_u64 v[130:131], v[250:251], 0, s[18:19]
	s_mov_b32 m0, s95
	s_add_i32 s40, s87, s46
	global_load_lds_dwordx4 v[130:131], off
	v_lshl_add_u64 v[130:131], v[250:251], 0, s[20:21]
	s_mov_b32 m0, s40
	s_add_i32 s41, s40, 0x2000
	global_load_lds_dwordx4 v[130:131], off
	v_lshl_add_u64 v[130:131], v[250:251], 0, s[22:23]
	s_mov_b32 m0, s41
	s_nop 0
	global_load_lds_dwordx4 v[130:131], off
	v_lshl_add_u64 v[130:131], v[248:249], 0, s[16:17]
	s_mov_b32 m0, s47
	s_nop 0
	global_load_lds_dwordx4 v[130:131], off
	v_lshl_add_u64 v[130:131], v[248:249], 0, s[18:19]
	s_mov_b32 m0, s52
	s_nop 0
	global_load_lds_dwordx4 v[130:131], off
	s_waitcnt vmcnt(24)
	s_waitcnt lgkmcnt(0)
	s_barrier
	s_waitcnt lgkmcnt(0)
	v_mfma_f32_16x16x32_bf16 v[130:133], v[2:5], v[62:65], 0
	v_mfma_f32_16x16x32_bf16 v[138:141], v[6:9], v[102:105], v[130:133]
	v_mfma_f32_16x16x32_bf16 v[130:133], v[10:13], v[62:65], 0
	v_mfma_f32_16x16x32_bf16 v[150:153], v[14:17], v[102:105], v[130:133]
	v_mfma_f32_16x16x32_bf16 v[130:133], v[2:5], v[106:109], 0
	v_mfma_f32_16x16x32_bf16 v[154:157], v[6:9], v[110:113], v[130:133]
	v_mfma_f32_16x16x32_bf16 v[130:133], v[10:13], v[106:109], 0
	v_mfma_f32_16x16x32_bf16 v[158:161], v[14:17], v[110:113], v[130:133]
	v_mfma_f32_16x16x32_bf16 v[130:133], v[2:5], v[114:117], 0
	v_mfma_f32_16x16x32_bf16 v[2:5], v[2:5], v[122:125], 0
	v_mfma_f32_16x16x32_bf16 v[162:165], v[6:9], v[118:121], v[130:133]
	v_mfma_f32_16x16x32_bf16 v[2:5], v[6:9], v[126:129], v[2:5]
	v_mfma_f32_16x16x32_bf16 v[6:9], v[10:13], v[122:125], 0
	v_mfma_f32_16x16x32_bf16 v[130:133], v[10:13], v[114:117], 0
	v_mfma_f32_16x16x32_bf16 v[6:9], v[14:17], v[126:129], v[6:9]
	v_mfma_f32_16x16x32_bf16 v[166:169], v[14:17], v[118:121], v[130:133]
	v_mfma_f32_16x16x32_bf16 v[10:13], v[18:21], v[62:65], 0
	v_mfma_f32_16x16x32_bf16 v[180:183], v[22:25], v[102:105], v[10:13]
	v_mfma_f32_16x16x32_bf16 v[10:13], v[26:29], v[62:65], 0
	v_mfma_f32_16x16x32_bf16 v[184:187], v[30:33], v[102:105], v[10:13]
	v_mfma_f32_16x16x32_bf16 v[10:13], v[18:21], v[106:109], 0
	v_mfma_f32_16x16x32_bf16 v[188:191], v[22:25], v[110:113], v[10:13]
	v_mfma_f32_16x16x32_bf16 v[10:13], v[26:29], v[106:109], 0
	v_mfma_f32_16x16x32_bf16 v[196:199], v[30:33], v[110:113], v[10:13]
	v_mfma_f32_16x16x32_bf16 v[10:13], v[18:21], v[114:117], 0
	v_mfma_f32_16x16x32_bf16 v[200:203], v[22:25], v[118:121], v[10:13]
	v_mfma_f32_16x16x32_bf16 v[10:13], v[26:29], v[114:117], 0
	v_mfma_f32_16x16x32_bf16 v[204:207], v[30:33], v[118:121], v[10:13]
	v_mfma_f32_16x16x32_bf16 v[10:13], v[18:21], v[122:125], 0
	v_mfma_f32_16x16x32_bf16 v[208:211], v[22:25], v[126:129], v[10:13]
	v_mfma_f32_16x16x32_bf16 v[10:13], v[26:29], v[122:125], 0
	v_mfma_f32_16x16x32_bf16 v[212:215], v[30:33], v[126:129], v[10:13]
	s_barrier
; #define PG8_WAIT_V(n) asm volatile("s_waitcnt vmcnt(" #n ")" ::: "memory")
; template <class Epi, class Sched, bool ALIGN_EPI = true, bool SP2 = true, bool FULLLINE = false, bool NOSTAGE = false, bool FP8 = false>
; __device__ __forceinline__ void gemm_phase(PG8_LAS unsigned char* lds, const Gemm g, const Sched& S, const Epi& E) {
;     ...
;         static_assert(SP2, "only the SP2 loop is kept");
;         { const int t = 0; if constexpr (Epi::NST == 16) PG8_ITER(PG8_WAIT_V(24)); else if constexpr (Epi::NST == 8) PG8_ITER(PG8_WAIT_V(16)); else PG8_ITER(PG8_WAIT_V(8)); }
;         for (int t = 2; t < nt; t += 2) PG8_ITER(PG8_WAIT_V(8));
	s_nop 5
	ds_read_b128 v[10:13], v194
	ds_read_b128 v[14:17], v194 offset:1024
	ds_read_b128 v[18:21], v194 offset:2048
	ds_read_b128 v[22:25], v194 offset:3072
	ds_read_b128 v[216:219], v195
	ds_read_b128 v[220:223], v195 offset:1024
	ds_read_b128 v[224:227], v195 offset:2048
	ds_read_b128 v[228:231], v195 offset:3072
	s_mov_b32 m0, s53
	v_lshl_add_u64 v[106:107], v[248:249], 0, s[20:21]
	ds_read_b128 v[26:29], v193 offset:32768
	ds_read_b128 v[30:33], v193 offset:33792
	ds_read_b128 v[62:65], v193 offset:34816
	ds_read_b128 v[102:105], v193 offset:35840
	ds_read_b128 v[232:235], v193 offset:36864
	ds_read_b128 v[236:239], v193 offset:37888
	ds_read_b128 v[240:243], v193 offset:38912
	ds_read_b128 v[244:247], v193 offset:39936
	global_load_lds_dwordx4 v[106:107], off
	v_lshl_add_u64 v[106:107], v[248:249], 0, s[22:23]
	s_mov_b32 m0, s54
	s_nop 0
	global_load_lds_dwordx4 v[106:107], off
	s_waitcnt vmcnt(8)
	s_waitcnt lgkmcnt(0)
	s_barrier
	s_waitcnt lgkmcnt(0)
	v_mfma_f32_16x16x32_bf16 v[66:69], v[10:13], v[26:29], v[66:69]
	v_mfma_f32_16x16x32_bf16 v[146:149], v[14:17], v[30:33], v[66:69]
	v_mfma_f32_16x16x32_bf16 v[66:69], v[18:21], v[26:29], v[70:73]
	v_mfma_f32_16x16x32_bf16 v[142:145], v[22:25], v[30:33], v[66:69]
	v_mfma_f32_16x16x32_bf16 v[66:69], v[10:13], v[62:65], v[74:77]
	v_mfma_f32_16x16x32_bf16 v[126:129], v[14:17], v[102:105], v[66:69]
	v_mfma_f32_16x16x32_bf16 v[66:69], v[18:21], v[62:65], v[78:81]
	v_mfma_f32_16x16x32_bf16 v[122:125], v[22:25], v[102:105], v[66:69]
	v_mfma_f32_16x16x32_bf16 v[66:69], v[10:13], v[232:235], v[82:85]
	v_mfma_f32_16x16x32_bf16 v[110:113], v[14:17], v[236:239], v[66:69]
	v_mfma_f32_16x16x32_bf16 v[66:69], v[18:21], v[232:235], v[86:89]
	v_mfma_f32_16x16x32_bf16 v[106:109], v[22:25], v[236:239], v[66:69]
	v_mfma_f32_16x16x32_bf16 v[66:69], v[10:13], v[240:243], v[90:93]
	v_mfma_f32_16x16x32_bf16 v[86:89], v[14:17], v[244:247], v[66:69]
	v_mfma_f32_16x16x32_bf16 v[66:69], v[18:21], v[240:243], v[94:97]
	v_mfma_f32_16x16x32_bf16 v[78:81], v[22:25], v[244:247], v[66:69]
	v_mfma_f32_16x16x32_bf16 v[66:69], v[216:219], v[26:29], v[98:101]
	v_mfma_f32_16x16x32_bf16 v[26:29], v[224:227], v[26:29], v[34:37]
	v_mfma_f32_16x16x32_bf16 v[130:133], v[228:231], v[30:33], v[26:29]
	v_mfma_f32_16x16x32_bf16 v[26:29], v[216:219], v[62:65], v[38:41]
	v_mfma_f32_16x16x32_bf16 v[118:121], v[220:223], v[102:105], v[26:29]
	v_mfma_f32_16x16x32_bf16 v[26:29], v[224:227], v[62:65], v[42:45]
	v_mfma_f32_16x16x32_bf16 v[114:117], v[228:231], v[102:105], v[26:29]
	v_mfma_f32_16x16x32_bf16 v[26:29], v[216:219], v[232:235], v[46:49]
	v_mfma_f32_16x16x32_bf16 v[102:105], v[220:223], v[236:239], v[26:29]
	v_mfma_f32_16x16x32_bf16 v[26:29], v[224:227], v[232:235], v[50:53]
	v_mfma_f32_16x16x32_bf16 v[98:101], v[228:231], v[236:239], v[26:29]
	v_mfma_f32_16x16x32_bf16 v[26:29], v[216:219], v[240:243], v[54:57]
	v_mfma_f32_16x16x32_bf16 v[70:73], v[220:223], v[244:247], v[26:29]
	v_mfma_f32_16x16x32_bf16 v[26:29], v[224:227], v[240:243], v[58:61]
	v_mfma_f32_16x16x32_bf16 v[134:137], v[220:223], v[30:33], v[66:69]
	v_mfma_f32_16x16x32_bf16 v[66:69], v[228:231], v[244:247], v[26:29]
	s_barrier
	s_add_i32 s50, s90, s46
	s_nop 3
	v_lshl_add_u64 v[26:27], v[250:251], 0, s[24:25]
	s_mov_b32 m0, s50
	s_add_i32 s51, s50, 0x2000
	ds_read_b128 v[34:37], v193 offset:49152
	ds_read_b128 v[38:41], v193 offset:50176
	ds_read_b128 v[74:77], v193 offset:51200
	ds_read_b128 v[82:85], v193 offset:52224
	ds_read_b128 v[90:93], v193 offset:53248
	ds_read_b128 v[94:97], v193 offset:54272
	ds_read_b128 v[232:235], v193 offset:55296
	ds_read_b128 v[236:239], v193 offset:56320
	global_load_lds_dwordx4 v[26:27], off
	v_lshl_add_u64 v[26:27], v[250:251], 0, s[26:27]
	s_mov_b32 m0, s51
	s_mov_b64 s[0:1], 0x80180
	s_add_i32 s33, s91, s46
	global_load_lds_dwordx4 v[26:27], off
	v_lshl_add_u64 v[26:27], v[250:251], 0, s[0:1]
	s_mov_b32 m0, s33
	s_mov_b64 s[0:1], 0xc0180
	s_add_i32 s56, s33, 0x2000
	global_load_lds_dwordx4 v[26:27], off
	v_lshl_add_u64 v[26:27], v[250:251], 0, s[0:1]
	s_mov_b32 m0, s56
	s_nop 0
	global_load_lds_dwordx4 v[26:27], off
	v_lshl_add_u64 v[26:27], v[248:249], 0, s[24:25]
	s_mov_b32 m0, s55
	s_nop 0
	global_load_lds_dwordx4 v[26:27], off
	v_lshl_add_u64 v[26:27], v[248:249], 0, s[26:27]
	s_mov_b32 m0, s62
	s_nop 0
	global_load_lds_dwordx4 v[26:27], off
	s_waitcnt vmcnt(8)
	s_waitcnt lgkmcnt(0)
	s_barrier
	s_waitcnt lgkmcnt(0)
	v_mfma_f32_16x16x32_bf16 v[26:29], v[10:13], v[34:37], v[138:141]
	v_mfma_f32_16x16x32_bf16 v[62:65], v[14:17], v[38:41], v[26:29]
	v_mfma_f32_16x16x32_bf16 v[26:29], v[18:21], v[34:37], v[150:153]
	v_mfma_f32_16x16x32_bf16 v[58:61], v[22:25], v[38:41], v[26:29]
	v_mfma_f32_16x16x32_bf16 v[26:29], v[10:13], v[74:77], v[154:157]
	v_mfma_f32_16x16x32_bf16 v[46:49], v[14:17], v[82:85], v[26:29]
	v_mfma_f32_16x16x32_bf16 v[26:29], v[18:21], v[74:77], v[158:161]
	v_mfma_f32_16x16x32_bf16 v[42:45], v[22:25], v[82:85], v[26:29]
	v_mfma_f32_16x16x32_bf16 v[26:29], v[10:13], v[90:93], v[162:165]
	v_mfma_f32_16x16x32_bf16 v[2:5], v[10:13], v[232:235], v[2:5]
	v_mfma_f32_16x16x32_bf16 v[30:33], v[14:17], v[94:97], v[26:29]
	v_mfma_f32_16x16x32_bf16 v[26:29], v[18:21], v[90:93], v[166:169]
	v_mfma_f32_16x16x32_bf16 v[14:17], v[14:17], v[236:239], v[2:5]
	v_mfma_f32_16x16x32_bf16 v[2:5], v[18:21], v[232:235], v[6:9]
	v_mfma_f32_16x16x32_bf16 v[26:29], v[22:25], v[94:97], v[26:29]
	v_mfma_f32_16x16x32_bf16 v[10:13], v[22:25], v[236:239], v[2:5]
	v_mfma_f32_16x16x32_bf16 v[2:5], v[216:219], v[34:37], v[180:183]
	v_mfma_f32_16x16x32_bf16 v[54:57], v[220:223], v[38:41], v[2:5]
	v_mfma_f32_16x16x32_bf16 v[2:5], v[224:227], v[34:37], v[184:187]
	v_mfma_f32_16x16x32_bf16 v[50:53], v[228:231], v[38:41], v[2:5]
	v_mfma_f32_16x16x32_bf16 v[2:5], v[216:219], v[74:77], v[188:191]
	v_mfma_f32_16x16x32_bf16 v[38:41], v[220:223], v[82:85], v[2:5]
	v_mfma_f32_16x16x32_bf16 v[2:5], v[224:227], v[74:77], v[196:199]
	v_mfma_f32_16x16x32_bf16 v[34:37], v[228:231], v[82:85], v[2:5]
	v_mfma_f32_16x16x32_bf16 v[2:5], v[216:219], v[90:93], v[200:203]
	v_mfma_f32_16x16x32_bf16 v[22:25], v[220:223], v[94:97], v[2:5]
	v_mfma_f32_16x16x32_bf16 v[2:5], v[224:227], v[90:93], v[204:207]
	v_mfma_f32_16x16x32_bf16 v[18:21], v[228:231], v[94:97], v[2:5]
	v_mfma_f32_16x16x32_bf16 v[2:5], v[216:219], v[232:235], v[208:211]
	v_mfma_f32_16x16x32_bf16 v[6:9], v[220:223], v[236:239], v[2:5]
	v_mfma_f32_16x16x32_bf16 v[2:5], v[224:227], v[232:235], v[212:215]
	v_mfma_f32_16x16x32_bf16 v[2:5], v[228:231], v[236:239], v[2:5]
	s_barrier
	s_add_u32 s76, s76, 0x80180
	s_addc_u32 s77, s77, 0
	s_add_u32 s57, s78, 0x200
	s_addc_u32 s78, s79, 0
	s_mov_b32 s79, 0
	.p2align 6

; template <class Epi, class Sched, bool ALIGN_EPI = true, bool SP2 = true, bool FULLLINE = false, bool NOSTAGE = false, bool FP8 = false>
; __device__ __forceinline__ void gemm_phase(PG8_LAS unsigned char* lds, const Gemm g, const Sched& S, const Epi& E) {
;     ...
;         const bool has_next = S.next(ui + 1, nxt);
;         const char* nA = has_next ? PG8_ABASE(nxt) : cA; const char* nB = has_next ? PG8_BBASE(nxt) : cB;
.LBB0_1380:
	s_ashr_i32 s69, s68, 31
	s_lshl_b64 s[0:1], s[68:69], 20
	s_add_u32 s70, s58, s0
	ds_read_b128 v[2:5], v1
	ds_read_b128 v[6:9], v1 offset:1024
	ds_read_b128 v[10:13], v1 offset:2048
	ds_read_b128 v[14:17], v1 offset:3072
	ds_read_b128 v[18:21], v142
	ds_read_b128 v[22:25], v142 offset:1024
	ds_read_b128 v[26:29], v142 offset:2048
	ds_read_b128 v[30:33], v142 offset:3072
	s_addc_u32 s71, s59, s1
	s_ashr_i32 s67, s66, 31
	s_lshl_b64 s[0:1], s[66:67], 20
	s_add_u32 s72, s3, s0
	s_addc_u32 s73, s42, s1
	s_and_b64 s[0:1], s[8:9], exec
	s_cselect_b32 s67, s71, s79
	s_cselect_b32 s69, s70, s78
	s_cselect_b32 s89, s73, s77
	s_cselect_b32 s90, s72, s76
	v_lshl_add_u64 v[140:141], s[78:79], 0, v[132:133]
	s_mov_b32 m0, s81
	v_lshl_add_u64 v[66:67], v[140:141], 0, s[12:13]
	ds_read_b128 v[34:37], v143
	ds_read_b128 v[38:41], v143 offset:1024
	ds_read_b128 v[42:45], v143 offset:2048
	ds_read_b128 v[46:49], v143 offset:3072
	ds_read_b128 v[50:53], v143 offset:4096
	ds_read_b128 v[54:57], v143 offset:5120
	ds_read_b128 v[58:61], v143 offset:6144
	ds_read_b128 v[62:65], v143 offset:7168
	global_load_lds_dwordx4 v[66:67], off
	v_lshl_add_u64 v[66:67], v[140:141], 0, s[14:15]
	s_mov_b32 m0, s82
	s_nop 0
	global_load_lds_dwordx4 v[66:67], off
	s_waitcnt vmcnt(16)
	s_waitcnt lgkmcnt(0)
	s_barrier
	s_waitcnt lgkmcnt(0)
	v_mfma_f32_16x16x32_bf16 v[86:89], v[10:13], v[50:53], 0
	v_mfma_f32_16x16x32_bf16 v[90:93], v[14:17], v[54:57], v[86:89]
	v_mfma_f32_16x16x32_bf16 v[86:89], v[2:5], v[58:61], 0
	v_mfma_f32_16x16x32_bf16 v[66:69], v[2:5], v[34:37], 0
	v_mfma_f32_16x16x32_bf16 v[70:73], v[10:13], v[34:37], 0
	v_mfma_f32_16x16x32_bf16 v[74:77], v[2:5], v[42:45], 0
	v_mfma_f32_16x16x32_bf16 v[78:81], v[10:13], v[42:45], 0
	v_mfma_f32_16x16x32_bf16 v[82:85], v[2:5], v[50:53], 0
	v_mfma_f32_16x16x32_bf16 v[94:97], v[6:9], v[62:65], v[86:89]
	v_mfma_f32_16x16x32_bf16 v[86:89], v[10:13], v[58:61], 0
	v_mfma_f32_16x16x32_bf16 v[66:69], v[6:9], v[38:41], v[66:69]
	v_mfma_f32_16x16x32_bf16 v[70:73], v[14:17], v[38:41], v[70:73]
	v_mfma_f32_16x16x32_bf16 v[74:77], v[6:9], v[46:49], v[74:77]
	v_mfma_f32_16x16x32_bf16 v[78:81], v[14:17], v[46:49], v[78:81]
	v_mfma_f32_16x16x32_bf16 v[82:85], v[6:9], v[54:57], v[82:85]
	v_mfma_f32_16x16x32_bf16 v[106:109], v[14:17], v[62:65], v[86:89]
	v_mfma_f32_16x16x32_bf16 v[86:89], v[18:21], v[34:37], 0
	v_mfma_f32_16x16x32_bf16 v[34:37], v[26:29], v[34:37], 0
	v_mfma_f32_16x16x32_bf16 v[110:113], v[22:25], v[38:41], v[86:89]
	v_mfma_f32_16x16x32_bf16 v[34:37], v[30:33], v[38:41], v[34:37]
	v_mfma_f32_16x16x32_bf16 v[38:41], v[18:21], v[42:45], 0
	v_mfma_f32_16x16x32_bf16 v[42:45], v[26:29], v[42:45], 0
	v_mfma_f32_16x16x32_bf16 v[38:41], v[22:25], v[46:49], v[38:41]
	v_mfma_f32_16x16x32_bf16 v[42:45], v[30:33], v[46:49], v[42:45]
	v_mfma_f32_16x16x32_bf16 v[46:49], v[18:21], v[50:53], 0
	v_mfma_f32_16x16x32_bf16 v[50:53], v[26:29], v[50:53], 0
	v_mfma_f32_16x16x32_bf16 v[46:49], v[22:25], v[54:57], v[46:49]
	v_mfma_f32_16x16x32_bf16 v[50:53], v[30:33], v[54:57], v[50:53]
	v_mfma_f32_16x16x32_bf16 v[54:57], v[18:21], v[58:61], 0
	v_mfma_f32_16x16x32_bf16 v[58:61], v[26:29], v[58:61], 0
	v_mfma_f32_16x16x32_bf16 v[54:57], v[22:25], v[62:65], v[54:57]
	v_mfma_f32_16x16x32_bf16 v[58:61], v[30:33], v[62:65], v[58:61]
	s_barrier
	v_lshl_add_u64 v[238:239], s[76:77], 0, v[130:131]
	s_mov_b32 m0, s83
	v_lshl_add_u64 v[146:147], v[238:239], 0, s[16:17]
	s_add_i32 s91, s83, 0x2000
	ds_read_b128 v[62:65], v143 offset:16384
	ds_read_b128 v[86:89], v143 offset:17408
	ds_read_b128 v[98:101], v143 offset:18432
	ds_read_b128 v[102:105], v143 offset:19456
	ds_read_b128 v[114:117], v143 offset:20480
	ds_read_b128 v[118:121], v143 offset:21504
	ds_read_b128 v[122:125], v143 offset:22528
	ds_read_b128 v[126:129], v143 offset:23552
	global_load_lds_dwordx4 v[146:147], off
	v_lshl_add_u64 v[146:147], v[238:239], 0, s[18:19]
	s_mov_b32 m0, s91
	s_add_i32 s40, s80, s43
	global_load_lds_dwordx4 v[146:147], off
	v_lshl_add_u64 v[146:147], v[238:239], 0, s[20:21]
	s_mov_b32 m0, s40
	s_add_i32 s41, s40, 0x2000
	global_load_lds_dwordx4 v[146:147], off
	v_lshl_add_u64 v[146:147], v[238:239], 0, s[22:23]
	s_mov_b32 m0, s41
	s_nop 0
	global_load_lds_dwordx4 v[146:147], off
	v_lshl_add_u64 v[146:147], v[140:141], 0, s[16:17]
	s_mov_b32 m0, s45
	s_nop 0
	global_load_lds_dwordx4 v[146:147], off
	v_lshl_add_u64 v[146:147], v[140:141], 0, s[18:19]
	s_mov_b32 m0, s46
	s_nop 0
	global_load_lds_dwordx4 v[146:147], off
	s_waitcnt vmcnt(16)
	s_waitcnt lgkmcnt(0)
	s_barrier
	s_waitcnt lgkmcnt(0)
	v_mfma_f32_16x16x32_bf16 v[146:149], v[2:5], v[62:65], 0
	v_mfma_f32_16x16x32_bf16 v[154:157], v[2:5], v[98:101], 0
	v_mfma_f32_16x16x32_bf16 v[162:165], v[2:5], v[114:117], 0
	v_mfma_f32_16x16x32_bf16 v[2:5], v[2:5], v[122:125], 0
	v_mfma_f32_16x16x32_bf16 v[146:149], v[6:9], v[86:89], v[146:149]
	v_mfma_f32_16x16x32_bf16 v[154:157], v[6:9], v[102:105], v[154:157]
	v_mfma_f32_16x16x32_bf16 v[162:165], v[6:9], v[118:121], v[162:165]
	v_mfma_f32_16x16x32_bf16 v[2:5], v[6:9], v[126:129], v[2:5]
	v_mfma_f32_16x16x32_bf16 v[6:9], v[10:13], v[122:125], 0
	v_mfma_f32_16x16x32_bf16 v[150:153], v[10:13], v[62:65], 0
	v_mfma_f32_16x16x32_bf16 v[158:161], v[10:13], v[98:101], 0
	v_mfma_f32_16x16x32_bf16 v[166:169], v[10:13], v[114:117], 0
	v_mfma_f32_16x16x32_bf16 v[10:13], v[14:17], v[126:129], v[6:9]
	v_mfma_f32_16x16x32_bf16 v[150:153], v[14:17], v[86:89], v[150:153]
	v_mfma_f32_16x16x32_bf16 v[158:161], v[14:17], v[102:105], v[158:161]
	v_mfma_f32_16x16x32_bf16 v[166:169], v[14:17], v[118:121], v[166:169]
	v_mfma_f32_16x16x32_bf16 v[6:9], v[18:21], v[62:65], 0
	v_mfma_f32_16x16x32_bf16 v[14:17], v[22:25], v[86:89], v[6:9]
	v_mfma_f32_16x16x32_bf16 v[6:9], v[26:29], v[62:65], 0
	v_mfma_f32_16x16x32_bf16 v[170:173], v[30:33], v[86:89], v[6:9]
	v_mfma_f32_16x16x32_bf16 v[6:9], v[18:21], v[98:101], 0
	v_mfma_f32_16x16x32_bf16 v[174:177], v[22:25], v[102:105], v[6:9]
	v_mfma_f32_16x16x32_bf16 v[6:9], v[26:29], v[98:101], 0
	v_mfma_f32_16x16x32_bf16 v[178:181], v[30:33], v[102:105], v[6:9]
	v_mfma_f32_16x16x32_bf16 v[6:9], v[18:21], v[114:117], 0
	v_mfma_f32_16x16x32_bf16 v[182:185], v[22:25], v[118:121], v[6:9]
	v_mfma_f32_16x16x32_bf16 v[6:9], v[26:29], v[114:117], 0
	v_mfma_f32_16x16x32_bf16 v[186:189], v[30:33], v[118:121], v[6:9]
	v_mfma_f32_16x16x32_bf16 v[6:9], v[18:21], v[122:125], 0
	v_mfma_f32_16x16x32_bf16 v[190:193], v[22:25], v[126:129], v[6:9]
	v_mfma_f32_16x16x32_bf16 v[6:9], v[26:29], v[122:125], 0
	v_mfma_f32_16x16x32_bf16 v[194:197], v[30:33], v[126:129], v[6:9]
	s_barrier
; #define PG8_WAIT_V(n) asm volatile("s_waitcnt vmcnt(" #n ")" ::: "memory")
; template <class Epi, class Sched, bool ALIGN_EPI = true, bool SP2 = true, bool FULLLINE = false, bool NOSTAGE = false, bool FP8 = false>
; __device__ __forceinline__ void gemm_phase(PG8_LAS unsigned char* lds, const Gemm g, const Sched& S, const Epi& E) {
;     ...
;         static_assert(SP2, "only the SP2 loop is kept");
;         { const int t = 0; if constexpr (Epi::NST == 16) PG8_ITER(PG8_WAIT_V(24)); else if constexpr (Epi::NST == 8) PG8_ITER(PG8_WAIT_V(16)); else PG8_ITER(PG8_WAIT_V(8)); }
;         for (int t = 2; t < nt; t += 2) PG8_ITER(PG8_WAIT_V(8));
	s_nop 5
	ds_read_b128 v[6:9], v144
	ds_read_b128 v[26:29], v144 offset:1024
	ds_read_b128 v[30:33], v144 offset:2048
	ds_read_b128 v[62:65], v144 offset:3072
	ds_read_b128 v[198:201], v145
	ds_read_b128 v[202:205], v145 offset:1024
	ds_read_b128 v[206:209], v145 offset:2048
	ds_read_b128 v[210:213], v145 offset:3072
	s_mov_b32 m0, s47
	v_lshl_add_u64 v[86:87], v[140:141], 0, s[20:21]
	ds_read_b128 v[18:21], v143 offset:32768
	ds_read_b128 v[22:25], v143 offset:33792
	ds_read_b128 v[214:217], v143 offset:34816
	ds_read_b128 v[218:221], v143 offset:35840
	ds_read_b128 v[222:225], v143 offset:36864
	ds_read_b128 v[226:229], v143 offset:37888
	ds_read_b128 v[230:233], v143 offset:38912
	ds_read_b128 v[234:237], v143 offset:39936
	global_load_lds_dwordx4 v[86:87], off
	v_lshl_add_u64 v[86:87], v[140:141], 0, s[22:23]
	s_mov_b32 m0, s52
	s_nop 0
	global_load_lds_dwordx4 v[86:87], off
	s_waitcnt vmcnt(8)
	s_waitcnt lgkmcnt(0)
	s_barrier
	s_waitcnt lgkmcnt(0)
	v_mfma_f32_16x16x32_bf16 v[66:69], v[6:9], v[18:21], v[66:69]
	v_mfma_f32_16x16x32_bf16 v[118:121], v[26:29], v[22:25], v[66:69]
	v_mfma_f32_16x16x32_bf16 v[66:69], v[30:33], v[18:21], v[70:73]
	v_mfma_f32_16x16x32_bf16 v[114:117], v[62:65], v[22:25], v[66:69]
	v_mfma_f32_16x16x32_bf16 v[66:69], v[6:9], v[214:217], v[74:77]
	v_mfma_f32_16x16x32_bf16 v[102:105], v[26:29], v[218:221], v[66:69]
	v_mfma_f32_16x16x32_bf16 v[66:69], v[30:33], v[214:217], v[78:81]
	v_mfma_f32_16x16x32_bf16 v[98:101], v[62:65], v[218:221], v[66:69]
	v_mfma_f32_16x16x32_bf16 v[66:69], v[6:9], v[222:225], v[82:85]
	v_mfma_f32_16x16x32_bf16 v[86:89], v[26:29], v[226:229], v[66:69]
	v_mfma_f32_16x16x32_bf16 v[66:69], v[30:33], v[222:225], v[90:93]
	v_mfma_f32_16x16x32_bf16 v[82:85], v[62:65], v[226:229], v[66:69]
	v_mfma_f32_16x16x32_bf16 v[66:69], v[6:9], v[230:233], v[94:97]
	v_mfma_f32_16x16x32_bf16 v[70:73], v[26:29], v[234:237], v[66:69]
	v_mfma_f32_16x16x32_bf16 v[66:69], v[30:33], v[230:233], v[106:109]
	v_mfma_f32_16x16x32_bf16 v[66:69], v[62:65], v[234:237], v[66:69]
	v_mfma_f32_16x16x32_bf16 v[74:77], v[198:201], v[18:21], v[110:113]
	v_mfma_f32_16x16x32_bf16 v[18:21], v[206:209], v[18:21], v[34:37]
	v_mfma_f32_16x16x32_bf16 v[122:125], v[210:213], v[22:25], v[18:21]
	v_mfma_f32_16x16x32_bf16 v[18:21], v[198:201], v[214:217], v[38:41]
	v_mfma_f32_16x16x32_bf16 v[110:113], v[202:205], v[218:221], v[18:21]
	v_mfma_f32_16x16x32_bf16 v[18:21], v[206:209], v[214:217], v[42:45]
	v_mfma_f32_16x16x32_bf16 v[106:109], v[210:213], v[218:221], v[18:21]
	v_mfma_f32_16x16x32_bf16 v[18:21], v[198:201], v[222:225], v[46:49]
	v_mfma_f32_16x16x32_bf16 v[94:97], v[202:205], v[226:229], v[18:21]
	v_mfma_f32_16x16x32_bf16 v[18:21], v[206:209], v[222:225], v[50:53]
	v_mfma_f32_16x16x32_bf16 v[90:93], v[210:213], v[226:229], v[18:21]
	v_mfma_f32_16x16x32_bf16 v[18:21], v[198:201], v[230:233], v[54:57]
	v_mfma_f32_16x16x32_bf16 v[78:81], v[202:205], v[234:237], v[18:21]
	v_mfma_f32_16x16x32_bf16 v[18:21], v[206:209], v[230:233], v[58:61]
	v_mfma_f32_16x16x32_bf16 v[126:129], v[202:205], v[22:25], v[74:77]
	v_mfma_f32_16x16x32_bf16 v[74:77], v[210:213], v[234:237], v[18:21]
	s_barrier
	s_add_i32 s50, s84, s43
	s_nop 3
	v_lshl_add_u64 v[18:19], v[238:239], 0, s[24:25]
	s_mov_b32 m0, s50
	s_add_i32 s51, s50, 0x2000
	ds_read_b128 v[42:45], v143 offset:49152
	ds_read_b128 v[46:49], v143 offset:50176
	ds_read_b128 v[214:217], v143 offset:51200
	ds_read_b128 v[218:221], v143 offset:52224
	ds_read_b128 v[222:225], v143 offset:53248
	ds_read_b128 v[226:229], v143 offset:54272
	ds_read_b128 v[230:233], v143 offset:55296
	ds_read_b128 v[234:237], v143 offset:56320
	global_load_lds_dwordx4 v[18:19], off
	v_lshl_add_u64 v[18:19], v[238:239], 0, s[26:27]
	s_mov_b32 m0, s51
	s_mov_b64 s[0:1], 0x80180
	s_add_i32 s33, s85, s43
	global_load_lds_dwordx4 v[18:19], off
	v_lshl_add_u64 v[18:19], v[238:239], 0, s[0:1]
	s_mov_b32 m0, s33
	s_mov_b64 s[0:1], 0xc0180
	s_add_i32 s56, s33, 0x2000
	global_load_lds_dwordx4 v[18:19], off
	v_lshl_add_u64 v[18:19], v[238:239], 0, s[0:1]
	s_mov_b32 m0, s56
	s_nop 0
	global_load_lds_dwordx4 v[18:19], off
	v_lshl_add_u64 v[18:19], v[140:141], 0, s[24:25]
	s_mov_b32 m0, s53
	s_nop 0
	global_load_lds_dwordx4 v[18:19], off
	v_lshl_add_u64 v[18:19], v[140:141], 0, s[26:27]
	s_mov_b32 m0, s54
	s_nop 0
	global_load_lds_dwordx4 v[18:19], off
	s_waitcnt vmcnt(8)
	s_waitcnt lgkmcnt(0)
	s_barrier
	s_waitcnt lgkmcnt(0)
	v_mfma_f32_16x16x32_bf16 v[18:21], v[6:9], v[42:45], v[146:149]
	v_mfma_f32_16x16x32_bf16 v[54:57], v[26:29], v[46:49], v[18:21]
	v_mfma_f32_16x16x32_bf16 v[18:21], v[30:33], v[42:45], v[150:153]
	v_mfma_f32_16x16x32_bf16 v[50:53], v[62:65], v[46:49], v[18:21]
	v_mfma_f32_16x16x32_bf16 v[18:21], v[6:9], v[214:217], v[154:157]
	v_mfma_f32_16x16x32_bf16 v[38:41], v[26:29], v[218:221], v[18:21]
	v_mfma_f32_16x16x32_bf16 v[18:21], v[30:33], v[214:217], v[158:161]
	v_mfma_f32_16x16x32_bf16 v[34:37], v[62:65], v[218:221], v[18:21]
	v_mfma_f32_16x16x32_bf16 v[18:21], v[6:9], v[222:225], v[162:165]
	v_mfma_f32_16x16x32_bf16 v[2:5], v[6:9], v[230:233], v[2:5]
	v_mfma_f32_16x16x32_bf16 v[22:25], v[26:29], v[226:229], v[18:21]
	v_mfma_f32_16x16x32_bf16 v[18:21], v[30:33], v[222:225], v[166:169]
	v_mfma_f32_16x16x32_bf16 v[6:9], v[26:29], v[234:237], v[2:5]
	v_mfma_f32_16x16x32_bf16 v[2:5], v[30:33], v[230:233], v[10:13]
	v_mfma_f32_16x16x32_bf16 v[18:21], v[62:65], v[226:229], v[18:21]
	v_mfma_f32_16x16x32_bf16 v[2:5], v[62:65], v[234:237], v[2:5]
	v_mfma_f32_16x16x32_bf16 v[10:13], v[198:201], v[42:45], v[14:17]
	v_mfma_f32_16x16x32_bf16 v[62:65], v[202:205], v[46:49], v[10:13]
	v_mfma_f32_16x16x32_bf16 v[10:13], v[206:209], v[42:45], v[170:173]
	v_mfma_f32_16x16x32_bf16 v[58:61], v[210:213], v[46:49], v[10:13]
	v_mfma_f32_16x16x32_bf16 v[10:13], v[198:201], v[214:217], v[174:177]
	v_mfma_f32_16x16x32_bf16 v[46:49], v[202:205], v[218:221], v[10:13]
	v_mfma_f32_16x16x32_bf16 v[10:13], v[206:209], v[214:217], v[178:181]
	v_mfma_f32_16x16x32_bf16 v[42:45], v[210:213], v[218:221], v[10:13]
	v_mfma_f32_16x16x32_bf16 v[10:13], v[198:201], v[222:225], v[182:185]
	v_mfma_f32_16x16x32_bf16 v[30:33], v[202:205], v[226:229], v[10:13]
	v_mfma_f32_16x16x32_bf16 v[10:13], v[206:209], v[222:225], v[186:189]
	v_mfma_f32_16x16x32_bf16 v[26:29], v[210:213], v[226:229], v[10:13]
	v_mfma_f32_16x16x32_bf16 v[10:13], v[198:201], v[230:233], v[190:193]
	v_mfma_f32_16x16x32_bf16 v[14:17], v[202:205], v[234:237], v[10:13]
	v_mfma_f32_16x16x32_bf16 v[10:13], v[206:209], v[230:233], v[194:197]
	v_mfma_f32_16x16x32_bf16 v[10:13], v[210:213], v[234:237], v[10:13]
	s_barrier
	s_add_u32 s78, s78, 0x80180
	s_addc_u32 s79, s79, 0
	s_add_u32 s57, s76, 0x200
	s_addc_u32 s76, s77, 0
	s_mov_b32 s77, 0
	.p2align 6

.LBB0_1483:
	ds_read_b128 v[2:5], v1
	ds_read_b128 v[6:9], v1 offset:1024
	ds_read_b128 v[10:13], v1 offset:2048
	ds_read_b128 v[14:17], v1 offset:3072
	ds_read_b128 v[18:21], v192
	ds_read_b128 v[22:25], v192 offset:1024
	ds_read_b128 v[26:29], v192 offset:2048
	ds_read_b128 v[30:33], v192 offset:3072
	v_lshl_add_u64 v[248:249], s[70:71], 0, v[170:171]
	s_add_i32 s85, s45, 0xc000
	v_lshl_add_u64 v[66:67], v[248:249], 0, s[14:15]
	s_mov_b32 m0, s85
	s_add_i32 s87, s45, 0xe000
	ds_read_b128 v[34:37], v193
	ds_read_b128 v[38:41], v193 offset:1024
	ds_read_b128 v[42:45], v193 offset:2048
	ds_read_b128 v[46:49], v193 offset:3072
	ds_read_b128 v[50:53], v193 offset:4096
	ds_read_b128 v[54:57], v193 offset:5120
	ds_read_b128 v[58:61], v193 offset:6144
	ds_read_b128 v[62:65], v193 offset:7168
	global_load_lds_dwordx4 v[66:67], off
	v_lshl_add_u64 v[66:67], v[248:249], 0, s[16:17]
	s_mov_b32 m0, s87
	s_nop 0
	global_load_lds_dwordx4 v[66:67], off
	s_waitcnt vmcnt(24)
	s_waitcnt lgkmcnt(0)
	s_barrier
	s_waitcnt lgkmcnt(0)
	v_mfma_f32_16x16x32_bf16 v[66:69], v[2:5], v[34:37], 0
	v_mfma_f32_16x16x32_bf16 v[70:73], v[10:13], v[34:37], 0
	v_mfma_f32_16x16x32_bf16 v[78:81], v[10:13], v[42:45], 0
	v_mfma_f32_16x16x32_bf16 v[86:89], v[10:13], v[50:53], 0
	v_mfma_f32_16x16x32_bf16 v[66:69], v[6:9], v[38:41], v[66:69]
	v_mfma_f32_16x16x32_bf16 v[70:73], v[14:17], v[38:41], v[70:73]
	v_mfma_f32_16x16x32_bf16 v[74:77], v[2:5], v[42:45], 0
	v_mfma_f32_16x16x32_bf16 v[78:81], v[14:17], v[46:49], v[78:81]
	v_mfma_f32_16x16x32_bf16 v[82:85], v[2:5], v[50:53], 0
	v_mfma_f32_16x16x32_bf16 v[86:89], v[14:17], v[54:57], v[86:89]
	v_mfma_f32_16x16x32_bf16 v[90:93], v[2:5], v[58:61], 0
	v_mfma_f32_16x16x32_bf16 v[94:97], v[10:13], v[58:61], 0
	v_mfma_f32_16x16x32_bf16 v[74:77], v[6:9], v[46:49], v[74:77]
	v_mfma_f32_16x16x32_bf16 v[82:85], v[6:9], v[54:57], v[82:85]
	v_mfma_f32_16x16x32_bf16 v[90:93], v[6:9], v[62:65], v[90:93]
	v_mfma_f32_16x16x32_bf16 v[94:97], v[14:17], v[62:65], v[94:97]
	v_mfma_f32_16x16x32_bf16 v[98:101], v[18:21], v[34:37], 0
	v_mfma_f32_16x16x32_bf16 v[34:37], v[26:29], v[34:37], 0
	v_mfma_f32_16x16x32_bf16 v[98:101], v[22:25], v[38:41], v[98:101]
	v_mfma_f32_16x16x32_bf16 v[34:37], v[30:33], v[38:41], v[34:37]
	v_mfma_f32_16x16x32_bf16 v[38:41], v[18:21], v[42:45], 0
	v_mfma_f32_16x16x32_bf16 v[42:45], v[26:29], v[42:45], 0
	v_mfma_f32_16x16x32_bf16 v[38:41], v[22:25], v[46:49], v[38:41]
	v_mfma_f32_16x16x32_bf16 v[42:45], v[30:33], v[46:49], v[42:45]
	v_mfma_f32_16x16x32_bf16 v[46:49], v[18:21], v[50:53], 0
	v_mfma_f32_16x16x32_bf16 v[50:53], v[26:29], v[50:53], 0
	v_mfma_f32_16x16x32_bf16 v[46:49], v[22:25], v[54:57], v[46:49]
	v_mfma_f32_16x16x32_bf16 v[50:53], v[30:33], v[54:57], v[50:53]
	v_mfma_f32_16x16x32_bf16 v[54:57], v[18:21], v[58:61], 0
	v_mfma_f32_16x16x32_bf16 v[58:61], v[26:29], v[58:61], 0
	v_mfma_f32_16x16x32_bf16 v[54:57], v[22:25], v[62:65], v[54:57]
	v_mfma_f32_16x16x32_bf16 v[58:61], v[30:33], v[62:65], v[58:61]
	s_barrier
	v_lshl_add_u64 v[250:251], s[72:73], 0, v[172:173]
	s_add_i32 s88, s77, s44
	v_lshl_add_u64 v[130:131], v[250:251], 0, s[18:19]
	s_mov_b32 m0, s88
	s_add_i32 s89, s88, 0x2000
	ds_read_b128 v[62:65], v193 offset:16384
	ds_read_b128 v[102:105], v193 offset:17408
	ds_read_b128 v[106:109], v193 offset:18432
	ds_read_b128 v[110:113], v193 offset:19456
	ds_read_b128 v[114:117], v193 offset:20480
	ds_read_b128 v[118:121], v193 offset:21504
	ds_read_b128 v[122:125], v193 offset:22528
	ds_read_b128 v[126:129], v193 offset:23552
	global_load_lds_dwordx4 v[130:131], off
	v_lshl_add_u64 v[130:131], v[250:251], 0, s[20:21]
	s_mov_b32 m0, s89
	s_add_i32 s40, s78, s44
	global_load_lds_dwordx4 v[130:131], off
	v_lshl_add_u64 v[130:131], v[250:251], 0, s[22:23]
	s_mov_b32 m0, s40
	s_add_i32 s41, s40, 0x2000
	global_load_lds_dwordx4 v[130:131], off
	v_lshl_add_u64 v[130:131], v[250:251], 0, s[24:25]
	s_mov_b32 m0, s41
	s_nop 0
	global_load_lds_dwordx4 v[130:131], off
	v_lshl_add_u64 v[130:131], v[248:249], 0, s[18:19]
	s_mov_b32 m0, s45
	s_nop 0
	global_load_lds_dwordx4 v[130:131], off
	v_lshl_add_u64 v[130:131], v[248:249], 0, s[20:21]
	s_mov_b32 m0, s46
	s_nop 0
	global_load_lds_dwordx4 v[130:131], off
	s_waitcnt vmcnt(24)
	s_waitcnt lgkmcnt(0)
	s_barrier
	s_waitcnt lgkmcnt(0)
	v_mfma_f32_16x16x32_bf16 v[130:133], v[2:5], v[62:65], 0
	v_mfma_f32_16x16x32_bf16 v[138:141], v[6:9], v[102:105], v[130:133]
	v_mfma_f32_16x16x32_bf16 v[130:133], v[10:13], v[62:65], 0
	v_mfma_f32_16x16x32_bf16 v[150:153], v[14:17], v[102:105], v[130:133]
	v_mfma_f32_16x16x32_bf16 v[130:133], v[2:5], v[106:109], 0
	v_mfma_f32_16x16x32_bf16 v[154:157], v[6:9], v[110:113], v[130:133]
	v_mfma_f32_16x16x32_bf16 v[130:133], v[10:13], v[106:109], 0
	v_mfma_f32_16x16x32_bf16 v[158:161], v[14:17], v[110:113], v[130:133]
	v_mfma_f32_16x16x32_bf16 v[130:133], v[2:5], v[114:117], 0
	v_mfma_f32_16x16x32_bf16 v[2:5], v[2:5], v[122:125], 0
	v_mfma_f32_16x16x32_bf16 v[162:165], v[6:9], v[118:121], v[130:133]
	v_mfma_f32_16x16x32_bf16 v[2:5], v[6:9], v[126:129], v[2:5]
	v_mfma_f32_16x16x32_bf16 v[6:9], v[10:13], v[122:125], 0
	v_mfma_f32_16x16x32_bf16 v[130:133], v[10:13], v[114:117], 0
	v_mfma_f32_16x16x32_bf16 v[6:9], v[14:17], v[126:129], v[6:9]
	v_mfma_f32_16x16x32_bf16 v[166:169], v[14:17], v[118:121], v[130:133]
	v_mfma_f32_16x16x32_bf16 v[10:13], v[18:21], v[62:65], 0
	v_mfma_f32_16x16x32_bf16 v[180:183], v[22:25], v[102:105], v[10:13]
	v_mfma_f32_16x16x32_bf16 v[10:13], v[26:29], v[62:65], 0
	v_mfma_f32_16x16x32_bf16 v[184:187], v[30:33], v[102:105], v[10:13]
	v_mfma_f32_16x16x32_bf16 v[10:13], v[18:21], v[106:109], 0
	v_mfma_f32_16x16x32_bf16 v[188:191], v[22:25], v[110:113], v[10:13]
	v_mfma_f32_16x16x32_bf16 v[10:13], v[26:29], v[106:109], 0
	v_mfma_f32_16x16x32_bf16 v[196:199], v[30:33], v[110:113], v[10:13]
	v_mfma_f32_16x16x32_bf16 v[10:13], v[18:21], v[114:117], 0
	v_mfma_f32_16x16x32_bf16 v[200:203], v[22:25], v[118:121], v[10:13]
	v_mfma_f32_16x16x32_bf16 v[10:13], v[26:29], v[114:117], 0
	v_mfma_f32_16x16x32_bf16 v[204:207], v[30:33], v[118:121], v[10:13]
	v_mfma_f32_16x16x32_bf16 v[10:13], v[18:21], v[122:125], 0
	v_mfma_f32_16x16x32_bf16 v[208:211], v[22:25], v[126:129], v[10:13]
	v_mfma_f32_16x16x32_bf16 v[10:13], v[26:29], v[122:125], 0
	v_mfma_f32_16x16x32_bf16 v[212:215], v[30:33], v[126:129], v[10:13]
	s_barrier
; #define PG8_WAIT_V(n) asm volatile("s_waitcnt vmcnt(" #n ")" ::: "memory")
; template <class Epi, class Sched, bool ALIGN_EPI = true, bool SP2 = true, bool FULLLINE = false, bool NOSTAGE = false, bool FP8 = false>
; __device__ __forceinline__ void gemm_phase(PG8_LAS unsigned char* lds, const Gemm g, const Sched& S, const Epi& E) {
;     ...
;         static_assert(SP2, "only the SP2 loop is kept");
;         { const int t = 0; if constexpr (Epi::NST == 16) PG8_ITER(PG8_WAIT_V(24)); else if constexpr (Epi::NST == 8) PG8_ITER(PG8_WAIT_V(16)); else PG8_ITER(PG8_WAIT_V(8)); }
;         for (int t = 2; t < nt; t += 2) PG8_ITER(PG8_WAIT_V(8));
	s_nop 5
	ds_read_b128 v[10:13], v194
	ds_read_b128 v[14:17], v194 offset:1024
	ds_read_b128 v[18:21], v194 offset:2048
	ds_read_b128 v[22:25], v194 offset:3072
	ds_read_b128 v[216:219], v195
	ds_read_b128 v[220:223], v195 offset:1024
	ds_read_b128 v[224:227], v195 offset:2048
	ds_read_b128 v[228:231], v195 offset:3072
	s_mov_b32 m0, s47
	v_lshl_add_u64 v[106:107], v[248:249], 0, s[22:23]
	ds_read_b128 v[26:29], v193 offset:32768
	ds_read_b128 v[30:33], v193 offset:33792
	ds_read_b128 v[62:65], v193 offset:34816
	ds_read_b128 v[102:105], v193 offset:35840
	ds_read_b128 v[232:235], v193 offset:36864
	ds_read_b128 v[236:239], v193 offset:37888
	ds_read_b128 v[240:243], v193 offset:38912
	ds_read_b128 v[244:247], v193 offset:39936
	global_load_lds_dwordx4 v[106:107], off
	v_lshl_add_u64 v[106:107], v[248:249], 0, s[24:25]
	s_mov_b32 m0, s52
	s_nop 0
	global_load_lds_dwordx4 v[106:107], off
	s_waitcnt vmcnt(8)
	s_waitcnt lgkmcnt(0)
	s_barrier
	s_waitcnt lgkmcnt(0)
	v_mfma_f32_16x16x32_bf16 v[66:69], v[10:13], v[26:29], v[66:69]
	v_mfma_f32_16x16x32_bf16 v[146:149], v[14:17], v[30:33], v[66:69]
	v_mfma_f32_16x16x32_bf16 v[66:69], v[18:21], v[26:29], v[70:73]
	v_mfma_f32_16x16x32_bf16 v[142:145], v[22:25], v[30:33], v[66:69]
	v_mfma_f32_16x16x32_bf16 v[66:69], v[10:13], v[62:65], v[74:77]
	v_mfma_f32_16x16x32_bf16 v[126:129], v[14:17], v[102:105], v[66:69]
	v_mfma_f32_16x16x32_bf16 v[66:69], v[18:21], v[62:65], v[78:81]
	v_mfma_f32_16x16x32_bf16 v[122:125], v[22:25], v[102:105], v[66:69]
	v_mfma_f32_16x16x32_bf16 v[66:69], v[10:13], v[232:235], v[82:85]
	v_mfma_f32_16x16x32_bf16 v[110:113], v[14:17], v[236:239], v[66:69]
	v_mfma_f32_16x16x32_bf16 v[66:69], v[18:21], v[232:235], v[86:89]
	v_mfma_f32_16x16x32_bf16 v[106:109], v[22:25], v[236:239], v[66:69]
	v_mfma_f32_16x16x32_bf16 v[66:69], v[10:13], v[240:243], v[90:93]
	v_mfma_f32_16x16x32_bf16 v[86:89], v[14:17], v[244:247], v[66:69]
	v_mfma_f32_16x16x32_bf16 v[66:69], v[18:21], v[240:243], v[94:97]
	v_mfma_f32_16x16x32_bf16 v[78:81], v[22:25], v[244:247], v[66:69]
	v_mfma_f32_16x16x32_bf16 v[66:69], v[216:219], v[26:29], v[98:101]
	v_mfma_f32_16x16x32_bf16 v[26:29], v[224:227], v[26:29], v[34:37]
	v_mfma_f32_16x16x32_bf16 v[130:133], v[228:231], v[30:33], v[26:29]
	v_mfma_f32_16x16x32_bf16 v[26:29], v[216:219], v[62:65], v[38:41]
	v_mfma_f32_16x16x32_bf16 v[118:121], v[220:223], v[102:105], v[26:29]
	v_mfma_f32_16x16x32_bf16 v[26:29], v[224:227], v[62:65], v[42:45]
	v_mfma_f32_16x16x32_bf16 v[114:117], v[228:231], v[102:105], v[26:29]
	v_mfma_f32_16x16x32_bf16 v[26:29], v[216:219], v[232:235], v[46:49]
	v_mfma_f32_16x16x32_bf16 v[102:105], v[220:223], v[236:239], v[26:29]
	v_mfma_f32_16x16x32_bf16 v[26:29], v[224:227], v[232:235], v[50:53]
	v_mfma_f32_16x16x32_bf16 v[98:101], v[228:231], v[236:239], v[26:29]
	v_mfma_f32_16x16x32_bf16 v[26:29], v[216:219], v[240:243], v[54:57]
	v_mfma_f32_16x16x32_bf16 v[70:73], v[220:223], v[244:247], v[26:29]
	v_mfma_f32_16x16x32_bf16 v[26:29], v[224:227], v[240:243], v[58:61]
	v_mfma_f32_16x16x32_bf16 v[134:137], v[220:223], v[30:33], v[66:69]
	v_mfma_f32_16x16x32_bf16 v[66:69], v[228:231], v[244:247], v[26:29]
	s_barrier
	s_add_i32 s50, s79, s44
	s_nop 3
	v_lshl_add_u64 v[26:27], v[250:251], 0, s[26:27]
	s_mov_b32 m0, s50
	s_add_i32 s51, s50, 0x2000
	ds_read_b128 v[34:37], v193 offset:49152
	ds_read_b128 v[38:41], v193 offset:50176
	ds_read_b128 v[74:77], v193 offset:51200
	ds_read_b128 v[82:85], v193 offset:52224
	ds_read_b128 v[90:93], v193 offset:53248
	ds_read_b128 v[94:97], v193 offset:54272
	ds_read_b128 v[232:235], v193 offset:55296
	ds_read_b128 v[236:239], v193 offset:56320
	global_load_lds_dwordx4 v[26:27], off
	v_lshl_add_u64 v[26:27], v[250:251], 0, s[28:29]
	s_mov_b32 m0, s51
	s_mov_b64 s[0:1], 0x160180
	s_add_i32 s33, s80, s44
	global_load_lds_dwordx4 v[26:27], off
	v_lshl_add_u64 v[26:27], v[250:251], 0, s[0:1]
	s_mov_b32 m0, s33
	s_mov_b64 s[0:1], 0x210180
	s_add_i32 s56, s33, 0x2000
	global_load_lds_dwordx4 v[26:27], off
	v_lshl_add_u64 v[26:27], v[250:251], 0, s[0:1]
	s_mov_b32 m0, s56
	s_nop 0
	global_load_lds_dwordx4 v[26:27], off
	v_lshl_add_u64 v[26:27], v[248:249], 0, s[26:27]
	s_mov_b32 m0, s53
	s_nop 0
	global_load_lds_dwordx4 v[26:27], off
	v_lshl_add_u64 v[26:27], v[248:249], 0, s[28:29]
	s_mov_b32 m0, s54
	s_nop 0
	global_load_lds_dwordx4 v[26:27], off
	s_waitcnt vmcnt(8)
	s_waitcnt lgkmcnt(0)
	s_barrier
	s_waitcnt lgkmcnt(0)
	v_mfma_f32_16x16x32_bf16 v[26:29], v[10:13], v[34:37], v[138:141]
	v_mfma_f32_16x16x32_bf16 v[62:65], v[14:17], v[38:41], v[26:29]
	v_mfma_f32_16x16x32_bf16 v[26:29], v[18:21], v[34:37], v[150:153]
	v_mfma_f32_16x16x32_bf16 v[58:61], v[22:25], v[38:41], v[26:29]
	v_mfma_f32_16x16x32_bf16 v[26:29], v[10:13], v[74:77], v[154:157]
	v_mfma_f32_16x16x32_bf16 v[46:49], v[14:17], v[82:85], v[26:29]
	v_mfma_f32_16x16x32_bf16 v[26:29], v[18:21], v[74:77], v[158:161]
	v_mfma_f32_16x16x32_bf16 v[42:45], v[22:25], v[82:85], v[26:29]
	v_mfma_f32_16x16x32_bf16 v[26:29], v[10:13], v[90:93], v[162:165]
	v_mfma_f32_16x16x32_bf16 v[2:5], v[10:13], v[232:235], v[2:5]
	v_mfma_f32_16x16x32_bf16 v[30:33], v[14:17], v[94:97], v[26:29]
	v_mfma_f32_16x16x32_bf16 v[26:29], v[18:21], v[90:93], v[166:169]
	v_mfma_f32_16x16x32_bf16 v[14:17], v[14:17], v[236:239], v[2:5]
	v_mfma_f32_16x16x32_bf16 v[2:5], v[18:21], v[232:235], v[6:9]
	v_mfma_f32_16x16x32_bf16 v[26:29], v[22:25], v[94:97], v[26:29]
	v_mfma_f32_16x16x32_bf16 v[10:13], v[22:25], v[236:239], v[2:5]
	v_mfma_f32_16x16x32_bf16 v[2:5], v[216:219], v[34:37], v[180:183]
	v_mfma_f32_16x16x32_bf16 v[54:57], v[220:223], v[38:41], v[2:5]
	v_mfma_f32_16x16x32_bf16 v[2:5], v[224:227], v[34:37], v[184:187]
	v_mfma_f32_16x16x32_bf16 v[50:53], v[228:231], v[38:41], v[2:5]
	v_mfma_f32_16x16x32_bf16 v[2:5], v[216:219], v[74:77], v[188:191]
	v_mfma_f32_16x16x32_bf16 v[38:41], v[220:223], v[82:85], v[2:5]
	v_mfma_f32_16x16x32_bf16 v[2:5], v[224:227], v[74:77], v[196:199]
	v_mfma_f32_16x16x32_bf16 v[34:37], v[228:231], v[82:85], v[2:5]
	v_mfma_f32_16x16x32_bf16 v[2:5], v[216:219], v[90:93], v[200:203]
	v_mfma_f32_16x16x32_bf16 v[22:25], v[220:223], v[94:97], v[2:5]
	v_mfma_f32_16x16x32_bf16 v[2:5], v[224:227], v[90:93], v[204:207]
	v_mfma_f32_16x16x32_bf16 v[18:21], v[228:231], v[94:97], v[2:5]
	v_mfma_f32_16x16x32_bf16 v[2:5], v[216:219], v[232:235], v[208:211]
	v_mfma_f32_16x16x32_bf16 v[6:9], v[220:223], v[236:239], v[2:5]
	v_mfma_f32_16x16x32_bf16 v[2:5], v[224:227], v[232:235], v[212:215]
	v_mfma_f32_16x16x32_bf16 v[2:5], v[228:231], v[236:239], v[2:5]
	s_barrier
	s_add_u32 s70, s70, 0x160180
	s_addc_u32 s71, s71, 0
	s_add_u32 s57, s72, 0x200
	s_addc_u32 s72, s73, 0
	s_mov_b32 s73, 0
	.p2align 6

; template <class Epi, class Sched, bool ALIGN_EPI = true, bool SP2 = true, bool FULLLINE = false, bool NOSTAGE = false, bool FP8 = false>
; __device__ __forceinline__ void gemm_phase(PG8_LAS unsigned char* lds, const Gemm g, const Sched& S, const Epi& E) {
;     ...
;         const bool has_next = S.next(ui + 1, nxt);
;         const char* nA = has_next ? PG8_ABASE(nxt) : cA; const char* nB = has_next ? PG8_BBASE(nxt) : cB;
.LBB0_1645:
	s_ashr_i32 s71, s70, 31
	s_lshl_b64 s[0:1], s[70:71], 20
	s_add_u32 s72, s58, s0
	ds_read_b128 v[2:5], v144
	ds_read_b128 v[6:9], v144 offset:1024
	ds_read_b128 v[10:13], v144 offset:2048
	ds_read_b128 v[14:17], v144 offset:3072
	ds_read_b128 v[18:21], v145
	ds_read_b128 v[22:25], v145 offset:1024
	ds_read_b128 v[26:29], v145 offset:2048
	ds_read_b128 v[30:33], v145 offset:3072
	s_addc_u32 s73, s59, s1
	s_ashr_i32 s69, s68, 31
	s_lshl_b64 s[0:1], s[68:69], 20
	s_add_u32 s74, s44, s0
	s_addc_u32 s75, s45, s1
	s_and_b64 s[0:1], s[8:9], exec
	s_cselect_b32 s11, s73, s79
	s_cselect_b32 s14, s72, s78
	s_cselect_b32 s69, s75, s77
	s_cselect_b32 s71, s74, s76
	v_lshl_add_u64 v[242:243], s[78:79], 0, v[130:131]
	s_mov_b32 m0, s97
	v_lshl_add_u64 v[66:67], v[242:243], 0, s[16:17]
	ds_read_b128 v[34:37], v146
	ds_read_b128 v[38:41], v146 offset:1024
	ds_read_b128 v[42:45], v146 offset:2048
	ds_read_b128 v[46:49], v146 offset:3072
	ds_read_b128 v[50:53], v146 offset:4096
	ds_read_b128 v[54:57], v146 offset:5120
	ds_read_b128 v[58:61], v146 offset:6144
	ds_read_b128 v[62:65], v146 offset:7168
	global_load_lds_dwordx4 v[66:67], off
	v_lshl_add_u64 v[66:67], v[242:243], 0, s[18:19]
	s_mov_b32 m0, s47
	s_nop 0
	global_load_lds_dwordx4 v[66:67], off
	s_waitcnt vmcnt(24)
	s_waitcnt lgkmcnt(0)
	s_barrier
	s_waitcnt lgkmcnt(0)
	v_mfma_f32_16x16x32_bf16 v[90:93], v[2:5], v[58:61], 0
	v_mfma_f32_16x16x32_bf16 v[66:69], v[2:5], v[34:37], 0
	v_mfma_f32_16x16x32_bf16 v[70:73], v[10:13], v[34:37], 0
	v_mfma_f32_16x16x32_bf16 v[74:77], v[2:5], v[42:45], 0
	v_mfma_f32_16x16x32_bf16 v[78:81], v[10:13], v[42:45], 0
	v_mfma_f32_16x16x32_bf16 v[82:85], v[2:5], v[50:53], 0
	v_mfma_f32_16x16x32_bf16 v[86:89], v[10:13], v[50:53], 0
	v_mfma_f32_16x16x32_bf16 v[98:101], v[6:9], v[62:65], v[90:93]
	v_mfma_f32_16x16x32_bf16 v[90:93], v[10:13], v[58:61], 0
	v_mfma_f32_16x16x32_bf16 v[66:69], v[6:9], v[38:41], v[66:69]
	v_mfma_f32_16x16x32_bf16 v[70:73], v[14:17], v[38:41], v[70:73]
	v_mfma_f32_16x16x32_bf16 v[74:77], v[6:9], v[46:49], v[74:77]
	v_mfma_f32_16x16x32_bf16 v[78:81], v[14:17], v[46:49], v[78:81]
	v_mfma_f32_16x16x32_bf16 v[82:85], v[6:9], v[54:57], v[82:85]
	v_mfma_f32_16x16x32_bf16 v[86:89], v[14:17], v[54:57], v[86:89]
	v_mfma_f32_16x16x32_bf16 v[102:105], v[14:17], v[62:65], v[90:93]
	v_mfma_f32_16x16x32_bf16 v[90:93], v[18:21], v[34:37], 0
	v_mfma_f32_16x16x32_bf16 v[34:37], v[26:29], v[34:37], 0
	v_mfma_f32_16x16x32_bf16 v[114:117], v[22:25], v[38:41], v[90:93]
	v_mfma_f32_16x16x32_bf16 v[34:37], v[30:33], v[38:41], v[34:37]
	v_mfma_f32_16x16x32_bf16 v[38:41], v[18:21], v[42:45], 0
	v_mfma_f32_16x16x32_bf16 v[42:45], v[26:29], v[42:45], 0
	v_mfma_f32_16x16x32_bf16 v[38:41], v[22:25], v[46:49], v[38:41]
	v_mfma_f32_16x16x32_bf16 v[42:45], v[30:33], v[46:49], v[42:45]
	v_mfma_f32_16x16x32_bf16 v[46:49], v[18:21], v[50:53], 0
	v_mfma_f32_16x16x32_bf16 v[50:53], v[26:29], v[50:53], 0
	v_mfma_f32_16x16x32_bf16 v[46:49], v[22:25], v[54:57], v[46:49]
	v_mfma_f32_16x16x32_bf16 v[50:53], v[30:33], v[54:57], v[50:53]
	v_mfma_f32_16x16x32_bf16 v[54:57], v[18:21], v[58:61], 0
	v_mfma_f32_16x16x32_bf16 v[58:61], v[26:29], v[58:61], 0
	v_mfma_f32_16x16x32_bf16 v[54:57], v[22:25], v[62:65], v[54:57]
	v_mfma_f32_16x16x32_bf16 v[58:61], v[30:33], v[62:65], v[58:61]
	s_barrier
	v_lshl_add_u64 v[244:245], s[76:77], 0, v[132:133]
	s_add_i32 s81, s95, s46
	v_lshl_add_u64 v[140:141], v[244:245], 0, s[20:21]
	s_mov_b32 m0, s81
	s_add_i32 s82, s81, 0x2000
	ds_read_b128 v[62:65], v146 offset:16384
	ds_read_b128 v[90:93], v146 offset:17408
	ds_read_b128 v[94:97], v146 offset:18432
	ds_read_b128 v[106:109], v146 offset:19456
	ds_read_b128 v[110:113], v146 offset:20480
	ds_read_b128 v[118:121], v146 offset:21504
	ds_read_b128 v[122:125], v146 offset:22528
	ds_read_b128 v[126:129], v146 offset:23552
	global_load_lds_dwordx4 v[140:141], off
	v_lshl_add_u64 v[140:141], v[244:245], 0, s[22:23]
	s_mov_b32 m0, s82
	s_add_i32 s83, s96, s46
	global_load_lds_dwordx4 v[140:141], off
	v_lshl_add_u64 v[140:141], v[244:245], 0, s[24:25]
	s_mov_b32 m0, s83
	s_add_i32 s84, s83, 0x2000
	global_load_lds_dwordx4 v[140:141], off
	v_lshl_add_u64 v[140:141], v[244:245], 0, s[26:27]
	s_mov_b32 m0, s84
	s_nop 0
	global_load_lds_dwordx4 v[140:141], off
	v_lshl_add_u64 v[140:141], v[242:243], 0, s[20:21]
	s_mov_b32 m0, s87
	s_nop 0
	global_load_lds_dwordx4 v[140:141], off
	v_lshl_add_u64 v[140:141], v[242:243], 0, s[22:23]
	s_mov_b32 m0, s52
	s_nop 0
	global_load_lds_dwordx4 v[140:141], off
	s_waitcnt vmcnt(24)
	s_waitcnt lgkmcnt(0)
	s_barrier
	s_waitcnt lgkmcnt(0)
	v_mfma_f32_16x16x32_bf16 v[140:143], v[2:5], v[62:65], 0
	v_mfma_f32_16x16x32_bf16 v[154:157], v[2:5], v[94:97], 0
	v_mfma_f32_16x16x32_bf16 v[162:165], v[2:5], v[110:113], 0
	v_mfma_f32_16x16x32_bf16 v[2:5], v[2:5], v[122:125], 0
	v_mfma_f32_16x16x32_bf16 v[140:143], v[6:9], v[90:93], v[140:143]
	v_mfma_f32_16x16x32_bf16 v[154:157], v[6:9], v[106:109], v[154:157]
	v_mfma_f32_16x16x32_bf16 v[162:165], v[6:9], v[118:121], v[162:165]
	v_mfma_f32_16x16x32_bf16 v[2:5], v[6:9], v[126:129], v[2:5]
	v_mfma_f32_16x16x32_bf16 v[6:9], v[10:13], v[122:125], 0
	v_mfma_f32_16x16x32_bf16 v[150:153], v[10:13], v[62:65], 0
	v_mfma_f32_16x16x32_bf16 v[158:161], v[10:13], v[94:97], 0
	v_mfma_f32_16x16x32_bf16 v[166:169], v[10:13], v[110:113], 0
	v_mfma_f32_16x16x32_bf16 v[6:9], v[14:17], v[126:129], v[6:9]
	v_mfma_f32_16x16x32_bf16 v[150:153], v[14:17], v[90:93], v[150:153]
	v_mfma_f32_16x16x32_bf16 v[158:161], v[14:17], v[106:109], v[158:161]
	v_mfma_f32_16x16x32_bf16 v[166:169], v[14:17], v[118:121], v[166:169]
	v_mfma_f32_16x16x32_bf16 v[10:13], v[18:21], v[62:65], 0
	v_mfma_f32_16x16x32_bf16 v[170:173], v[22:25], v[90:93], v[10:13]
	v_mfma_f32_16x16x32_bf16 v[10:13], v[26:29], v[62:65], 0
	v_mfma_f32_16x16x32_bf16 v[174:177], v[30:33], v[90:93], v[10:13]
	v_mfma_f32_16x16x32_bf16 v[10:13], v[18:21], v[94:97], 0
	v_mfma_f32_16x16x32_bf16 v[178:181], v[22:25], v[106:109], v[10:13]
	v_mfma_f32_16x16x32_bf16 v[10:13], v[26:29], v[94:97], 0
	v_mfma_f32_16x16x32_bf16 v[182:185], v[30:33], v[106:109], v[10:13]
	v_mfma_f32_16x16x32_bf16 v[10:13], v[18:21], v[110:113], 0
	v_mfma_f32_16x16x32_bf16 v[186:189], v[22:25], v[118:121], v[10:13]
	v_mfma_f32_16x16x32_bf16 v[10:13], v[26:29], v[110:113], 0
	v_mfma_f32_16x16x32_bf16 v[190:193], v[30:33], v[118:121], v[10:13]
	v_mfma_f32_16x16x32_bf16 v[10:13], v[18:21], v[122:125], 0
	v_mfma_f32_16x16x32_bf16 v[194:197], v[22:25], v[126:129], v[10:13]
	v_mfma_f32_16x16x32_bf16 v[10:13], v[26:29], v[122:125], 0
	v_mfma_f32_16x16x32_bf16 v[198:201], v[30:33], v[126:129], v[10:13]
	s_barrier
; #define PG8_WAIT_V(n) asm volatile("s_waitcnt vmcnt(" #n ")" ::: "memory")
; template <class Epi, class Sched, bool ALIGN_EPI = true, bool SP2 = true, bool FULLLINE = false, bool NOSTAGE = false, bool FP8 = false>
; __device__ __forceinline__ void gemm_phase(PG8_LAS unsigned char* lds, const Gemm g, const Sched& S, const Epi& E) {
;     ...
;         static_assert(SP2, "only the SP2 loop is kept");
;         { const int t = 0; if constexpr (Epi::NST == 16) PG8_ITER(PG8_WAIT_V(24)); else if constexpr (Epi::NST == 8) PG8_ITER(PG8_WAIT_V(16)); else PG8_ITER(PG8_WAIT_V(8)); }
;         for (int t = 2; t < nt; t += 2) PG8_ITER(PG8_WAIT_V(8));
	s_nop 5
	ds_read_b128 v[10:13], v147
	ds_read_b128 v[14:17], v147 offset:1024
	ds_read_b128 v[18:21], v147 offset:2048
	ds_read_b128 v[22:25], v147 offset:3072
	ds_read_b128 v[202:205], v148
	ds_read_b128 v[206:209], v148 offset:1024
	ds_read_b128 v[210:213], v148 offset:2048
	ds_read_b128 v[214:217], v148 offset:3072
	s_mov_b32 m0, s53
	v_lshl_add_u64 v[90:91], v[242:243], 0, s[24:25]
	ds_read_b128 v[26:29], v146 offset:32768
	ds_read_b128 v[30:33], v146 offset:33792
	ds_read_b128 v[62:65], v146 offset:34816
	ds_read_b128 v[218:221], v146 offset:35840
	ds_read_b128 v[222:225], v146 offset:36864
	ds_read_b128 v[226:229], v146 offset:37888
	ds_read_b128 v[230:233], v146 offset:38912
	ds_read_b128 v[234:237], v146 offset:39936
	global_load_lds_dwordx4 v[90:91], off
	v_lshl_add_u64 v[90:91], v[242:243], 0, s[26:27]
	s_mov_b32 m0, s54
	s_nop 0
	global_load_lds_dwordx4 v[90:91], off
	s_waitcnt vmcnt(8)
	s_waitcnt lgkmcnt(0)
	s_barrier
	s_waitcnt lgkmcnt(0)
	v_mfma_f32_16x16x32_bf16 v[66:69], v[10:13], v[26:29], v[66:69]
	v_mfma_f32_16x16x32_bf16 v[126:129], v[14:17], v[30:33], v[66:69]
	v_mfma_f32_16x16x32_bf16 v[66:69], v[18:21], v[26:29], v[70:73]
	v_mfma_f32_16x16x32_bf16 v[122:125], v[22:25], v[30:33], v[66:69]
	v_mfma_f32_16x16x32_bf16 v[66:69], v[10:13], v[62:65], v[74:77]
	v_mfma_f32_16x16x32_bf16 v[110:113], v[14:17], v[218:221], v[66:69]
	v_mfma_f32_16x16x32_bf16 v[66:69], v[18:21], v[62:65], v[78:81]
	v_mfma_f32_16x16x32_bf16 v[106:109], v[22:25], v[218:221], v[66:69]
	v_mfma_f32_16x16x32_bf16 v[66:69], v[10:13], v[222:225], v[82:85]
	v_mfma_f32_16x16x32_bf16 v[94:97], v[14:17], v[226:229], v[66:69]
	v_mfma_f32_16x16x32_bf16 v[66:69], v[18:21], v[222:225], v[86:89]
	v_mfma_f32_16x16x32_bf16 v[90:93], v[22:25], v[226:229], v[66:69]
	v_mfma_f32_16x16x32_bf16 v[66:69], v[10:13], v[230:233], v[98:101]
	v_mfma_f32_16x16x32_bf16 v[78:81], v[14:17], v[234:237], v[66:69]
	v_mfma_f32_16x16x32_bf16 v[66:69], v[18:21], v[230:233], v[102:105]
	v_mfma_f32_16x16x32_bf16 v[74:77], v[22:25], v[234:237], v[66:69]
	v_mfma_f32_16x16x32_bf16 v[66:69], v[202:205], v[26:29], v[114:117]
	v_mfma_f32_16x16x32_bf16 v[26:29], v[210:213], v[26:29], v[34:37]
	v_mfma_f32_16x16x32_bf16 v[114:117], v[214:217], v[30:33], v[26:29]
	v_mfma_f32_16x16x32_bf16 v[26:29], v[202:205], v[62:65], v[38:41]
	v_mfma_f32_16x16x32_bf16 v[102:105], v[206:209], v[218:221], v[26:29]
	v_mfma_f32_16x16x32_bf16 v[26:29], v[210:213], v[62:65], v[42:45]
	v_mfma_f32_16x16x32_bf16 v[98:101], v[214:217], v[218:221], v[26:29]
	v_mfma_f32_16x16x32_bf16 v[26:29], v[202:205], v[222:225], v[46:49]
	v_mfma_f32_16x16x32_bf16 v[86:89], v[206:209], v[226:229], v[26:29]
	v_mfma_f32_16x16x32_bf16 v[26:29], v[210:213], v[222:225], v[50:53]
	v_mfma_f32_16x16x32_bf16 v[82:85], v[214:217], v[226:229], v[26:29]
	v_mfma_f32_16x16x32_bf16 v[26:29], v[202:205], v[230:233], v[54:57]
	v_mfma_f32_16x16x32_bf16 v[70:73], v[206:209], v[234:237], v[26:29]
	v_mfma_f32_16x16x32_bf16 v[26:29], v[210:213], v[230:233], v[58:61]
	v_mfma_f32_16x16x32_bf16 v[118:121], v[206:209], v[30:33], v[66:69]
	v_mfma_f32_16x16x32_bf16 v[66:69], v[214:217], v[234:237], v[26:29]
	s_barrier
	s_add_i32 s50, s3, s46
	s_nop 3
	v_lshl_add_u64 v[26:27], v[244:245], 0, s[28:29]
	s_mov_b32 m0, s50
	s_add_i32 s51, s50, 0x2000
	ds_read_b128 v[34:37], v146 offset:49152
	ds_read_b128 v[38:41], v146 offset:50176
	ds_read_b128 v[218:221], v146 offset:51200
	ds_read_b128 v[222:225], v146 offset:52224
	ds_read_b128 v[226:229], v146 offset:53248
	ds_read_b128 v[230:233], v146 offset:54272
	ds_read_b128 v[234:237], v146 offset:55296
	ds_read_b128 v[238:241], v146 offset:56320
	global_load_lds_dwordx4 v[26:27], off
	v_lshl_add_u64 v[26:27], v[244:245], 0, s[30:31]
	s_mov_b32 m0, s51
	s_mov_b64 s[0:1], 0x80180
	s_add_i32 s33, s42, s46
	global_load_lds_dwordx4 v[26:27], off
	v_lshl_add_u64 v[26:27], v[244:245], 0, s[0:1]
	s_mov_b32 m0, s33
	s_mov_b64 s[0:1], 0xc0180
	s_add_i32 s56, s33, 0x2000
	global_load_lds_dwordx4 v[26:27], off
	v_lshl_add_u64 v[26:27], v[244:245], 0, s[0:1]
	s_mov_b32 m0, s56
	s_nop 0
	global_load_lds_dwordx4 v[26:27], off
	v_lshl_add_u64 v[26:27], v[242:243], 0, s[28:29]
	s_mov_b32 m0, s55
	s_nop 0
	global_load_lds_dwordx4 v[26:27], off
	v_lshl_add_u64 v[26:27], v[242:243], 0, s[30:31]
	s_mov_b32 m0, s62
	s_nop 0
	global_load_lds_dwordx4 v[26:27], off
	s_waitcnt vmcnt(8)
	s_waitcnt lgkmcnt(0)
	s_barrier
	s_waitcnt lgkmcnt(0)
	v_mfma_f32_16x16x32_bf16 v[26:29], v[10:13], v[34:37], v[140:143]
	v_mfma_f32_16x16x32_bf16 v[62:65], v[14:17], v[38:41], v[26:29]
	v_mfma_f32_16x16x32_bf16 v[26:29], v[18:21], v[34:37], v[150:153]
	v_mfma_f32_16x16x32_bf16 v[58:61], v[22:25], v[38:41], v[26:29]
	v_mfma_f32_16x16x32_bf16 v[26:29], v[10:13], v[218:221], v[154:157]
	v_mfma_f32_16x16x32_bf16 v[46:49], v[14:17], v[222:225], v[26:29]
	v_mfma_f32_16x16x32_bf16 v[26:29], v[18:21], v[218:221], v[158:161]
	v_mfma_f32_16x16x32_bf16 v[42:45], v[22:25], v[222:225], v[26:29]
	v_mfma_f32_16x16x32_bf16 v[26:29], v[10:13], v[226:229], v[162:165]
	v_mfma_f32_16x16x32_bf16 v[2:5], v[10:13], v[234:237], v[2:5]
	v_mfma_f32_16x16x32_bf16 v[30:33], v[14:17], v[230:233], v[26:29]
	v_mfma_f32_16x16x32_bf16 v[26:29], v[18:21], v[226:229], v[166:169]
	v_mfma_f32_16x16x32_bf16 v[14:17], v[14:17], v[238:241], v[2:5]
	v_mfma_f32_16x16x32_bf16 v[2:5], v[18:21], v[234:237], v[6:9]
	v_mfma_f32_16x16x32_bf16 v[26:29], v[22:25], v[230:233], v[26:29]
	v_mfma_f32_16x16x32_bf16 v[10:13], v[22:25], v[238:241], v[2:5]
	v_mfma_f32_16x16x32_bf16 v[2:5], v[202:205], v[34:37], v[170:173]
	v_mfma_f32_16x16x32_bf16 v[54:57], v[206:209], v[38:41], v[2:5]
	v_mfma_f32_16x16x32_bf16 v[2:5], v[210:213], v[34:37], v[174:177]
	v_mfma_f32_16x16x32_bf16 v[50:53], v[214:217], v[38:41], v[2:5]
	v_mfma_f32_16x16x32_bf16 v[2:5], v[202:205], v[218:221], v[178:181]
	v_mfma_f32_16x16x32_bf16 v[38:41], v[206:209], v[222:225], v[2:5]
	v_mfma_f32_16x16x32_bf16 v[2:5], v[210:213], v[218:221], v[182:185]
	v_mfma_f32_16x16x32_bf16 v[34:37], v[214:217], v[222:225], v[2:5]
	v_mfma_f32_16x16x32_bf16 v[2:5], v[202:205], v[226:229], v[186:189]
	v_mfma_f32_16x16x32_bf16 v[22:25], v[206:209], v[230:233], v[2:5]
	v_mfma_f32_16x16x32_bf16 v[2:5], v[210:213], v[226:229], v[190:193]
	v_mfma_f32_16x16x32_bf16 v[18:21], v[214:217], v[230:233], v[2:5]
	v_mfma_f32_16x16x32_bf16 v[2:5], v[202:205], v[234:237], v[194:197]
	v_mfma_f32_16x16x32_bf16 v[6:9], v[206:209], v[238:241], v[2:5]
	v_mfma_f32_16x16x32_bf16 v[2:5], v[210:213], v[234:237], v[198:201]
	v_mfma_f32_16x16x32_bf16 v[2:5], v[214:217], v[238:241], v[2:5]
	s_barrier
	s_add_u32 s78, s78, 0x80180
	s_addc_u32 s79, s79, 0
	s_add_u32 s57, s76, 0x200
	s_addc_u32 s76, s77, 0
	s_mov_b32 s77, 0
	.p2align 6

; template <class Epi, class Sched, bool ALIGN_EPI = true, bool SP2 = true, bool FULLLINE = false, bool NOSTAGE = false, bool FP8 = false>
; __device__ __forceinline__ void gemm_phase(PG8_LAS unsigned char* lds, const Gemm g, const Sched& S, const Epi& E) {
;     ...
;         const bool has_next = S.next(ui + 1, nxt);
;         const char* nA = has_next ? PG8_ABASE(nxt) : cA; const char* nB = has_next ? PG8_BBASE(nxt) : cB;
.LBB0_2096:
	s_ashr_i32 s67, s66, 31
	ds_read_b128 v[2:5], v1
	ds_read_b128 v[6:9], v1 offset:1024
	ds_read_b128 v[10:13], v1 offset:2048
	ds_read_b128 v[14:17], v1 offset:3072
	ds_read_b128 v[18:21], v192
	ds_read_b128 v[22:25], v192 offset:1024
	ds_read_b128 v[26:29], v192 offset:2048
	ds_read_b128 v[30:33], v192 offset:3072
	s_lshl_b64 s[0:1], s[66:67], 20
	s_add_u32 s68, s42, s0
	s_addc_u32 s69, s43, s1
	s_and_b64 s[0:1], s[8:9], exec
	s_cselect_b32 s67, s69, s75
	s_cselect_b32 s90, s68, s74
	s_ashr_i32 s41, s40, 31
	s_lshl_b64 s[0:1], s[40:41], 20
	s_add_u32 s70, s44, s0
	s_addc_u32 s71, s45, s1
	s_and_b64 s[0:1], s[8:9], exec
	s_cselect_b32 s41, s71, s77
	s_cselect_b32 s91, s70, s76
	v_lshl_add_u64 v[248:249], s[74:75], 0, v[170:171]
	s_mov_b32 m0, s85
	v_lshl_add_u64 v[66:67], v[248:249], 0, s[12:13]
	ds_read_b128 v[34:37], v193
	ds_read_b128 v[38:41], v193 offset:1024
	ds_read_b128 v[42:45], v193 offset:2048
	ds_read_b128 v[46:49], v193 offset:3072
	ds_read_b128 v[50:53], v193 offset:4096
	ds_read_b128 v[54:57], v193 offset:5120
	ds_read_b128 v[58:61], v193 offset:6144
	ds_read_b128 v[62:65], v193 offset:7168
	global_load_lds_dwordx4 v[66:67], off
	v_lshl_add_u64 v[66:67], v[248:249], 0, s[14:15]
	s_mov_b32 m0, s87
	s_nop 0
	global_load_lds_dwordx4 v[66:67], off
	s_waitcnt vmcnt(24)
	s_waitcnt lgkmcnt(0)
	s_barrier
	s_waitcnt lgkmcnt(0)
	v_mfma_f32_16x16x32_bf16 v[66:69], v[2:5], v[34:37], 0
	v_mfma_f32_16x16x32_bf16 v[70:73], v[10:13], v[34:37], 0
	v_mfma_f32_16x16x32_bf16 v[78:81], v[10:13], v[42:45], 0
	v_mfma_f32_16x16x32_bf16 v[86:89], v[10:13], v[50:53], 0
	v_mfma_f32_16x16x32_bf16 v[66:69], v[6:9], v[38:41], v[66:69]
	v_mfma_f32_16x16x32_bf16 v[70:73], v[14:17], v[38:41], v[70:73]
	v_mfma_f32_16x16x32_bf16 v[74:77], v[2:5], v[42:45], 0
	v_mfma_f32_16x16x32_bf16 v[78:81], v[14:17], v[46:49], v[78:81]
	v_mfma_f32_16x16x32_bf16 v[82:85], v[2:5], v[50:53], 0
	v_mfma_f32_16x16x32_bf16 v[86:89], v[14:17], v[54:57], v[86:89]
	v_mfma_f32_16x16x32_bf16 v[90:93], v[2:5], v[58:61], 0
	v_mfma_f32_16x16x32_bf16 v[94:97], v[10:13], v[58:61], 0
	v_mfma_f32_16x16x32_bf16 v[74:77], v[6:9], v[46:49], v[74:77]
	v_mfma_f32_16x16x32_bf16 v[82:85], v[6:9], v[54:57], v[82:85]
	v_mfma_f32_16x16x32_bf16 v[90:93], v[6:9], v[62:65], v[90:93]
	v_mfma_f32_16x16x32_bf16 v[94:97], v[14:17], v[62:65], v[94:97]
	v_mfma_f32_16x16x32_bf16 v[98:101], v[18:21], v[34:37], 0
	v_mfma_f32_16x16x32_bf16 v[34:37], v[26:29], v[34:37], 0
	v_mfma_f32_16x16x32_bf16 v[98:101], v[22:25], v[38:41], v[98:101]
	v_mfma_f32_16x16x32_bf16 v[34:37], v[30:33], v[38:41], v[34:37]
	v_mfma_f32_16x16x32_bf16 v[38:41], v[18:21], v[42:45], 0
	v_mfma_f32_16x16x32_bf16 v[42:45], v[26:29], v[42:45], 0
	v_mfma_f32_16x16x32_bf16 v[38:41], v[22:25], v[46:49], v[38:41]
	v_mfma_f32_16x16x32_bf16 v[42:45], v[30:33], v[46:49], v[42:45]
	v_mfma_f32_16x16x32_bf16 v[46:49], v[18:21], v[50:53], 0
	v_mfma_f32_16x16x32_bf16 v[50:53], v[26:29], v[50:53], 0
	v_mfma_f32_16x16x32_bf16 v[46:49], v[22:25], v[54:57], v[46:49]
	v_mfma_f32_16x16x32_bf16 v[50:53], v[30:33], v[54:57], v[50:53]
	v_mfma_f32_16x16x32_bf16 v[54:57], v[18:21], v[58:61], 0
	v_mfma_f32_16x16x32_bf16 v[58:61], v[26:29], v[58:61], 0
	v_mfma_f32_16x16x32_bf16 v[54:57], v[22:25], v[62:65], v[54:57]
	v_mfma_f32_16x16x32_bf16 v[58:61], v[30:33], v[62:65], v[58:61]
	s_barrier
	v_lshl_add_u64 v[250:251], s[76:77], 0, v[172:173]
	s_add_i32 s92, s83, s46
	v_lshl_add_u64 v[130:131], v[250:251], 0, s[16:17]
	s_mov_b32 m0, s92
	s_add_i32 s93, s92, 0x2000
	ds_read_b128 v[62:65], v193 offset:16384
	ds_read_b128 v[102:105], v193 offset:17408
	ds_read_b128 v[106:109], v193 offset:18432
	ds_read_b128 v[110:113], v193 offset:19456
	ds_read_b128 v[114:117], v193 offset:20480
	ds_read_b128 v[118:121], v193 offset:21504
	ds_read_b128 v[122:125], v193 offset:22528
	ds_read_b128 v[126:129], v193 offset:23552
	global_load_lds_dwordx4 v[130:131], off
	v_lshl_add_u64 v[130:131], v[250:251], 0, s[18:19]
	s_mov_b32 m0, s93
	s_add_i32 s94, s84, s46
	global_load_lds_dwordx4 v[130:131], off
	v_lshl_add_u64 v[130:131], v[250:251], 0, s[20:21]
	s_mov_b32 m0, s94
	s_add_i32 s95, s94, 0x2000
	global_load_lds_dwordx4 v[130:131], off
	v_lshl_add_u64 v[130:131], v[250:251], 0, s[22:23]
	s_mov_b32 m0, s95
	s_nop 0
	global_load_lds_dwordx4 v[130:131], off
	v_lshl_add_u64 v[130:131], v[248:249], 0, s[16:17]
	s_mov_b32 m0, s47
	s_nop 0
	global_load_lds_dwordx4 v[130:131], off
	v_lshl_add_u64 v[130:131], v[248:249], 0, s[18:19]
	s_mov_b32 m0, s52
	s_nop 0
	global_load_lds_dwordx4 v[130:131], off
	s_waitcnt vmcnt(24)
	s_waitcnt lgkmcnt(0)
	s_barrier
	s_waitcnt lgkmcnt(0)
	v_mfma_f32_16x16x32_bf16 v[130:133], v[2:5], v[62:65], 0
	v_mfma_f32_16x16x32_bf16 v[138:141], v[6:9], v[102:105], v[130:133]
	v_mfma_f32_16x16x32_bf16 v[130:133], v[10:13], v[62:65], 0
	v_mfma_f32_16x16x32_bf16 v[150:153], v[14:17], v[102:105], v[130:133]
	v_mfma_f32_16x16x32_bf16 v[130:133], v[2:5], v[106:109], 0
	v_mfma_f32_16x16x32_bf16 v[154:157], v[6:9], v[110:113], v[130:133]
	v_mfma_f32_16x16x32_bf16 v[130:133], v[10:13], v[106:109], 0
	v_mfma_f32_16x16x32_bf16 v[158:161], v[14:17], v[110:113], v[130:133]
	v_mfma_f32_16x16x32_bf16 v[130:133], v[2:5], v[114:117], 0
	v_mfma_f32_16x16x32_bf16 v[2:5], v[2:5], v[122:125], 0
	v_mfma_f32_16x16x32_bf16 v[162:165], v[6:9], v[118:121], v[130:133]
	v_mfma_f32_16x16x32_bf16 v[2:5], v[6:9], v[126:129], v[2:5]
	v_mfma_f32_16x16x32_bf16 v[6:9], v[10:13], v[122:125], 0
	v_mfma_f32_16x16x32_bf16 v[130:133], v[10:13], v[114:117], 0
	v_mfma_f32_16x16x32_bf16 v[6:9], v[14:17], v[126:129], v[6:9]
	v_mfma_f32_16x16x32_bf16 v[166:169], v[14:17], v[118:121], v[130:133]
	v_mfma_f32_16x16x32_bf16 v[10:13], v[18:21], v[62:65], 0
	v_mfma_f32_16x16x32_bf16 v[180:183], v[22:25], v[102:105], v[10:13]
	v_mfma_f32_16x16x32_bf16 v[10:13], v[26:29], v[62:65], 0
	v_mfma_f32_16x16x32_bf16 v[184:187], v[30:33], v[102:105], v[10:13]
	v_mfma_f32_16x16x32_bf16 v[10:13], v[18:21], v[106:109], 0
	v_mfma_f32_16x16x32_bf16 v[188:191], v[22:25], v[110:113], v[10:13]
	v_mfma_f32_16x16x32_bf16 v[10:13], v[26:29], v[106:109], 0
	v_mfma_f32_16x16x32_bf16 v[196:199], v[30:33], v[110:113], v[10:13]
	v_mfma_f32_16x16x32_bf16 v[10:13], v[18:21], v[114:117], 0
	v_mfma_f32_16x16x32_bf16 v[200:203], v[22:25], v[118:121], v[10:13]
	v_mfma_f32_16x16x32_bf16 v[10:13], v[26:29], v[114:117], 0
	v_mfma_f32_16x16x32_bf16 v[204:207], v[30:33], v[118:121], v[10:13]
	v_mfma_f32_16x16x32_bf16 v[10:13], v[18:21], v[122:125], 0
	v_mfma_f32_16x16x32_bf16 v[208:211], v[22:25], v[126:129], v[10:13]
	v_mfma_f32_16x16x32_bf16 v[10:13], v[26:29], v[122:125], 0
	v_mfma_f32_16x16x32_bf16 v[212:215], v[30:33], v[126:129], v[10:13]
	s_barrier
; #define PG8_WAIT_V(n) asm volatile("s_waitcnt vmcnt(" #n ")" ::: "memory")
; template <class Epi, class Sched, bool ALIGN_EPI = true, bool SP2 = true, bool FULLLINE = false, bool NOSTAGE = false, bool FP8 = false>
; __device__ __forceinline__ void gemm_phase(PG8_LAS unsigned char* lds, const Gemm g, const Sched& S, const Epi& E) {
;     ...
;         static_assert(SP2, "only the SP2 loop is kept");
;         { const int t = 0; if constexpr (Epi::NST == 16) PG8_ITER(PG8_WAIT_V(24)); else if constexpr (Epi::NST == 8) PG8_ITER(PG8_WAIT_V(16)); else PG8_ITER(PG8_WAIT_V(8)); }
;         for (int t = 2; t < nt; t += 2) PG8_ITER(PG8_WAIT_V(8));
	s_nop 5
	ds_read_b128 v[10:13], v194
	ds_read_b128 v[14:17], v194 offset:1024
	ds_read_b128 v[18:21], v194 offset:2048
	ds_read_b128 v[22:25], v194 offset:3072
	ds_read_b128 v[216:219], v195
	ds_read_b128 v[220:223], v195 offset:1024
	ds_read_b128 v[224:227], v195 offset:2048
	ds_read_b128 v[228:231], v195 offset:3072
	s_mov_b32 m0, s53
	v_lshl_add_u64 v[106:107], v[248:249], 0, s[20:21]
	ds_read_b128 v[26:29], v193 offset:32768
	ds_read_b128 v[30:33], v193 offset:33792
	ds_read_b128 v[62:65], v193 offset:34816
	ds_read_b128 v[102:105], v193 offset:35840
	ds_read_b128 v[232:235], v193 offset:36864
	ds_read_b128 v[236:239], v193 offset:37888
	ds_read_b128 v[240:243], v193 offset:38912
	ds_read_b128 v[244:247], v193 offset:39936
	global_load_lds_dwordx4 v[106:107], off
	v_lshl_add_u64 v[106:107], v[248:249], 0, s[22:23]
	s_mov_b32 m0, s54
	s_nop 0
	global_load_lds_dwordx4 v[106:107], off
	s_waitcnt vmcnt(8)
	s_waitcnt lgkmcnt(0)
	s_barrier
	s_waitcnt lgkmcnt(0)
	v_mfma_f32_16x16x32_bf16 v[66:69], v[10:13], v[26:29], v[66:69]
	v_mfma_f32_16x16x32_bf16 v[146:149], v[14:17], v[30:33], v[66:69]
	v_mfma_f32_16x16x32_bf16 v[66:69], v[18:21], v[26:29], v[70:73]
	v_mfma_f32_16x16x32_bf16 v[142:145], v[22:25], v[30:33], v[66:69]
	v_mfma_f32_16x16x32_bf16 v[66:69], v[10:13], v[62:65], v[74:77]
	v_mfma_f32_16x16x32_bf16 v[126:129], v[14:17], v[102:105], v[66:69]
	v_mfma_f32_16x16x32_bf16 v[66:69], v[18:21], v[62:65], v[78:81]
	v_mfma_f32_16x16x32_bf16 v[122:125], v[22:25], v[102:105], v[66:69]
	v_mfma_f32_16x16x32_bf16 v[66:69], v[10:13], v[232:235], v[82:85]
	v_mfma_f32_16x16x32_bf16 v[110:113], v[14:17], v[236:239], v[66:69]
	v_mfma_f32_16x16x32_bf16 v[66:69], v[18:21], v[232:235], v[86:89]
	v_mfma_f32_16x16x32_bf16 v[106:109], v[22:25], v[236:239], v[66:69]
	v_mfma_f32_16x16x32_bf16 v[66:69], v[10:13], v[240:243], v[90:93]
	v_mfma_f32_16x16x32_bf16 v[86:89], v[14:17], v[244:247], v[66:69]
	v_mfma_f32_16x16x32_bf16 v[66:69], v[18:21], v[240:243], v[94:97]
	v_mfma_f32_16x16x32_bf16 v[78:81], v[22:25], v[244:247], v[66:69]
	v_mfma_f32_16x16x32_bf16 v[66:69], v[216:219], v[26:29], v[98:101]
	v_mfma_f32_16x16x32_bf16 v[26:29], v[224:227], v[26:29], v[34:37]
	v_mfma_f32_16x16x32_bf16 v[130:133], v[228:231], v[30:33], v[26:29]
	v_mfma_f32_16x16x32_bf16 v[26:29], v[216:219], v[62:65], v[38:41]
	v_mfma_f32_16x16x32_bf16 v[118:121], v[220:223], v[102:105], v[26:29]
	v_mfma_f32_16x16x32_bf16 v[26:29], v[224:227], v[62:65], v[42:45]
	v_mfma_f32_16x16x32_bf16 v[114:117], v[228:231], v[102:105], v[26:29]
	v_mfma_f32_16x16x32_bf16 v[26:29], v[216:219], v[232:235], v[46:49]
	v_mfma_f32_16x16x32_bf16 v[102:105], v[220:223], v[236:239], v[26:29]
	v_mfma_f32_16x16x32_bf16 v[26:29], v[224:227], v[232:235], v[50:53]
	v_mfma_f32_16x16x32_bf16 v[98:101], v[228:231], v[236:239], v[26:29]
	v_mfma_f32_16x16x32_bf16 v[26:29], v[216:219], v[240:243], v[54:57]
	v_mfma_f32_16x16x32_bf16 v[70:73], v[220:223], v[244:247], v[26:29]
	v_mfma_f32_16x16x32_bf16 v[26:29], v[224:227], v[240:243], v[58:61]
	v_mfma_f32_16x16x32_bf16 v[134:137], v[220:223], v[30:33], v[66:69]
	v_mfma_f32_16x16x32_bf16 v[66:69], v[228:231], v[244:247], v[26:29]
	s_barrier
	s_add_i32 s50, s88, s46
	s_nop 3
	v_lshl_add_u64 v[26:27], v[250:251], 0, s[24:25]
	s_mov_b32 m0, s50
	s_add_i32 s51, s50, 0x2000
	ds_read_b128 v[34:37], v193 offset:49152
	ds_read_b128 v[38:41], v193 offset:50176
	ds_read_b128 v[74:77], v193 offset:51200
	ds_read_b128 v[82:85], v193 offset:52224
	ds_read_b128 v[90:93], v193 offset:53248
	ds_read_b128 v[94:97], v193 offset:54272
	ds_read_b128 v[232:235], v193 offset:55296
	ds_read_b128 v[236:239], v193 offset:56320
	global_load_lds_dwordx4 v[26:27], off
	v_lshl_add_u64 v[26:27], v[250:251], 0, s[26:27]
	s_mov_b32 m0, s51
	s_mov_b64 s[0:1], 0x80180
	s_add_i32 s33, s89, s46
	global_load_lds_dwordx4 v[26:27], off
	v_lshl_add_u64 v[26:27], v[250:251], 0, s[0:1]
	s_mov_b32 m0, s33
	s_mov_b64 s[0:1], 0xc0180
	s_add_i32 s56, s33, 0x2000
	global_load_lds_dwordx4 v[26:27], off
	v_lshl_add_u64 v[26:27], v[250:251], 0, s[0:1]
	s_mov_b32 m0, s56
	s_nop 0
	global_load_lds_dwordx4 v[26:27], off
	v_lshl_add_u64 v[26:27], v[248:249], 0, s[24:25]
	s_mov_b32 m0, s55
	s_nop 0
	global_load_lds_dwordx4 v[26:27], off
	v_lshl_add_u64 v[26:27], v[248:249], 0, s[26:27]
	s_mov_b32 m0, s62
	s_nop 0
	global_load_lds_dwordx4 v[26:27], off
	s_waitcnt vmcnt(8)
	s_waitcnt lgkmcnt(0)
	s_barrier
	s_waitcnt lgkmcnt(0)
	v_mfma_f32_16x16x32_bf16 v[26:29], v[10:13], v[34:37], v[138:141]
	v_mfma_f32_16x16x32_bf16 v[62:65], v[14:17], v[38:41], v[26:29]
	v_mfma_f32_16x16x32_bf16 v[26:29], v[18:21], v[34:37], v[150:153]
	v_mfma_f32_16x16x32_bf16 v[58:61], v[22:25], v[38:41], v[26:29]
	v_mfma_f32_16x16x32_bf16 v[26:29], v[10:13], v[74:77], v[154:157]
	v_mfma_f32_16x16x32_bf16 v[46:49], v[14:17], v[82:85], v[26:29]
	v_mfma_f32_16x16x32_bf16 v[26:29], v[18:21], v[74:77], v[158:161]
	v_mfma_f32_16x16x32_bf16 v[42:45], v[22:25], v[82:85], v[26:29]
	v_mfma_f32_16x16x32_bf16 v[26:29], v[10:13], v[90:93], v[162:165]
	v_mfma_f32_16x16x32_bf16 v[2:5], v[10:13], v[232:235], v[2:5]
	v_mfma_f32_16x16x32_bf16 v[30:33], v[14:17], v[94:97], v[26:29]
	v_mfma_f32_16x16x32_bf16 v[26:29], v[18:21], v[90:93], v[166:169]
	v_mfma_f32_16x16x32_bf16 v[14:17], v[14:17], v[236:239], v[2:5]
	v_mfma_f32_16x16x32_bf16 v[2:5], v[18:21], v[232:235], v[6:9]
	v_mfma_f32_16x16x32_bf16 v[26:29], v[22:25], v[94:97], v[26:29]
	v_mfma_f32_16x16x32_bf16 v[10:13], v[22:25], v[236:239], v[2:5]
	v_mfma_f32_16x16x32_bf16 v[2:5], v[216:219], v[34:37], v[180:183]
	v_mfma_f32_16x16x32_bf16 v[54:57], v[220:223], v[38:41], v[2:5]
	v_mfma_f32_16x16x32_bf16 v[2:5], v[224:227], v[34:37], v[184:187]
	v_mfma_f32_16x16x32_bf16 v[50:53], v[228:231], v[38:41], v[2:5]
	v_mfma_f32_16x16x32_bf16 v[2:5], v[216:219], v[74:77], v[188:191]
	v_mfma_f32_16x16x32_bf16 v[38:41], v[220:223], v[82:85], v[2:5]
	v_mfma_f32_16x16x32_bf16 v[2:5], v[224:227], v[74:77], v[196:199]
	v_mfma_f32_16x16x32_bf16 v[34:37], v[228:231], v[82:85], v[2:5]
	v_mfma_f32_16x16x32_bf16 v[2:5], v[216:219], v[90:93], v[200:203]
	v_mfma_f32_16x16x32_bf16 v[22:25], v[220:223], v[94:97], v[2:5]
	v_mfma_f32_16x16x32_bf16 v[2:5], v[224:227], v[90:93], v[204:207]
	v_mfma_f32_16x16x32_bf16 v[18:21], v[228:231], v[94:97], v[2:5]
	v_mfma_f32_16x16x32_bf16 v[2:5], v[216:219], v[232:235], v[208:211]
	v_mfma_f32_16x16x32_bf16 v[6:9], v[220:223], v[236:239], v[2:5]
	v_mfma_f32_16x16x32_bf16 v[2:5], v[224:227], v[232:235], v[212:215]
	v_mfma_f32_16x16x32_bf16 v[2:5], v[228:231], v[236:239], v[2:5]
	s_barrier
	s_add_u32 s74, s74, 0x80180
	s_addc_u32 s75, s75, 0
	s_add_u32 s57, s76, 0x200
	s_addc_u32 s76, s77, 0
	s_mov_b32 s77, 0
	.p2align 6

; template <class Epi, class Sched, bool ALIGN_EPI = true, bool SP2 = true, bool FULLLINE = false, bool NOSTAGE = false, bool FP8 = false>
; __device__ __forceinline__ void gemm_phase(PG8_LAS unsigned char* lds, const Gemm g, const Sched& S, const Epi& E) {
;     ...
;         const bool has_next = S.next(ui + 1, nxt);
;         const char* nA = has_next ? PG8_ABASE(nxt) : cA; const char* nB = has_next ? PG8_BBASE(nxt) : cB;
.LBB0_2286:
	s_ashr_i32 s63, s62, 31
	s_lshl_b64 s[0:1], s[62:63], 20
	s_add_u32 s66, s58, s0
	ds_read_b128 v[2:5], v1
	ds_read_b128 v[6:9], v1 offset:1024
	ds_read_b128 v[10:13], v1 offset:2048
	ds_read_b128 v[14:17], v1 offset:3072
	ds_read_b128 v[18:21], v142
	ds_read_b128 v[22:25], v142 offset:1024
	ds_read_b128 v[26:29], v142 offset:2048
	ds_read_b128 v[30:33], v142 offset:3072
	s_addc_u32 s67, s59, s1
	s_ashr_i32 s41, s40, 31
	s_lshl_b64 s[0:1], s[40:41], 20
	s_add_u32 s68, s3, s0
	s_addc_u32 s69, s42, s1
	s_and_b64 s[0:1], s[8:9], exec
	s_cselect_b32 s41, s67, s75
	s_cselect_b32 s63, s66, s74
	s_cselect_b32 s87, s69, s73
	s_cselect_b32 s88, s68, s72
	v_lshl_add_u64 v[140:141], s[74:75], 0, v[132:133]
	s_mov_b32 m0, s79
	v_lshl_add_u64 v[66:67], v[140:141], 0, s[12:13]
	ds_read_b128 v[34:37], v143
	ds_read_b128 v[38:41], v143 offset:1024
	ds_read_b128 v[42:45], v143 offset:2048
	ds_read_b128 v[46:49], v143 offset:3072
	ds_read_b128 v[50:53], v143 offset:4096
	ds_read_b128 v[54:57], v143 offset:5120
	ds_read_b128 v[58:61], v143 offset:6144
	ds_read_b128 v[62:65], v143 offset:7168
	global_load_lds_dwordx4 v[66:67], off
	v_lshl_add_u64 v[66:67], v[140:141], 0, s[14:15]
	s_mov_b32 m0, s80
	s_nop 0
	global_load_lds_dwordx4 v[66:67], off
	s_waitcnt vmcnt(16)
	s_waitcnt lgkmcnt(0)
	s_barrier
	s_waitcnt lgkmcnt(0)
	v_mfma_f32_16x16x32_bf16 v[86:89], v[10:13], v[50:53], 0
	v_mfma_f32_16x16x32_bf16 v[90:93], v[14:17], v[54:57], v[86:89]
	v_mfma_f32_16x16x32_bf16 v[86:89], v[2:5], v[58:61], 0
	v_mfma_f32_16x16x32_bf16 v[66:69], v[2:5], v[34:37], 0
	v_mfma_f32_16x16x32_bf16 v[70:73], v[10:13], v[34:37], 0
	v_mfma_f32_16x16x32_bf16 v[74:77], v[2:5], v[42:45], 0
	v_mfma_f32_16x16x32_bf16 v[78:81], v[10:13], v[42:45], 0
	v_mfma_f32_16x16x32_bf16 v[82:85], v[2:5], v[50:53], 0
	v_mfma_f32_16x16x32_bf16 v[94:97], v[6:9], v[62:65], v[86:89]
	v_mfma_f32_16x16x32_bf16 v[86:89], v[10:13], v[58:61], 0
	v_mfma_f32_16x16x32_bf16 v[66:69], v[6:9], v[38:41], v[66:69]
	v_mfma_f32_16x16x32_bf16 v[70:73], v[14:17], v[38:41], v[70:73]
	v_mfma_f32_16x16x32_bf16 v[74:77], v[6:9], v[46:49], v[74:77]
	v_mfma_f32_16x16x32_bf16 v[78:81], v[14:17], v[46:49], v[78:81]
	v_mfma_f32_16x16x32_bf16 v[82:85], v[6:9], v[54:57], v[82:85]
	v_mfma_f32_16x16x32_bf16 v[106:109], v[14:17], v[62:65], v[86:89]
	v_mfma_f32_16x16x32_bf16 v[86:89], v[18:21], v[34:37], 0
	v_mfma_f32_16x16x32_bf16 v[34:37], v[26:29], v[34:37], 0
	v_mfma_f32_16x16x32_bf16 v[110:113], v[22:25], v[38:41], v[86:89]
	v_mfma_f32_16x16x32_bf16 v[34:37], v[30:33], v[38:41], v[34:37]
	v_mfma_f32_16x16x32_bf16 v[38:41], v[18:21], v[42:45], 0
	v_mfma_f32_16x16x32_bf16 v[42:45], v[26:29], v[42:45], 0
	v_mfma_f32_16x16x32_bf16 v[38:41], v[22:25], v[46:49], v[38:41]
	v_mfma_f32_16x16x32_bf16 v[42:45], v[30:33], v[46:49], v[42:45]
	v_mfma_f32_16x16x32_bf16 v[46:49], v[18:21], v[50:53], 0
	v_mfma_f32_16x16x32_bf16 v[50:53], v[26:29], v[50:53], 0
	v_mfma_f32_16x16x32_bf16 v[46:49], v[22:25], v[54:57], v[46:49]
	v_mfma_f32_16x16x32_bf16 v[50:53], v[30:33], v[54:57], v[50:53]
	v_mfma_f32_16x16x32_bf16 v[54:57], v[18:21], v[58:61], 0
	v_mfma_f32_16x16x32_bf16 v[58:61], v[26:29], v[58:61], 0
	v_mfma_f32_16x16x32_bf16 v[54:57], v[22:25], v[62:65], v[54:57]
	v_mfma_f32_16x16x32_bf16 v[58:61], v[30:33], v[62:65], v[58:61]
	s_barrier
	v_lshl_add_u64 v[238:239], s[72:73], 0, v[130:131]
	s_mov_b32 m0, s81
	v_lshl_add_u64 v[146:147], v[238:239], 0, s[16:17]
	s_add_i32 s89, s81, 0x2000
	ds_read_b128 v[62:65], v143 offset:16384
	ds_read_b128 v[86:89], v143 offset:17408
	ds_read_b128 v[98:101], v143 offset:18432
	ds_read_b128 v[102:105], v143 offset:19456
	ds_read_b128 v[114:117], v143 offset:20480
	ds_read_b128 v[118:121], v143 offset:21504
	ds_read_b128 v[122:125], v143 offset:22528
	ds_read_b128 v[126:129], v143 offset:23552
	global_load_lds_dwordx4 v[146:147], off
	v_lshl_add_u64 v[146:147], v[238:239], 0, s[18:19]
	s_mov_b32 m0, s89
	s_add_i32 s90, s78, s43
	global_load_lds_dwordx4 v[146:147], off
	v_lshl_add_u64 v[146:147], v[238:239], 0, s[20:21]
	s_mov_b32 m0, s90
	s_add_i32 s91, s90, 0x2000
	global_load_lds_dwordx4 v[146:147], off
	v_lshl_add_u64 v[146:147], v[238:239], 0, s[22:23]
	s_mov_b32 m0, s91
	s_nop 0
	global_load_lds_dwordx4 v[146:147], off
	v_lshl_add_u64 v[146:147], v[140:141], 0, s[16:17]
	s_mov_b32 m0, s45
	s_nop 0
	global_load_lds_dwordx4 v[146:147], off
	v_lshl_add_u64 v[146:147], v[140:141], 0, s[18:19]
	s_mov_b32 m0, s46
	s_nop 0
	global_load_lds_dwordx4 v[146:147], off
	s_waitcnt vmcnt(16)
	s_waitcnt lgkmcnt(0)
	s_barrier
	s_waitcnt lgkmcnt(0)
	v_mfma_f32_16x16x32_bf16 v[146:149], v[2:5], v[62:65], 0
	v_mfma_f32_16x16x32_bf16 v[154:157], v[2:5], v[98:101], 0
	v_mfma_f32_16x16x32_bf16 v[162:165], v[2:5], v[114:117], 0
	v_mfma_f32_16x16x32_bf16 v[2:5], v[2:5], v[122:125], 0
	v_mfma_f32_16x16x32_bf16 v[146:149], v[6:9], v[86:89], v[146:149]
	v_mfma_f32_16x16x32_bf16 v[154:157], v[6:9], v[102:105], v[154:157]
	v_mfma_f32_16x16x32_bf16 v[162:165], v[6:9], v[118:121], v[162:165]
	v_mfma_f32_16x16x32_bf16 v[2:5], v[6:9], v[126:129], v[2:5]
	v_mfma_f32_16x16x32_bf16 v[6:9], v[10:13], v[122:125], 0
	v_mfma_f32_16x16x32_bf16 v[150:153], v[10:13], v[62:65], 0
	v_mfma_f32_16x16x32_bf16 v[158:161], v[10:13], v[98:101], 0
	v_mfma_f32_16x16x32_bf16 v[166:169], v[10:13], v[114:117], 0
	v_mfma_f32_16x16x32_bf16 v[10:13], v[14:17], v[126:129], v[6:9]
	v_mfma_f32_16x16x32_bf16 v[150:153], v[14:17], v[86:89], v[150:153]
	v_mfma_f32_16x16x32_bf16 v[158:161], v[14:17], v[102:105], v[158:161]
	v_mfma_f32_16x16x32_bf16 v[166:169], v[14:17], v[118:121], v[166:169]
	v_mfma_f32_16x16x32_bf16 v[6:9], v[18:21], v[62:65], 0
	v_mfma_f32_16x16x32_bf16 v[14:17], v[22:25], v[86:89], v[6:9]
	v_mfma_f32_16x16x32_bf16 v[6:9], v[26:29], v[62:65], 0
	v_mfma_f32_16x16x32_bf16 v[170:173], v[30:33], v[86:89], v[6:9]
	v_mfma_f32_16x16x32_bf16 v[6:9], v[18:21], v[98:101], 0
	v_mfma_f32_16x16x32_bf16 v[174:177], v[22:25], v[102:105], v[6:9]
	v_mfma_f32_16x16x32_bf16 v[6:9], v[26:29], v[98:101], 0
	v_mfma_f32_16x16x32_bf16 v[178:181], v[30:33], v[102:105], v[6:9]
	v_mfma_f32_16x16x32_bf16 v[6:9], v[18:21], v[114:117], 0
	v_mfma_f32_16x16x32_bf16 v[182:185], v[22:25], v[118:121], v[6:9]
	v_mfma_f32_16x16x32_bf16 v[6:9], v[26:29], v[114:117], 0
	v_mfma_f32_16x16x32_bf16 v[186:189], v[30:33], v[118:121], v[6:9]
	v_mfma_f32_16x16x32_bf16 v[6:9], v[18:21], v[122:125], 0
	v_mfma_f32_16x16x32_bf16 v[190:193], v[22:25], v[126:129], v[6:9]
	v_mfma_f32_16x16x32_bf16 v[6:9], v[26:29], v[122:125], 0
	v_mfma_f32_16x16x32_bf16 v[194:197], v[30:33], v[126:129], v[6:9]
	s_barrier
; #define PG8_WAIT_V(n) asm volatile("s_waitcnt vmcnt(" #n ")" ::: "memory")
; template <class Epi, class Sched, bool ALIGN_EPI = true, bool SP2 = true, bool FULLLINE = false, bool NOSTAGE = false, bool FP8 = false>
; __device__ __forceinline__ void gemm_phase(PG8_LAS unsigned char* lds, const Gemm g, const Sched& S, const Epi& E) {
;     ...
;         static_assert(SP2, "only the SP2 loop is kept");
;         { const int t = 0; if constexpr (Epi::NST == 16) PG8_ITER(PG8_WAIT_V(24)); else if constexpr (Epi::NST == 8) PG8_ITER(PG8_WAIT_V(16)); else PG8_ITER(PG8_WAIT_V(8)); }
;         for (int t = 2; t < nt; t += 2) PG8_ITER(PG8_WAIT_V(8));
	s_nop 5
	ds_read_b128 v[6:9], v144
	ds_read_b128 v[26:29], v144 offset:1024
	ds_read_b128 v[30:33], v144 offset:2048
	ds_read_b128 v[62:65], v144 offset:3072
	ds_read_b128 v[198:201], v145
	ds_read_b128 v[202:205], v145 offset:1024
	ds_read_b128 v[206:209], v145 offset:2048
	ds_read_b128 v[210:213], v145 offset:3072
	s_mov_b32 m0, s47
	v_lshl_add_u64 v[86:87], v[140:141], 0, s[20:21]
	ds_read_b128 v[18:21], v143 offset:32768
	ds_read_b128 v[22:25], v143 offset:33792
	ds_read_b128 v[214:217], v143 offset:34816
	ds_read_b128 v[218:221], v143 offset:35840
	ds_read_b128 v[222:225], v143 offset:36864
	ds_read_b128 v[226:229], v143 offset:37888
	ds_read_b128 v[230:233], v143 offset:38912
	ds_read_b128 v[234:237], v143 offset:39936
	global_load_lds_dwordx4 v[86:87], off
	v_lshl_add_u64 v[86:87], v[140:141], 0, s[22:23]
	s_mov_b32 m0, s52
	s_nop 0
	global_load_lds_dwordx4 v[86:87], off
	s_waitcnt vmcnt(8)
	s_waitcnt lgkmcnt(0)
	s_barrier
	s_waitcnt lgkmcnt(0)
	v_mfma_f32_16x16x32_bf16 v[66:69], v[6:9], v[18:21], v[66:69]
	v_mfma_f32_16x16x32_bf16 v[118:121], v[26:29], v[22:25], v[66:69]
	v_mfma_f32_16x16x32_bf16 v[66:69], v[30:33], v[18:21], v[70:73]
	v_mfma_f32_16x16x32_bf16 v[114:117], v[62:65], v[22:25], v[66:69]
	v_mfma_f32_16x16x32_bf16 v[66:69], v[6:9], v[214:217], v[74:77]
	v_mfma_f32_16x16x32_bf16 v[102:105], v[26:29], v[218:221], v[66:69]
	v_mfma_f32_16x16x32_bf16 v[66:69], v[30:33], v[214:217], v[78:81]
	v_mfma_f32_16x16x32_bf16 v[98:101], v[62:65], v[218:221], v[66:69]
	v_mfma_f32_16x16x32_bf16 v[66:69], v[6:9], v[222:225], v[82:85]
	v_mfma_f32_16x16x32_bf16 v[86:89], v[26:29], v[226:229], v[66:69]
	v_mfma_f32_16x16x32_bf16 v[66:69], v[30:33], v[222:225], v[90:93]
	v_mfma_f32_16x16x32_bf16 v[82:85], v[62:65], v[226:229], v[66:69]
	v_mfma_f32_16x16x32_bf16 v[66:69], v[6:9], v[230:233], v[94:97]
	v_mfma_f32_16x16x32_bf16 v[70:73], v[26:29], v[234:237], v[66:69]
	v_mfma_f32_16x16x32_bf16 v[66:69], v[30:33], v[230:233], v[106:109]
	v_mfma_f32_16x16x32_bf16 v[66:69], v[62:65], v[234:237], v[66:69]
	v_mfma_f32_16x16x32_bf16 v[74:77], v[198:201], v[18:21], v[110:113]
	v_mfma_f32_16x16x32_bf16 v[18:21], v[206:209], v[18:21], v[34:37]
	v_mfma_f32_16x16x32_bf16 v[122:125], v[210:213], v[22:25], v[18:21]
	v_mfma_f32_16x16x32_bf16 v[18:21], v[198:201], v[214:217], v[38:41]
	v_mfma_f32_16x16x32_bf16 v[110:113], v[202:205], v[218:221], v[18:21]
	v_mfma_f32_16x16x32_bf16 v[18:21], v[206:209], v[214:217], v[42:45]
	v_mfma_f32_16x16x32_bf16 v[106:109], v[210:213], v[218:221], v[18:21]
	v_mfma_f32_16x16x32_bf16 v[18:21], v[198:201], v[222:225], v[46:49]
	v_mfma_f32_16x16x32_bf16 v[94:97], v[202:205], v[226:229], v[18:21]
	v_mfma_f32_16x16x32_bf16 v[18:21], v[206:209], v[222:225], v[50:53]
	v_mfma_f32_16x16x32_bf16 v[90:93], v[210:213], v[226:229], v[18:21]
	v_mfma_f32_16x16x32_bf16 v[18:21], v[198:201], v[230:233], v[54:57]
	v_mfma_f32_16x16x32_bf16 v[78:81], v[202:205], v[234:237], v[18:21]
	v_mfma_f32_16x16x32_bf16 v[18:21], v[206:209], v[230:233], v[58:61]
	v_mfma_f32_16x16x32_bf16 v[126:129], v[202:205], v[22:25], v[74:77]
	v_mfma_f32_16x16x32_bf16 v[74:77], v[210:213], v[234:237], v[18:21]
	s_barrier
	s_add_i32 s50, s82, s43
	s_nop 3
	v_lshl_add_u64 v[18:19], v[238:239], 0, s[24:25]
	s_mov_b32 m0, s50
	s_add_i32 s51, s50, 0x2000
	ds_read_b128 v[42:45], v143 offset:49152
	ds_read_b128 v[46:49], v143 offset:50176
	ds_read_b128 v[214:217], v143 offset:51200
	ds_read_b128 v[218:221], v143 offset:52224
	ds_read_b128 v[222:225], v143 offset:53248
	ds_read_b128 v[226:229], v143 offset:54272
	ds_read_b128 v[230:233], v143 offset:55296
	ds_read_b128 v[234:237], v143 offset:56320
	global_load_lds_dwordx4 v[18:19], off
	v_lshl_add_u64 v[18:19], v[238:239], 0, s[26:27]
	s_mov_b32 m0, s51
	s_mov_b64 s[0:1], 0x80180
	s_add_i32 s33, s83, s43
	global_load_lds_dwordx4 v[18:19], off
	v_lshl_add_u64 v[18:19], v[238:239], 0, s[0:1]
	s_mov_b32 m0, s33
	s_mov_b64 s[0:1], 0xc0180
	s_add_i32 s56, s33, 0x2000
	global_load_lds_dwordx4 v[18:19], off
	v_lshl_add_u64 v[18:19], v[238:239], 0, s[0:1]
	s_mov_b32 m0, s56
	s_nop 0
	global_load_lds_dwordx4 v[18:19], off
	v_lshl_add_u64 v[18:19], v[140:141], 0, s[24:25]
	s_mov_b32 m0, s53
	s_nop 0
	global_load_lds_dwordx4 v[18:19], off
	v_lshl_add_u64 v[18:19], v[140:141], 0, s[26:27]
	s_mov_b32 m0, s54
	s_nop 0
	global_load_lds_dwordx4 v[18:19], off
	s_waitcnt vmcnt(8)
	s_waitcnt lgkmcnt(0)
	s_barrier
	s_waitcnt lgkmcnt(0)
	v_mfma_f32_16x16x32_bf16 v[18:21], v[6:9], v[42:45], v[146:149]
	v_mfma_f32_16x16x32_bf16 v[54:57], v[26:29], v[46:49], v[18:21]
	v_mfma_f32_16x16x32_bf16 v[18:21], v[30:33], v[42:45], v[150:153]
	v_mfma_f32_16x16x32_bf16 v[50:53], v[62:65], v[46:49], v[18:21]
	v_mfma_f32_16x16x32_bf16 v[18:21], v[6:9], v[214:217], v[154:157]
	v_mfma_f32_16x16x32_bf16 v[38:41], v[26:29], v[218:221], v[18:21]
	v_mfma_f32_16x16x32_bf16 v[18:21], v[30:33], v[214:217], v[158:161]
	v_mfma_f32_16x16x32_bf16 v[34:37], v[62:65], v[218:221], v[18:21]
	v_mfma_f32_16x16x32_bf16 v[18:21], v[6:9], v[222:225], v[162:165]
	v_mfma_f32_16x16x32_bf16 v[2:5], v[6:9], v[230:233], v[2:5]
	v_mfma_f32_16x16x32_bf16 v[22:25], v[26:29], v[226:229], v[18:21]
	v_mfma_f32_16x16x32_bf16 v[18:21], v[30:33], v[222:225], v[166:169]
	v_mfma_f32_16x16x32_bf16 v[6:9], v[26:29], v[234:237], v[2:5]
	v_mfma_f32_16x16x32_bf16 v[2:5], v[30:33], v[230:233], v[10:13]
	v_mfma_f32_16x16x32_bf16 v[18:21], v[62:65], v[226:229], v[18:21]
	v_mfma_f32_16x16x32_bf16 v[2:5], v[62:65], v[234:237], v[2:5]
	v_mfma_f32_16x16x32_bf16 v[10:13], v[198:201], v[42:45], v[14:17]
	v_mfma_f32_16x16x32_bf16 v[62:65], v[202:205], v[46:49], v[10:13]
	v_mfma_f32_16x16x32_bf16 v[10:13], v[206:209], v[42:45], v[170:173]
	v_mfma_f32_16x16x32_bf16 v[58:61], v[210:213], v[46:49], v[10:13]
	v_mfma_f32_16x16x32_bf16 v[10:13], v[198:201], v[214:217], v[174:177]
	v_mfma_f32_16x16x32_bf16 v[46:49], v[202:205], v[218:221], v[10:13]
	v_mfma_f32_16x16x32_bf16 v[10:13], v[206:209], v[214:217], v[178:181]
	v_mfma_f32_16x16x32_bf16 v[42:45], v[210:213], v[218:221], v[10:13]
	v_mfma_f32_16x16x32_bf16 v[10:13], v[198:201], v[222:225], v[182:185]
	v_mfma_f32_16x16x32_bf16 v[30:33], v[202:205], v[226:229], v[10:13]
	v_mfma_f32_16x16x32_bf16 v[10:13], v[206:209], v[222:225], v[186:189]
	v_mfma_f32_16x16x32_bf16 v[26:29], v[210:213], v[226:229], v[10:13]
	v_mfma_f32_16x16x32_bf16 v[10:13], v[198:201], v[230:233], v[190:193]
	v_mfma_f32_16x16x32_bf16 v[14:17], v[202:205], v[234:237], v[10:13]
	v_mfma_f32_16x16x32_bf16 v[10:13], v[206:209], v[230:233], v[194:197]
	v_mfma_f32_16x16x32_bf16 v[10:13], v[210:213], v[234:237], v[10:13]
	s_barrier
	s_add_u32 s74, s74, 0x80180
	s_addc_u32 s75, s75, 0
	s_add_u32 s57, s72, 0x200
	s_addc_u32 s72, s73, 0
	s_mov_b32 s73, 0
	.p2align 6

.LBB0_2389:
	ds_read_b128 v[2:5], v1
	ds_read_b128 v[6:9], v1 offset:1024
	ds_read_b128 v[10:13], v1 offset:2048
	ds_read_b128 v[14:17], v1 offset:3072
	ds_read_b128 v[18:21], v192
	ds_read_b128 v[22:25], v192 offset:1024
	ds_read_b128 v[26:29], v192 offset:2048
	ds_read_b128 v[30:33], v192 offset:3072
	v_lshl_add_u64 v[244:245], s[66:67], 0, v[170:171]
	s_add_i32 s83, s45, 0xc000
	v_lshl_add_u64 v[66:67], v[244:245], 0, s[14:15]
	s_mov_b32 m0, s83
	s_add_i32 s84, s45, 0xe000
	ds_read_b128 v[34:37], v193
	ds_read_b128 v[38:41], v193 offset:1024
	ds_read_b128 v[42:45], v193 offset:2048
	ds_read_b128 v[46:49], v193 offset:3072
	ds_read_b128 v[50:53], v193 offset:4096
	ds_read_b128 v[54:57], v193 offset:5120
	ds_read_b128 v[58:61], v193 offset:6144
	ds_read_b128 v[62:65], v193 offset:7168
	global_load_lds_dwordx4 v[66:67], off
	v_lshl_add_u64 v[66:67], v[244:245], 0, s[16:17]
	s_mov_b32 m0, s84
	s_nop 0
	global_load_lds_dwordx4 v[66:67], off
	s_waitcnt vmcnt(24)
	s_waitcnt lgkmcnt(0)
	s_barrier
	s_waitcnt lgkmcnt(0)
	v_mfma_f32_16x16x32_bf16 v[66:69], v[2:5], v[34:37], 0
	v_mfma_f32_16x16x32_bf16 v[70:73], v[10:13], v[34:37], 0
	v_mfma_f32_16x16x32_bf16 v[74:77], v[2:5], v[42:45], 0
	v_mfma_f32_16x16x32_bf16 v[78:81], v[10:13], v[42:45], 0
	v_mfma_f32_16x16x32_bf16 v[90:93], v[2:5], v[58:61], 0
	v_mfma_f32_16x16x32_bf16 v[94:97], v[10:13], v[58:61], 0
	v_mfma_f32_16x16x32_bf16 v[66:69], v[6:9], v[38:41], v[66:69]
	v_mfma_f32_16x16x32_bf16 v[70:73], v[14:17], v[38:41], v[70:73]
	v_mfma_f32_16x16x32_bf16 v[74:77], v[6:9], v[46:49], v[74:77]
	v_mfma_f32_16x16x32_bf16 v[78:81], v[14:17], v[46:49], v[78:81]
	v_mfma_f32_16x16x32_bf16 v[82:85], v[2:5], v[50:53], 0
	v_mfma_f32_16x16x32_bf16 v[86:89], v[10:13], v[50:53], 0
	v_mfma_f32_16x16x32_bf16 v[90:93], v[6:9], v[62:65], v[90:93]
	v_mfma_f32_16x16x32_bf16 v[94:97], v[14:17], v[62:65], v[94:97]
	v_mfma_f32_16x16x32_bf16 v[82:85], v[6:9], v[54:57], v[82:85]
	v_mfma_f32_16x16x32_bf16 v[86:89], v[14:17], v[54:57], v[86:89]
	v_mfma_f32_16x16x32_bf16 v[98:101], v[18:21], v[34:37], 0
	v_mfma_f32_16x16x32_bf16 v[34:37], v[26:29], v[34:37], 0
	v_mfma_f32_16x16x32_bf16 v[98:101], v[22:25], v[38:41], v[98:101]
	v_mfma_f32_16x16x32_bf16 v[34:37], v[30:33], v[38:41], v[34:37]
	v_mfma_f32_16x16x32_bf16 v[38:41], v[18:21], v[42:45], 0
	v_mfma_f32_16x16x32_bf16 v[42:45], v[26:29], v[42:45], 0
	v_mfma_f32_16x16x32_bf16 v[38:41], v[22:25], v[46:49], v[38:41]
	v_mfma_f32_16x16x32_bf16 v[42:45], v[30:33], v[46:49], v[42:45]
	v_mfma_f32_16x16x32_bf16 v[46:49], v[18:21], v[50:53], 0
	v_mfma_f32_16x16x32_bf16 v[50:53], v[26:29], v[50:53], 0
	v_mfma_f32_16x16x32_bf16 v[46:49], v[22:25], v[54:57], v[46:49]
	v_mfma_f32_16x16x32_bf16 v[50:53], v[30:33], v[54:57], v[50:53]
	v_mfma_f32_16x16x32_bf16 v[54:57], v[18:21], v[58:61], 0
	v_mfma_f32_16x16x32_bf16 v[58:61], v[26:29], v[58:61], 0
	v_mfma_f32_16x16x32_bf16 v[54:57], v[22:25], v[62:65], v[54:57]
	v_mfma_f32_16x16x32_bf16 v[58:61], v[30:33], v[62:65], v[58:61]
	s_barrier
	v_lshl_add_u64 v[246:247], s[68:69], 0, v[172:173]
	s_add_i32 s85, s75, s44
	v_lshl_add_u64 v[130:131], v[246:247], 0, s[18:19]
	s_mov_b32 m0, s85
	s_add_i32 s87, s85, 0x2000
	ds_read_b128 v[62:65], v193 offset:16384
	ds_read_b128 v[102:105], v193 offset:17408
	ds_read_b128 v[106:109], v193 offset:18432
	ds_read_b128 v[110:113], v193 offset:19456
	ds_read_b128 v[114:117], v193 offset:20480
	ds_read_b128 v[118:121], v193 offset:21504
	ds_read_b128 v[122:125], v193 offset:22528
	ds_read_b128 v[126:129], v193 offset:23552
	global_load_lds_dwordx4 v[130:131], off
	v_lshl_add_u64 v[130:131], v[246:247], 0, s[20:21]
	s_mov_b32 m0, s87
	s_add_i32 s88, s76, s44
	global_load_lds_dwordx4 v[130:131], off
	v_lshl_add_u64 v[130:131], v[246:247], 0, s[22:23]
	s_mov_b32 m0, s88
	s_add_i32 s89, s88, 0x2000
	global_load_lds_dwordx4 v[130:131], off
	v_lshl_add_u64 v[130:131], v[246:247], 0, s[24:25]
	s_mov_b32 m0, s89
	s_nop 0
	global_load_lds_dwordx4 v[130:131], off
	v_lshl_add_u64 v[130:131], v[244:245], 0, s[18:19]
	s_mov_b32 m0, s45
	s_nop 0
	global_load_lds_dwordx4 v[130:131], off
	v_lshl_add_u64 v[130:131], v[244:245], 0, s[20:21]
	s_mov_b32 m0, s46
	s_nop 0
	global_load_lds_dwordx4 v[130:131], off
	s_waitcnt vmcnt(24)
	s_waitcnt lgkmcnt(0)
	s_barrier
	s_waitcnt lgkmcnt(0)
	v_mfma_f32_16x16x32_bf16 v[130:133], v[2:5], v[62:65], 0
	v_mfma_f32_16x16x32_bf16 v[146:149], v[6:9], v[102:105], v[130:133]
	v_mfma_f32_16x16x32_bf16 v[130:133], v[10:13], v[62:65], 0
	v_mfma_f32_16x16x32_bf16 v[150:153], v[14:17], v[102:105], v[130:133]
	v_mfma_f32_16x16x32_bf16 v[130:133], v[2:5], v[106:109], 0
	v_mfma_f32_16x16x32_bf16 v[154:157], v[6:9], v[110:113], v[130:133]
	v_mfma_f32_16x16x32_bf16 v[130:133], v[10:13], v[106:109], 0
	v_mfma_f32_16x16x32_bf16 v[158:161], v[14:17], v[110:113], v[130:133]
	v_mfma_f32_16x16x32_bf16 v[130:133], v[2:5], v[114:117], 0
	v_mfma_f32_16x16x32_bf16 v[2:5], v[2:5], v[122:125], 0
	v_mfma_f32_16x16x32_bf16 v[162:165], v[6:9], v[118:121], v[130:133]
	v_mfma_f32_16x16x32_bf16 v[2:5], v[6:9], v[126:129], v[2:5]
	v_mfma_f32_16x16x32_bf16 v[6:9], v[10:13], v[122:125], 0
	v_mfma_f32_16x16x32_bf16 v[130:133], v[10:13], v[114:117], 0
	v_mfma_f32_16x16x32_bf16 v[6:9], v[14:17], v[126:129], v[6:9]
	v_mfma_f32_16x16x32_bf16 v[166:169], v[14:17], v[118:121], v[130:133]
	v_mfma_f32_16x16x32_bf16 v[10:13], v[18:21], v[62:65], 0
	v_mfma_f32_16x16x32_bf16 v[180:183], v[22:25], v[102:105], v[10:13]
	v_mfma_f32_16x16x32_bf16 v[10:13], v[26:29], v[62:65], 0
	v_mfma_f32_16x16x32_bf16 v[102:105], v[30:33], v[102:105], v[10:13]
	v_mfma_f32_16x16x32_bf16 v[10:13], v[18:21], v[106:109], 0
	v_mfma_f32_16x16x32_bf16 v[184:187], v[22:25], v[110:113], v[10:13]
	v_mfma_f32_16x16x32_bf16 v[10:13], v[26:29], v[106:109], 0
	v_mfma_f32_16x16x32_bf16 v[188:191], v[30:33], v[110:113], v[10:13]
	v_mfma_f32_16x16x32_bf16 v[10:13], v[18:21], v[114:117], 0
	v_mfma_f32_16x16x32_bf16 v[196:199], v[22:25], v[118:121], v[10:13]
	v_mfma_f32_16x16x32_bf16 v[10:13], v[26:29], v[114:117], 0
	v_mfma_f32_16x16x32_bf16 v[200:203], v[30:33], v[118:121], v[10:13]
	v_mfma_f32_16x16x32_bf16 v[10:13], v[18:21], v[122:125], 0
	v_mfma_f32_16x16x32_bf16 v[204:207], v[22:25], v[126:129], v[10:13]
	v_mfma_f32_16x16x32_bf16 v[10:13], v[26:29], v[122:125], 0
	v_mfma_f32_16x16x32_bf16 v[208:211], v[30:33], v[126:129], v[10:13]
	s_barrier
; #define PG8_WAIT_V(n) asm volatile("s_waitcnt vmcnt(" #n ")" ::: "memory")
; template <class Epi, class Sched, bool ALIGN_EPI = true, bool SP2 = true, bool FULLLINE = false, bool NOSTAGE = false, bool FP8 = false>
; __device__ __forceinline__ void gemm_phase(PG8_LAS unsigned char* lds, const Gemm g, const Sched& S, const Epi& E) {
;     ...
;         static_assert(SP2, "only the SP2 loop is kept");
;         { const int t = 0; if constexpr (Epi::NST == 16) PG8_ITER(PG8_WAIT_V(24)); else if constexpr (Epi::NST == 8) PG8_ITER(PG8_WAIT_V(16)); else PG8_ITER(PG8_WAIT_V(8)); }
;         for (int t = 2; t < nt; t += 2) PG8_ITER(PG8_WAIT_V(8));
	s_nop 5
	ds_read_b128 v[10:13], v194
	ds_read_b128 v[14:17], v194 offset:1024
	ds_read_b128 v[18:21], v194 offset:2048
	ds_read_b128 v[22:25], v194 offset:3072
	ds_read_b128 v[212:215], v195
	ds_read_b128 v[216:219], v195 offset:1024
	ds_read_b128 v[220:223], v195 offset:2048
	ds_read_b128 v[224:227], v195 offset:3072
	s_mov_b32 m0, s47
	v_lshl_add_u64 v[106:107], v[244:245], 0, s[22:23]
	ds_read_b128 v[26:29], v193 offset:32768
	ds_read_b128 v[30:33], v193 offset:33792
	ds_read_b128 v[62:65], v193 offset:34816
	ds_read_b128 v[114:117], v193 offset:35840
	ds_read_b128 v[228:231], v193 offset:36864
	ds_read_b128 v[232:235], v193 offset:37888
	ds_read_b128 v[236:239], v193 offset:38912
	ds_read_b128 v[240:243], v193 offset:39936
	global_load_lds_dwordx4 v[106:107], off
	v_lshl_add_u64 v[106:107], v[244:245], 0, s[24:25]
	s_mov_b32 m0, s52
	s_nop 0
	global_load_lds_dwordx4 v[106:107], off
	s_waitcnt vmcnt(8)
	s_waitcnt lgkmcnt(0)
	s_barrier
	s_waitcnt lgkmcnt(0)
	v_mfma_f32_16x16x32_bf16 v[66:69], v[10:13], v[26:29], v[66:69]
	v_mfma_f32_16x16x32_bf16 v[142:145], v[14:17], v[30:33], v[66:69]
	v_mfma_f32_16x16x32_bf16 v[66:69], v[18:21], v[26:29], v[70:73]
	v_mfma_f32_16x16x32_bf16 v[138:141], v[22:25], v[30:33], v[66:69]
	v_mfma_f32_16x16x32_bf16 v[66:69], v[10:13], v[62:65], v[74:77]
	v_mfma_f32_16x16x32_bf16 v[126:129], v[14:17], v[114:117], v[66:69]
	v_mfma_f32_16x16x32_bf16 v[66:69], v[18:21], v[62:65], v[78:81]
	v_mfma_f32_16x16x32_bf16 v[122:125], v[22:25], v[114:117], v[66:69]
	v_mfma_f32_16x16x32_bf16 v[66:69], v[10:13], v[228:231], v[82:85]
	v_mfma_f32_16x16x32_bf16 v[110:113], v[14:17], v[232:235], v[66:69]
	v_mfma_f32_16x16x32_bf16 v[66:69], v[18:21], v[228:231], v[86:89]
	v_mfma_f32_16x16x32_bf16 v[106:109], v[22:25], v[232:235], v[66:69]
	v_mfma_f32_16x16x32_bf16 v[66:69], v[10:13], v[236:239], v[90:93]
	v_mfma_f32_16x16x32_bf16 v[78:81], v[14:17], v[240:243], v[66:69]
	v_mfma_f32_16x16x32_bf16 v[66:69], v[18:21], v[236:239], v[94:97]
	v_mfma_f32_16x16x32_bf16 v[74:77], v[22:25], v[240:243], v[66:69]
	v_mfma_f32_16x16x32_bf16 v[66:69], v[212:215], v[26:29], v[98:101]
	v_mfma_f32_16x16x32_bf16 v[26:29], v[220:223], v[26:29], v[34:37]
	v_mfma_f32_16x16x32_bf16 v[130:133], v[224:227], v[30:33], v[26:29]
	v_mfma_f32_16x16x32_bf16 v[26:29], v[212:215], v[62:65], v[38:41]
	v_mfma_f32_16x16x32_bf16 v[118:121], v[216:219], v[114:117], v[26:29]
	v_mfma_f32_16x16x32_bf16 v[26:29], v[220:223], v[62:65], v[42:45]
	v_mfma_f32_16x16x32_bf16 v[114:117], v[224:227], v[114:117], v[26:29]
	v_mfma_f32_16x16x32_bf16 v[26:29], v[212:215], v[228:231], v[46:49]
	v_mfma_f32_16x16x32_bf16 v[94:97], v[216:219], v[232:235], v[26:29]
	v_mfma_f32_16x16x32_bf16 v[26:29], v[220:223], v[228:231], v[50:53]
	v_mfma_f32_16x16x32_bf16 v[90:93], v[224:227], v[232:235], v[26:29]
	v_mfma_f32_16x16x32_bf16 v[26:29], v[212:215], v[236:239], v[54:57]
	v_mfma_f32_16x16x32_bf16 v[70:73], v[216:219], v[240:243], v[26:29]
	v_mfma_f32_16x16x32_bf16 v[26:29], v[220:223], v[236:239], v[58:61]
	v_mfma_f32_16x16x32_bf16 v[134:137], v[216:219], v[30:33], v[66:69]
	v_mfma_f32_16x16x32_bf16 v[66:69], v[224:227], v[240:243], v[26:29]
	s_barrier
	s_add_i32 s50, s77, s44
	s_nop 3
	v_lshl_add_u64 v[26:27], v[246:247], 0, s[26:27]
	s_mov_b32 m0, s50
	s_add_i32 s51, s50, 0x2000
	ds_read_b128 v[34:37], v193 offset:49152
	ds_read_b128 v[38:41], v193 offset:50176
	ds_read_b128 v[82:85], v193 offset:51200
	ds_read_b128 v[86:89], v193 offset:52224
	ds_read_b128 v[98:101], v193 offset:53248
	ds_read_b128 v[228:231], v193 offset:54272
	ds_read_b128 v[232:235], v193 offset:55296
	ds_read_b128 v[236:239], v193 offset:56320
	global_load_lds_dwordx4 v[26:27], off
	v_lshl_add_u64 v[26:27], v[246:247], 0, s[28:29]
	s_mov_b32 m0, s51
	s_mov_b64 s[0:1], 0x160180
	s_add_i32 s33, s78, s44
	global_load_lds_dwordx4 v[26:27], off
	v_lshl_add_u64 v[26:27], v[246:247], 0, s[0:1]
	s_mov_b32 m0, s33
	s_mov_b64 s[0:1], 0x210180
	s_add_i32 s56, s33, 0x2000
	global_load_lds_dwordx4 v[26:27], off
	v_lshl_add_u64 v[26:27], v[246:247], 0, s[0:1]
	s_mov_b32 m0, s56
	s_nop 0
	global_load_lds_dwordx4 v[26:27], off
	v_lshl_add_u64 v[26:27], v[244:245], 0, s[26:27]
	s_mov_b32 m0, s53
	s_nop 0
	global_load_lds_dwordx4 v[26:27], off
	v_lshl_add_u64 v[26:27], v[244:245], 0, s[28:29]
	s_mov_b32 m0, s54
	s_nop 0
	global_load_lds_dwordx4 v[26:27], off
	s_waitcnt vmcnt(8)
	s_waitcnt lgkmcnt(0)
	s_barrier
	s_waitcnt lgkmcnt(0)
	v_mfma_f32_16x16x32_bf16 v[26:29], v[10:13], v[34:37], v[146:149]
	v_mfma_f32_16x16x32_bf16 v[62:65], v[14:17], v[38:41], v[26:29]
	v_mfma_f32_16x16x32_bf16 v[26:29], v[18:21], v[34:37], v[150:153]
	v_mfma_f32_16x16x32_bf16 v[58:61], v[22:25], v[38:41], v[26:29]
	v_mfma_f32_16x16x32_bf16 v[26:29], v[10:13], v[82:85], v[154:157]
	v_mfma_f32_16x16x32_bf16 v[46:49], v[14:17], v[86:89], v[26:29]
	v_mfma_f32_16x16x32_bf16 v[26:29], v[18:21], v[82:85], v[158:161]
	v_mfma_f32_16x16x32_bf16 v[42:45], v[22:25], v[86:89], v[26:29]
	v_mfma_f32_16x16x32_bf16 v[26:29], v[10:13], v[98:101], v[162:165]
	v_mfma_f32_16x16x32_bf16 v[2:5], v[10:13], v[232:235], v[2:5]
	v_mfma_f32_16x16x32_bf16 v[30:33], v[14:17], v[228:231], v[26:29]
	v_mfma_f32_16x16x32_bf16 v[26:29], v[18:21], v[98:101], v[166:169]
	v_mfma_f32_16x16x32_bf16 v[14:17], v[14:17], v[236:239], v[2:5]
	v_mfma_f32_16x16x32_bf16 v[2:5], v[18:21], v[232:235], v[6:9]
	v_mfma_f32_16x16x32_bf16 v[26:29], v[22:25], v[228:231], v[26:29]
	v_mfma_f32_16x16x32_bf16 v[10:13], v[22:25], v[236:239], v[2:5]
	v_mfma_f32_16x16x32_bf16 v[2:5], v[212:215], v[34:37], v[180:183]
	v_mfma_f32_16x16x32_bf16 v[54:57], v[216:219], v[38:41], v[2:5]
	v_mfma_f32_16x16x32_bf16 v[2:5], v[220:223], v[34:37], v[102:105]
	v_mfma_f32_16x16x32_bf16 v[50:53], v[224:227], v[38:41], v[2:5]
	v_mfma_f32_16x16x32_bf16 v[2:5], v[212:215], v[82:85], v[184:187]
	v_mfma_f32_16x16x32_bf16 v[38:41], v[216:219], v[86:89], v[2:5]
	v_mfma_f32_16x16x32_bf16 v[2:5], v[220:223], v[82:85], v[188:191]
	v_mfma_f32_16x16x32_bf16 v[34:37], v[224:227], v[86:89], v[2:5]
	v_mfma_f32_16x16x32_bf16 v[2:5], v[212:215], v[98:101], v[196:199]
	v_mfma_f32_16x16x32_bf16 v[22:25], v[216:219], v[228:231], v[2:5]
	v_mfma_f32_16x16x32_bf16 v[2:5], v[220:223], v[98:101], v[200:203]
	v_mfma_f32_16x16x32_bf16 v[18:21], v[224:227], v[228:231], v[2:5]
	v_mfma_f32_16x16x32_bf16 v[2:5], v[212:215], v[232:235], v[204:207]
	v_mfma_f32_16x16x32_bf16 v[6:9], v[216:219], v[236:239], v[2:5]
	v_mfma_f32_16x16x32_bf16 v[2:5], v[220:223], v[232:235], v[208:211]
	v_mfma_f32_16x16x32_bf16 v[2:5], v[224:227], v[236:239], v[2:5]
	s_barrier
	s_add_u32 s66, s66, 0x160180
	s_addc_u32 s67, s67, 0
	s_add_u32 s57, s68, 0x200
	s_addc_u32 s68, s69, 0
	s_mov_b32 s69, 0
	.p2align 6

; template <class Epi, class Sched, bool ALIGN_EPI = true, bool SP2 = true, bool FULLLINE = false, bool NOSTAGE = false, bool FP8 = false>
; __device__ __forceinline__ void gemm_phase(PG8_LAS unsigned char* lds, const Gemm g, const Sched& S, const Epi& E) {
;     ...
;         const bool has_next = S.next(ui + 1, nxt);
;         const char* nA = has_next ? PG8_ABASE(nxt) : cA; const char* nB = has_next ? PG8_BBASE(nxt) : cB;
.LBB0_2681:
	ds_read_b128 v[2:5], v1
	ds_read_b128 v[6:9], v1 offset:1024
	ds_read_b128 v[10:13], v1 offset:2048
	ds_read_b128 v[14:17], v1 offset:3072
	ds_read_b128 v[18:21], v200
	ds_read_b128 v[22:25], v200 offset:1024
	ds_read_b128 v[26:29], v200 offset:2048
	ds_read_b128 v[30:33], v200 offset:3072
	s_ashr_i32 s31, s30, 31
	s_lshl_b64 s[0:1], s[30:31], 18
	s_add_u32 s38, s43, s0
	s_addc_u32 s39, s46, s1
	s_and_b64 s[0:1], s[10:11], exec
	s_cselect_b32 s31, s39, s63
	s_cselect_b32 s35, s38, s62
	v_lshl_add_u64 v[244:245], s[66:67], 0, v[178:179]
	s_mov_b64 s[0:1], 0x80080
	s_add_i32 s79, s41, 0xc000
	v_lshl_add_u64 v[66:67], v[244:245], 0, s[0:1]
	s_mov_b32 m0, s79
	s_mov_b64 s[0:1], 0xc0080
	s_add_i32 s80, s41, 0xe000
	ds_read_b128 v[34:37], v201
	ds_read_b128 v[38:41], v201 offset:1024
	ds_read_b128 v[42:45], v201 offset:2048
	ds_read_b128 v[46:49], v201 offset:3072
	ds_read_b128 v[50:53], v201 offset:4096
	ds_read_b128 v[54:57], v201 offset:5120
	ds_read_b128 v[58:61], v201 offset:6144
	ds_read_b128 v[62:65], v201 offset:7168
	global_load_lds_dwordx4 v[66:67], off
	v_lshl_add_u64 v[66:67], v[244:245], 0, s[0:1]
	s_mov_b32 m0, s80
	s_nop 0
	global_load_lds_dwordx4 v[66:67], off
	s_waitcnt vmcnt(24)
	s_waitcnt lgkmcnt(0)
	s_barrier
	s_waitcnt lgkmcnt(0)
	v_mfma_f32_16x16x32_bf16 v[66:69], v[2:5], v[34:37], 0
	v_mfma_f32_16x16x32_bf16 v[70:73], v[10:13], v[34:37], 0
	v_mfma_f32_16x16x32_bf16 v[74:77], v[2:5], v[42:45], 0
	v_mfma_f32_16x16x32_bf16 v[78:81], v[10:13], v[42:45], 0
	v_mfma_f32_16x16x32_bf16 v[82:85], v[2:5], v[50:53], 0
	v_mfma_f32_16x16x32_bf16 v[90:93], v[2:5], v[58:61], 0
	v_mfma_f32_16x16x32_bf16 v[66:69], v[6:9], v[38:41], v[66:69]
	v_mfma_f32_16x16x32_bf16 v[70:73], v[14:17], v[38:41], v[70:73]
	v_mfma_f32_16x16x32_bf16 v[74:77], v[6:9], v[46:49], v[74:77]
	v_mfma_f32_16x16x32_bf16 v[78:81], v[14:17], v[46:49], v[78:81]
	v_mfma_f32_16x16x32_bf16 v[82:85], v[6:9], v[54:57], v[82:85]
	v_mfma_f32_16x16x32_bf16 v[86:89], v[10:13], v[50:53], 0
	v_mfma_f32_16x16x32_bf16 v[90:93], v[6:9], v[62:65], v[90:93]
	v_mfma_f32_16x16x32_bf16 v[94:97], v[10:13], v[58:61], 0
	v_mfma_f32_16x16x32_bf16 v[86:89], v[14:17], v[54:57], v[86:89]
	v_mfma_f32_16x16x32_bf16 v[94:97], v[14:17], v[62:65], v[94:97]
	v_mfma_f32_16x16x32_bf16 v[98:101], v[18:21], v[34:37], 0
	v_mfma_f32_16x16x32_bf16 v[34:37], v[26:29], v[34:37], 0
	v_mfma_f32_16x16x32_bf16 v[102:105], v[22:25], v[38:41], v[98:101]
	v_mfma_f32_16x16x32_bf16 v[34:37], v[30:33], v[38:41], v[34:37]
	v_mfma_f32_16x16x32_bf16 v[38:41], v[18:21], v[42:45], 0
	v_mfma_f32_16x16x32_bf16 v[42:45], v[26:29], v[42:45], 0
	v_mfma_f32_16x16x32_bf16 v[38:41], v[22:25], v[46:49], v[38:41]
	v_mfma_f32_16x16x32_bf16 v[42:45], v[30:33], v[46:49], v[42:45]
	v_mfma_f32_16x16x32_bf16 v[46:49], v[18:21], v[50:53], 0
	v_mfma_f32_16x16x32_bf16 v[50:53], v[26:29], v[50:53], 0
	v_mfma_f32_16x16x32_bf16 v[46:49], v[22:25], v[54:57], v[46:49]
	v_mfma_f32_16x16x32_bf16 v[50:53], v[30:33], v[54:57], v[50:53]
	v_mfma_f32_16x16x32_bf16 v[54:57], v[18:21], v[58:61], 0
	v_mfma_f32_16x16x32_bf16 v[58:61], v[26:29], v[58:61], 0
	v_mfma_f32_16x16x32_bf16 v[54:57], v[22:25], v[62:65], v[54:57]
	v_mfma_f32_16x16x32_bf16 v[58:61], v[30:33], v[62:65], v[58:61]
	s_barrier
	v_lshl_add_u64 v[246:247], s[62:63], 0, v[180:181]
	s_add_i32 s81, s75, s47
	v_lshl_add_u64 v[130:131], v[246:247], 0, s[18:19]
	s_mov_b32 m0, s81
	s_mov_b64 s[0:1], 0x10100
	s_add_i32 s82, s81, 0x2000
	ds_read_b128 v[62:65], v201 offset:16384
	ds_read_b128 v[98:101], v201 offset:17408
	ds_read_b128 v[106:109], v201 offset:18432
	ds_read_b128 v[110:113], v201 offset:19456
	ds_read_b128 v[114:117], v201 offset:20480
	ds_read_b128 v[118:121], v201 offset:21504
	ds_read_b128 v[122:125], v201 offset:22528
	ds_read_b128 v[126:129], v201 offset:23552
	global_load_lds_dwordx4 v[130:131], off
	v_lshl_add_u64 v[130:131], v[246:247], 0, s[0:1]
	s_mov_b32 m0, s82
	s_mov_b64 s[0:1], 0x20100
	s_add_i32 s83, s76, s47
	global_load_lds_dwordx4 v[130:131], off
	v_lshl_add_u64 v[130:131], v[246:247], 0, s[0:1]
	s_mov_b32 m0, s83
	s_mov_b64 s[0:1], 0x30100
	s_add_i32 s84, s83, 0x2000
	global_load_lds_dwordx4 v[130:131], off
	v_lshl_add_u64 v[130:131], v[246:247], 0, s[0:1]
	s_mov_b32 m0, s84
	s_mov_b64 s[0:1], 0x40100
	global_load_lds_dwordx4 v[130:131], off
	v_lshl_add_u64 v[130:131], v[244:245], 0, s[18:19]
	s_mov_b32 m0, s41
	s_nop 0
	global_load_lds_dwordx4 v[130:131], off
	v_lshl_add_u64 v[130:131], v[244:245], 0, s[0:1]
	s_mov_b32 m0, s45
	s_nop 0
	global_load_lds_dwordx4 v[130:131], off
	s_waitcnt vmcnt(24)
	s_waitcnt lgkmcnt(0)
	s_barrier
	s_waitcnt lgkmcnt(0)
	v_mfma_f32_16x16x32_bf16 v[130:133], v[2:5], v[62:65], 0
	v_mfma_f32_16x16x32_bf16 v[146:149], v[6:9], v[98:101], v[130:133]
	v_mfma_f32_16x16x32_bf16 v[130:133], v[10:13], v[62:65], 0
	v_mfma_f32_16x16x32_bf16 v[150:153], v[14:17], v[98:101], v[130:133]
	v_mfma_f32_16x16x32_bf16 v[130:133], v[2:5], v[106:109], 0
	v_mfma_f32_16x16x32_bf16 v[154:157], v[6:9], v[110:113], v[130:133]
	v_mfma_f32_16x16x32_bf16 v[130:133], v[10:13], v[106:109], 0
	v_mfma_f32_16x16x32_bf16 v[158:161], v[14:17], v[110:113], v[130:133]
	v_mfma_f32_16x16x32_bf16 v[130:133], v[2:5], v[114:117], 0
	v_mfma_f32_16x16x32_bf16 v[2:5], v[2:5], v[122:125], 0
	v_mfma_f32_16x16x32_bf16 v[162:165], v[6:9], v[118:121], v[130:133]
	v_mfma_f32_16x16x32_bf16 v[2:5], v[6:9], v[126:129], v[2:5]
	v_mfma_f32_16x16x32_bf16 v[6:9], v[10:13], v[122:125], 0
	v_mfma_f32_16x16x32_bf16 v[130:133], v[10:13], v[114:117], 0
	v_mfma_f32_16x16x32_bf16 v[6:9], v[14:17], v[126:129], v[6:9]
	v_mfma_f32_16x16x32_bf16 v[166:169], v[14:17], v[118:121], v[130:133]
	v_mfma_f32_16x16x32_bf16 v[10:13], v[18:21], v[62:65], 0
	v_mfma_f32_16x16x32_bf16 v[170:173], v[22:25], v[98:101], v[10:13]
	v_mfma_f32_16x16x32_bf16 v[10:13], v[26:29], v[62:65], 0
	v_mfma_f32_16x16x32_bf16 v[174:177], v[30:33], v[98:101], v[10:13]
	v_mfma_f32_16x16x32_bf16 v[10:13], v[18:21], v[106:109], 0
	v_mfma_f32_16x16x32_bf16 v[188:191], v[22:25], v[110:113], v[10:13]
	v_mfma_f32_16x16x32_bf16 v[10:13], v[26:29], v[106:109], 0
	v_mfma_f32_16x16x32_bf16 v[106:109], v[30:33], v[110:113], v[10:13]
	v_mfma_f32_16x16x32_bf16 v[10:13], v[18:21], v[114:117], 0
	v_mfma_f32_16x16x32_bf16 v[192:195], v[22:25], v[118:121], v[10:13]
	v_mfma_f32_16x16x32_bf16 v[10:13], v[26:29], v[114:117], 0
	v_mfma_f32_16x16x32_bf16 v[196:199], v[30:33], v[118:121], v[10:13]
	v_mfma_f32_16x16x32_bf16 v[10:13], v[18:21], v[122:125], 0
	v_mfma_f32_16x16x32_bf16 v[204:207], v[22:25], v[126:129], v[10:13]
	v_mfma_f32_16x16x32_bf16 v[10:13], v[26:29], v[122:125], 0
	v_mfma_f32_16x16x32_bf16 v[208:211], v[30:33], v[126:129], v[10:13]
	s_barrier
; #define PG8_WAIT_V(n) asm volatile("s_waitcnt vmcnt(" #n ")" ::: "memory")
; template <class Epi, class Sched, bool ALIGN_EPI = true, bool SP2 = true, bool FULLLINE = false, bool NOSTAGE = false, bool FP8 = false>
; __device__ __forceinline__ void gemm_phase(PG8_LAS unsigned char* lds, const Gemm g, const Sched& S, const Epi& E) {
;     ...
;         static_assert(SP2, "only the SP2 loop is kept");
;         { const int t = 0; if constexpr (Epi::NST == 16) PG8_ITER(PG8_WAIT_V(24)); else if constexpr (Epi::NST == 8) PG8_ITER(PG8_WAIT_V(16)); else PG8_ITER(PG8_WAIT_V(8)); }
;         for (int t = 2; t < nt; t += 2) PG8_ITER(PG8_WAIT_V(8));
	s_nop 5
	ds_read_b128 v[10:13], v202
	ds_read_b128 v[14:17], v202 offset:1024
	ds_read_b128 v[18:21], v202 offset:2048
	ds_read_b128 v[22:25], v202 offset:3072
	ds_read_b128 v[212:215], v203
	ds_read_b128 v[216:219], v203 offset:1024
	ds_read_b128 v[220:223], v203 offset:2048
	ds_read_b128 v[224:227], v203 offset:3072
	s_mov_b64 s[0:1], 0x80100
	s_mov_b32 m0, s52
	v_lshl_add_u64 v[98:99], v[244:245], 0, s[0:1]
	s_mov_b64 s[0:1], 0xc0100
	ds_read_b128 v[26:29], v201 offset:32768
	ds_read_b128 v[30:33], v201 offset:33792
	ds_read_b128 v[62:65], v201 offset:34816
	ds_read_b128 v[114:117], v201 offset:35840
	ds_read_b128 v[228:231], v201 offset:36864
	ds_read_b128 v[232:235], v201 offset:37888
	ds_read_b128 v[236:239], v201 offset:38912
	ds_read_b128 v[240:243], v201 offset:39936
	global_load_lds_dwordx4 v[98:99], off
	v_lshl_add_u64 v[98:99], v[244:245], 0, s[0:1]
	s_mov_b32 m0, s53
	s_nop 0
	global_load_lds_dwordx4 v[98:99], off
	s_waitcnt vmcnt(8)
	s_waitcnt lgkmcnt(0)
	s_barrier
	s_waitcnt lgkmcnt(0)
	v_mfma_f32_16x16x32_bf16 v[66:69], v[10:13], v[26:29], v[66:69]
	v_mfma_f32_16x16x32_bf16 v[134:137], v[14:17], v[30:33], v[66:69]
	v_mfma_f32_16x16x32_bf16 v[66:69], v[18:21], v[26:29], v[70:73]
	v_mfma_f32_16x16x32_bf16 v[130:133], v[22:25], v[30:33], v[66:69]
	v_mfma_f32_16x16x32_bf16 v[66:69], v[10:13], v[62:65], v[74:77]
	v_mfma_f32_16x16x32_bf16 v[126:129], v[14:17], v[114:117], v[66:69]
	v_mfma_f32_16x16x32_bf16 v[66:69], v[18:21], v[62:65], v[78:81]
	v_mfma_f32_16x16x32_bf16 v[122:125], v[22:25], v[114:117], v[66:69]
	v_mfma_f32_16x16x32_bf16 v[66:69], v[10:13], v[228:231], v[82:85]
	v_mfma_f32_16x16x32_bf16 v[110:113], v[14:17], v[232:235], v[66:69]
	v_mfma_f32_16x16x32_bf16 v[66:69], v[18:21], v[228:231], v[86:89]
	v_mfma_f32_16x16x32_bf16 v[98:101], v[22:25], v[232:235], v[66:69]
	v_mfma_f32_16x16x32_bf16 v[66:69], v[10:13], v[236:239], v[90:93]
	v_mfma_f32_16x16x32_bf16 v[78:81], v[14:17], v[240:243], v[66:69]
	v_mfma_f32_16x16x32_bf16 v[66:69], v[18:21], v[236:239], v[94:97]
	v_mfma_f32_16x16x32_bf16 v[74:77], v[22:25], v[240:243], v[66:69]
	v_mfma_f32_16x16x32_bf16 v[66:69], v[212:215], v[26:29], v[102:105]
	v_mfma_f32_16x16x32_bf16 v[26:29], v[220:223], v[26:29], v[34:37]
	v_mfma_f32_16x16x32_bf16 v[138:141], v[224:227], v[30:33], v[26:29]
	v_mfma_f32_16x16x32_bf16 v[26:29], v[212:215], v[62:65], v[38:41]
	v_mfma_f32_16x16x32_bf16 v[118:121], v[216:219], v[114:117], v[26:29]
	v_mfma_f32_16x16x32_bf16 v[26:29], v[220:223], v[62:65], v[42:45]
	v_mfma_f32_16x16x32_bf16 v[114:117], v[224:227], v[114:117], v[26:29]
	v_mfma_f32_16x16x32_bf16 v[26:29], v[212:215], v[228:231], v[46:49]
	v_mfma_f32_16x16x32_bf16 v[90:93], v[216:219], v[232:235], v[26:29]
	v_mfma_f32_16x16x32_bf16 v[26:29], v[220:223], v[228:231], v[50:53]
	v_mfma_f32_16x16x32_bf16 v[82:85], v[224:227], v[232:235], v[26:29]
	v_mfma_f32_16x16x32_bf16 v[26:29], v[212:215], v[236:239], v[54:57]
	v_mfma_f32_16x16x32_bf16 v[70:73], v[216:219], v[240:243], v[26:29]
	v_mfma_f32_16x16x32_bf16 v[26:29], v[220:223], v[236:239], v[58:61]
	v_mfma_f32_16x16x32_bf16 v[142:145], v[216:219], v[30:33], v[66:69]
	v_mfma_f32_16x16x32_bf16 v[66:69], v[224:227], v[240:243], v[26:29]
	s_barrier
	s_add_i32 s85, s77, s47
	s_nop 3
	v_lshl_add_u64 v[26:27], v[246:247], 0, s[20:21]
	s_mov_b32 m0, s85
	s_mov_b64 s[0:1], 0x10180
	s_add_i32 s87, s85, 0x2000
	ds_read_b128 v[34:37], v201 offset:49152
	ds_read_b128 v[38:41], v201 offset:50176
	ds_read_b128 v[86:89], v201 offset:51200
	ds_read_b128 v[94:97], v201 offset:52224
	ds_read_b128 v[102:105], v201 offset:53248
	ds_read_b128 v[228:231], v201 offset:54272
	ds_read_b128 v[232:235], v201 offset:55296
	ds_read_b128 v[236:239], v201 offset:56320
	global_load_lds_dwordx4 v[26:27], off
	v_lshl_add_u64 v[26:27], v[246:247], 0, s[0:1]
	s_mov_b32 m0, s87
	s_mov_b64 s[0:1], 0x20180
	s_add_i32 s50, s78, s47
	global_load_lds_dwordx4 v[26:27], off
	v_lshl_add_u64 v[26:27], v[246:247], 0, s[0:1]
	s_mov_b32 m0, s50
	s_mov_b64 s[0:1], 0x30180
	s_add_i32 s51, s50, 0x2000
	global_load_lds_dwordx4 v[26:27], off
	v_lshl_add_u64 v[26:27], v[246:247], 0, s[0:1]
	s_mov_b32 m0, s51
	s_mov_b64 s[0:1], 0x40180
	global_load_lds_dwordx4 v[26:27], off
	v_lshl_add_u64 v[26:27], v[244:245], 0, s[20:21]
	s_mov_b32 m0, s54
	s_nop 0
	global_load_lds_dwordx4 v[26:27], off
	v_lshl_add_u64 v[26:27], v[244:245], 0, s[0:1]
	s_mov_b32 m0, s55
	s_nop 0
	global_load_lds_dwordx4 v[26:27], off
	s_waitcnt vmcnt(8)
	s_waitcnt lgkmcnt(0)
	s_barrier
	s_waitcnt lgkmcnt(0)
	v_mfma_f32_16x16x32_bf16 v[26:29], v[10:13], v[34:37], v[146:149]
	v_mfma_f32_16x16x32_bf16 v[62:65], v[14:17], v[38:41], v[26:29]
	v_mfma_f32_16x16x32_bf16 v[26:29], v[18:21], v[34:37], v[150:153]
	v_mfma_f32_16x16x32_bf16 v[58:61], v[22:25], v[38:41], v[26:29]
	v_mfma_f32_16x16x32_bf16 v[26:29], v[10:13], v[86:89], v[154:157]
	v_mfma_f32_16x16x32_bf16 v[46:49], v[14:17], v[94:97], v[26:29]
	v_mfma_f32_16x16x32_bf16 v[26:29], v[18:21], v[86:89], v[158:161]
	v_mfma_f32_16x16x32_bf16 v[42:45], v[22:25], v[94:97], v[26:29]
	v_mfma_f32_16x16x32_bf16 v[26:29], v[10:13], v[102:105], v[162:165]
	v_mfma_f32_16x16x32_bf16 v[2:5], v[10:13], v[232:235], v[2:5]
	v_mfma_f32_16x16x32_bf16 v[30:33], v[14:17], v[228:231], v[26:29]
	v_mfma_f32_16x16x32_bf16 v[26:29], v[18:21], v[102:105], v[166:169]
	v_mfma_f32_16x16x32_bf16 v[14:17], v[14:17], v[236:239], v[2:5]
	v_mfma_f32_16x16x32_bf16 v[2:5], v[18:21], v[232:235], v[6:9]
	v_mfma_f32_16x16x32_bf16 v[26:29], v[22:25], v[228:231], v[26:29]
	v_mfma_f32_16x16x32_bf16 v[10:13], v[22:25], v[236:239], v[2:5]
	v_mfma_f32_16x16x32_bf16 v[2:5], v[212:215], v[34:37], v[170:173]
	v_mfma_f32_16x16x32_bf16 v[54:57], v[216:219], v[38:41], v[2:5]
	v_mfma_f32_16x16x32_bf16 v[2:5], v[220:223], v[34:37], v[174:177]
	v_mfma_f32_16x16x32_bf16 v[50:53], v[224:227], v[38:41], v[2:5]
	v_mfma_f32_16x16x32_bf16 v[2:5], v[212:215], v[86:89], v[188:191]
	v_mfma_f32_16x16x32_bf16 v[38:41], v[216:219], v[94:97], v[2:5]
	v_mfma_f32_16x16x32_bf16 v[2:5], v[220:223], v[86:89], v[106:109]
	v_mfma_f32_16x16x32_bf16 v[34:37], v[224:227], v[94:97], v[2:5]
	v_mfma_f32_16x16x32_bf16 v[2:5], v[212:215], v[102:105], v[192:195]
	v_mfma_f32_16x16x32_bf16 v[22:25], v[216:219], v[228:231], v[2:5]
	v_mfma_f32_16x16x32_bf16 v[2:5], v[220:223], v[102:105], v[196:199]
	v_mfma_f32_16x16x32_bf16 v[18:21], v[224:227], v[228:231], v[2:5]
	v_mfma_f32_16x16x32_bf16 v[2:5], v[212:215], v[232:235], v[204:207]
	v_mfma_f32_16x16x32_bf16 v[6:9], v[216:219], v[236:239], v[2:5]
	v_mfma_f32_16x16x32_bf16 v[2:5], v[220:223], v[232:235], v[208:211]
	v_mfma_f32_16x16x32_bf16 v[2:5], v[224:227], v[236:239], v[2:5]
	s_barrier
	s_add_u32 s10, s66, 0x80180
	s_addc_u32 s11, s67, 0
	s_add_u32 s33, s62, 0x200
	s_addc_u32 s56, s63, 0
	s_mov_b32 s57, 0
	.p2align 6

; template <class Epi, class Sched, bool ALIGN_EPI = true, bool SP2 = true, bool FULLLINE = false, bool NOSTAGE = false, bool FP8 = false>
; __device__ __forceinline__ void gemm_phase(PG8_LAS unsigned char* lds, const Gemm g, const Sched& S, const Epi& E) {
;     ...
;         const bool has_next = S.next(ui + 1, nxt);
;         const char* nA = has_next ? PG8_ABASE(nxt) : cA; const char* nB = has_next ? PG8_BBASE(nxt) : cB;
.LBB0_2861:
	s_ashr_i32 s45, s44, 31
	s_lshl_b64 s[0:1], s[44:45], 20
	s_add_u32 s46, s58, s0
	ds_read_b128 v[2:5], v1
	ds_read_b128 v[6:9], v1 offset:1024
	ds_read_b128 v[10:13], v1 offset:2048
	ds_read_b128 v[14:17], v1 offset:3072
	ds_read_b128 v[18:21], v142
	ds_read_b128 v[22:25], v142 offset:1024
	ds_read_b128 v[26:29], v142 offset:2048
	ds_read_b128 v[30:33], v142 offset:3072
	s_addc_u32 s47, s59, s1
	s_ashr_i32 s41, s40, 31
	s_lshl_b64 s[0:1], s[40:41], 20
	s_add_u32 s62, s3, s0
	s_addc_u32 s63, s42, s1
	s_and_b64 s[0:1], s[8:9], exec
	s_cselect_b32 s41, s47, s71
	s_cselect_b32 s45, s46, s70
	s_cselect_b32 s87, s63, s69
	s_cselect_b32 s88, s62, s68
	v_lshl_add_u64 v[140:141], s[70:71], 0, v[132:133]
	s_mov_b32 m0, s79
	v_lshl_add_u64 v[66:67], v[140:141], 0, s[12:13]
	ds_read_b128 v[34:37], v143
	ds_read_b128 v[38:41], v143 offset:1024
	ds_read_b128 v[42:45], v143 offset:2048
	ds_read_b128 v[46:49], v143 offset:3072
	ds_read_b128 v[50:53], v143 offset:4096
	ds_read_b128 v[54:57], v143 offset:5120
	ds_read_b128 v[58:61], v143 offset:6144
	ds_read_b128 v[62:65], v143 offset:7168
	global_load_lds_dwordx4 v[66:67], off
	v_lshl_add_u64 v[66:67], v[140:141], 0, s[14:15]
	s_mov_b32 m0, s80
	s_nop 0
	global_load_lds_dwordx4 v[66:67], off
	s_waitcnt vmcnt(16)
	s_waitcnt lgkmcnt(0)
	s_barrier
	s_waitcnt lgkmcnt(0)
	v_mfma_f32_16x16x32_bf16 v[86:89], v[10:13], v[50:53], 0
	v_mfma_f32_16x16x32_bf16 v[90:93], v[14:17], v[54:57], v[86:89]
	v_mfma_f32_16x16x32_bf16 v[86:89], v[2:5], v[58:61], 0
	v_mfma_f32_16x16x32_bf16 v[66:69], v[2:5], v[34:37], 0
	v_mfma_f32_16x16x32_bf16 v[70:73], v[10:13], v[34:37], 0
	v_mfma_f32_16x16x32_bf16 v[74:77], v[2:5], v[42:45], 0
	v_mfma_f32_16x16x32_bf16 v[78:81], v[10:13], v[42:45], 0
	v_mfma_f32_16x16x32_bf16 v[82:85], v[2:5], v[50:53], 0
	v_mfma_f32_16x16x32_bf16 v[94:97], v[6:9], v[62:65], v[86:89]
	v_mfma_f32_16x16x32_bf16 v[86:89], v[10:13], v[58:61], 0
	v_mfma_f32_16x16x32_bf16 v[66:69], v[6:9], v[38:41], v[66:69]
	v_mfma_f32_16x16x32_bf16 v[70:73], v[14:17], v[38:41], v[70:73]
	v_mfma_f32_16x16x32_bf16 v[74:77], v[6:9], v[46:49], v[74:77]
	v_mfma_f32_16x16x32_bf16 v[78:81], v[14:17], v[46:49], v[78:81]
	v_mfma_f32_16x16x32_bf16 v[82:85], v[6:9], v[54:57], v[82:85]
	v_mfma_f32_16x16x32_bf16 v[106:109], v[14:17], v[62:65], v[86:89]
	v_mfma_f32_16x16x32_bf16 v[86:89], v[18:21], v[34:37], 0
	v_mfma_f32_16x16x32_bf16 v[34:37], v[26:29], v[34:37], 0
	v_mfma_f32_16x16x32_bf16 v[110:113], v[22:25], v[38:41], v[86:89]
	v_mfma_f32_16x16x32_bf16 v[34:37], v[30:33], v[38:41], v[34:37]
	v_mfma_f32_16x16x32_bf16 v[38:41], v[18:21], v[42:45], 0
	v_mfma_f32_16x16x32_bf16 v[42:45], v[26:29], v[42:45], 0
	v_mfma_f32_16x16x32_bf16 v[38:41], v[22:25], v[46:49], v[38:41]
	v_mfma_f32_16x16x32_bf16 v[42:45], v[30:33], v[46:49], v[42:45]
	v_mfma_f32_16x16x32_bf16 v[46:49], v[18:21], v[50:53], 0
	v_mfma_f32_16x16x32_bf16 v[50:53], v[26:29], v[50:53], 0
	v_mfma_f32_16x16x32_bf16 v[46:49], v[22:25], v[54:57], v[46:49]
	v_mfma_f32_16x16x32_bf16 v[50:53], v[30:33], v[54:57], v[50:53]
	v_mfma_f32_16x16x32_bf16 v[54:57], v[18:21], v[58:61], 0
	v_mfma_f32_16x16x32_bf16 v[58:61], v[26:29], v[58:61], 0
	v_mfma_f32_16x16x32_bf16 v[54:57], v[22:25], v[62:65], v[54:57]
	v_mfma_f32_16x16x32_bf16 v[58:61], v[30:33], v[62:65], v[58:61]
	s_barrier
	v_lshl_add_u64 v[238:239], s[68:69], 0, v[130:131]
	s_mov_b32 m0, s81
	v_lshl_add_u64 v[146:147], v[238:239], 0, s[16:17]
	s_add_i32 s89, s81, 0x2000
	ds_read_b128 v[62:65], v143 offset:16384
	ds_read_b128 v[86:89], v143 offset:17408
	ds_read_b128 v[98:101], v143 offset:18432
	ds_read_b128 v[102:105], v143 offset:19456
	ds_read_b128 v[114:117], v143 offset:20480
	ds_read_b128 v[118:121], v143 offset:21504
	ds_read_b128 v[122:125], v143 offset:22528
	ds_read_b128 v[126:129], v143 offset:23552
	global_load_lds_dwordx4 v[146:147], off
	v_lshl_add_u64 v[146:147], v[238:239], 0, s[18:19]
	s_mov_b32 m0, s89
	s_add_i32 s90, s78, s43
	global_load_lds_dwordx4 v[146:147], off
	v_lshl_add_u64 v[146:147], v[238:239], 0, s[20:21]
	s_mov_b32 m0, s90
	s_add_i32 s91, s90, 0x2000
	global_load_lds_dwordx4 v[146:147], off
	v_lshl_add_u64 v[146:147], v[238:239], 0, s[22:23]
	s_mov_b32 m0, s91
	s_nop 0
	global_load_lds_dwordx4 v[146:147], off
	v_lshl_add_u64 v[146:147], v[140:141], 0, s[16:17]
	s_mov_b32 m0, s53
	s_nop 0
	global_load_lds_dwordx4 v[146:147], off
	v_lshl_add_u64 v[146:147], v[140:141], 0, s[18:19]
	s_mov_b32 m0, s54
	s_nop 0
	global_load_lds_dwordx4 v[146:147], off
	s_waitcnt vmcnt(16)
	s_waitcnt lgkmcnt(0)
	s_barrier
	s_waitcnt lgkmcnt(0)
	v_mfma_f32_16x16x32_bf16 v[146:149], v[2:5], v[62:65], 0
	v_mfma_f32_16x16x32_bf16 v[154:157], v[2:5], v[98:101], 0
	v_mfma_f32_16x16x32_bf16 v[162:165], v[2:5], v[114:117], 0
	v_mfma_f32_16x16x32_bf16 v[2:5], v[2:5], v[122:125], 0
	v_mfma_f32_16x16x32_bf16 v[146:149], v[6:9], v[86:89], v[146:149]
	v_mfma_f32_16x16x32_bf16 v[154:157], v[6:9], v[102:105], v[154:157]
	v_mfma_f32_16x16x32_bf16 v[162:165], v[6:9], v[118:121], v[162:165]
	v_mfma_f32_16x16x32_bf16 v[2:5], v[6:9], v[126:129], v[2:5]
	v_mfma_f32_16x16x32_bf16 v[6:9], v[10:13], v[122:125], 0
	v_mfma_f32_16x16x32_bf16 v[150:153], v[10:13], v[62:65], 0
	v_mfma_f32_16x16x32_bf16 v[158:161], v[10:13], v[98:101], 0
	v_mfma_f32_16x16x32_bf16 v[166:169], v[10:13], v[114:117], 0
	v_mfma_f32_16x16x32_bf16 v[10:13], v[14:17], v[126:129], v[6:9]
	v_mfma_f32_16x16x32_bf16 v[150:153], v[14:17], v[86:89], v[150:153]
	v_mfma_f32_16x16x32_bf16 v[158:161], v[14:17], v[102:105], v[158:161]
	v_mfma_f32_16x16x32_bf16 v[166:169], v[14:17], v[118:121], v[166:169]
	v_mfma_f32_16x16x32_bf16 v[6:9], v[18:21], v[62:65], 0
	v_mfma_f32_16x16x32_bf16 v[14:17], v[22:25], v[86:89], v[6:9]
	v_mfma_f32_16x16x32_bf16 v[6:9], v[26:29], v[62:65], 0
	v_mfma_f32_16x16x32_bf16 v[170:173], v[30:33], v[86:89], v[6:9]
	v_mfma_f32_16x16x32_bf16 v[6:9], v[18:21], v[98:101], 0
	v_mfma_f32_16x16x32_bf16 v[174:177], v[22:25], v[102:105], v[6:9]
	v_mfma_f32_16x16x32_bf16 v[6:9], v[26:29], v[98:101], 0
	v_mfma_f32_16x16x32_bf16 v[178:181], v[30:33], v[102:105], v[6:9]
	v_mfma_f32_16x16x32_bf16 v[6:9], v[18:21], v[114:117], 0
	v_mfma_f32_16x16x32_bf16 v[182:185], v[22:25], v[118:121], v[6:9]
	v_mfma_f32_16x16x32_bf16 v[6:9], v[26:29], v[114:117], 0
	v_mfma_f32_16x16x32_bf16 v[186:189], v[30:33], v[118:121], v[6:9]
	v_mfma_f32_16x16x32_bf16 v[6:9], v[18:21], v[122:125], 0
	v_mfma_f32_16x16x32_bf16 v[190:193], v[22:25], v[126:129], v[6:9]
	v_mfma_f32_16x16x32_bf16 v[6:9], v[26:29], v[122:125], 0
	v_mfma_f32_16x16x32_bf16 v[194:197], v[30:33], v[126:129], v[6:9]
	s_barrier
; #define PG8_WAIT_V(n) asm volatile("s_waitcnt vmcnt(" #n ")" ::: "memory")
; template <class Epi, class Sched, bool ALIGN_EPI = true, bool SP2 = true, bool FULLLINE = false, bool NOSTAGE = false, bool FP8 = false>
; __device__ __forceinline__ void gemm_phase(PG8_LAS unsigned char* lds, const Gemm g, const Sched& S, const Epi& E) {
;     ...
;         static_assert(SP2, "only the SP2 loop is kept");
;         { const int t = 0; if constexpr (Epi::NST == 16) PG8_ITER(PG8_WAIT_V(24)); else if constexpr (Epi::NST == 8) PG8_ITER(PG8_WAIT_V(16)); else PG8_ITER(PG8_WAIT_V(8)); }
;         for (int t = 2; t < nt; t += 2) PG8_ITER(PG8_WAIT_V(8));
	s_nop 5
	ds_read_b128 v[6:9], v144
	ds_read_b128 v[26:29], v144 offset:1024
	ds_read_b128 v[30:33], v144 offset:2048
	ds_read_b128 v[62:65], v144 offset:3072
	ds_read_b128 v[198:201], v145
	ds_read_b128 v[202:205], v145 offset:1024
	ds_read_b128 v[206:209], v145 offset:2048
	ds_read_b128 v[210:213], v145 offset:3072
	s_mov_b32 m0, s55
	v_lshl_add_u64 v[86:87], v[140:141], 0, s[20:21]
	ds_read_b128 v[18:21], v143 offset:32768
	ds_read_b128 v[22:25], v143 offset:33792
	ds_read_b128 v[214:217], v143 offset:34816
	ds_read_b128 v[218:221], v143 offset:35840
	ds_read_b128 v[222:225], v143 offset:36864
	ds_read_b128 v[226:229], v143 offset:37888
	ds_read_b128 v[230:233], v143 offset:38912
	ds_read_b128 v[234:237], v143 offset:39936
	global_load_lds_dwordx4 v[86:87], off
	v_lshl_add_u64 v[86:87], v[140:141], 0, s[22:23]
	s_mov_b32 m0, s67
	s_nop 0
	global_load_lds_dwordx4 v[86:87], off
	s_waitcnt vmcnt(8)
	s_waitcnt lgkmcnt(0)
	s_barrier
	s_waitcnt lgkmcnt(0)
	v_mfma_f32_16x16x32_bf16 v[66:69], v[6:9], v[18:21], v[66:69]
	v_mfma_f32_16x16x32_bf16 v[118:121], v[26:29], v[22:25], v[66:69]
	v_mfma_f32_16x16x32_bf16 v[66:69], v[30:33], v[18:21], v[70:73]
	v_mfma_f32_16x16x32_bf16 v[114:117], v[62:65], v[22:25], v[66:69]
	v_mfma_f32_16x16x32_bf16 v[66:69], v[6:9], v[214:217], v[74:77]
	v_mfma_f32_16x16x32_bf16 v[102:105], v[26:29], v[218:221], v[66:69]
	v_mfma_f32_16x16x32_bf16 v[66:69], v[30:33], v[214:217], v[78:81]
	v_mfma_f32_16x16x32_bf16 v[98:101], v[62:65], v[218:221], v[66:69]
	v_mfma_f32_16x16x32_bf16 v[66:69], v[6:9], v[222:225], v[82:85]
	v_mfma_f32_16x16x32_bf16 v[86:89], v[26:29], v[226:229], v[66:69]
	v_mfma_f32_16x16x32_bf16 v[66:69], v[30:33], v[222:225], v[90:93]
	v_mfma_f32_16x16x32_bf16 v[82:85], v[62:65], v[226:229], v[66:69]
	v_mfma_f32_16x16x32_bf16 v[66:69], v[6:9], v[230:233], v[94:97]
	v_mfma_f32_16x16x32_bf16 v[70:73], v[26:29], v[234:237], v[66:69]
	v_mfma_f32_16x16x32_bf16 v[66:69], v[30:33], v[230:233], v[106:109]
	v_mfma_f32_16x16x32_bf16 v[66:69], v[62:65], v[234:237], v[66:69]
	v_mfma_f32_16x16x32_bf16 v[74:77], v[198:201], v[18:21], v[110:113]
	v_mfma_f32_16x16x32_bf16 v[18:21], v[206:209], v[18:21], v[34:37]
	v_mfma_f32_16x16x32_bf16 v[122:125], v[210:213], v[22:25], v[18:21]
	v_mfma_f32_16x16x32_bf16 v[18:21], v[198:201], v[214:217], v[38:41]
	v_mfma_f32_16x16x32_bf16 v[110:113], v[202:205], v[218:221], v[18:21]
	v_mfma_f32_16x16x32_bf16 v[18:21], v[206:209], v[214:217], v[42:45]
	v_mfma_f32_16x16x32_bf16 v[106:109], v[210:213], v[218:221], v[18:21]
	v_mfma_f32_16x16x32_bf16 v[18:21], v[198:201], v[222:225], v[46:49]
	v_mfma_f32_16x16x32_bf16 v[94:97], v[202:205], v[226:229], v[18:21]
	v_mfma_f32_16x16x32_bf16 v[18:21], v[206:209], v[222:225], v[50:53]
	v_mfma_f32_16x16x32_bf16 v[90:93], v[210:213], v[226:229], v[18:21]
	v_mfma_f32_16x16x32_bf16 v[18:21], v[198:201], v[230:233], v[54:57]
	v_mfma_f32_16x16x32_bf16 v[78:81], v[202:205], v[234:237], v[18:21]
	v_mfma_f32_16x16x32_bf16 v[18:21], v[206:209], v[230:233], v[58:61]
	v_mfma_f32_16x16x32_bf16 v[126:129], v[202:205], v[22:25], v[74:77]
	v_mfma_f32_16x16x32_bf16 v[74:77], v[210:213], v[234:237], v[18:21]
	s_barrier
	s_add_i32 s50, s82, s43
	s_nop 3
	v_lshl_add_u64 v[18:19], v[238:239], 0, s[24:25]
	s_mov_b32 m0, s50
	s_add_i32 s51, s50, 0x2000
	ds_read_b128 v[42:45], v143 offset:49152
	ds_read_b128 v[46:49], v143 offset:50176
	ds_read_b128 v[214:217], v143 offset:51200
	ds_read_b128 v[218:221], v143 offset:52224
	ds_read_b128 v[222:225], v143 offset:53248
	ds_read_b128 v[226:229], v143 offset:54272
	ds_read_b128 v[230:233], v143 offset:55296
	ds_read_b128 v[234:237], v143 offset:56320
	global_load_lds_dwordx4 v[18:19], off
	v_lshl_add_u64 v[18:19], v[238:239], 0, s[26:27]
	s_mov_b32 m0, s51
	s_mov_b64 s[0:1], 0x80180
	s_add_i32 s33, s83, s43
	global_load_lds_dwordx4 v[18:19], off
	v_lshl_add_u64 v[18:19], v[238:239], 0, s[0:1]
	s_mov_b32 m0, s33
	s_mov_b64 s[0:1], 0xc0180
	s_add_i32 s56, s33, 0x2000
	global_load_lds_dwordx4 v[18:19], off
	v_lshl_add_u64 v[18:19], v[238:239], 0, s[0:1]
	s_mov_b32 m0, s56
	s_nop 0
	global_load_lds_dwordx4 v[18:19], off
	v_lshl_add_u64 v[18:19], v[140:141], 0, s[24:25]
	s_mov_b32 m0, s72
	s_nop 0
	global_load_lds_dwordx4 v[18:19], off
	v_lshl_add_u64 v[18:19], v[140:141], 0, s[26:27]
	s_mov_b32 m0, s73
	s_nop 0
	global_load_lds_dwordx4 v[18:19], off
	s_waitcnt vmcnt(8)
	s_waitcnt lgkmcnt(0)
	s_barrier
	s_waitcnt lgkmcnt(0)
	v_mfma_f32_16x16x32_bf16 v[18:21], v[6:9], v[42:45], v[146:149]
	v_mfma_f32_16x16x32_bf16 v[54:57], v[26:29], v[46:49], v[18:21]
	v_mfma_f32_16x16x32_bf16 v[18:21], v[30:33], v[42:45], v[150:153]
	v_mfma_f32_16x16x32_bf16 v[50:53], v[62:65], v[46:49], v[18:21]
	v_mfma_f32_16x16x32_bf16 v[18:21], v[6:9], v[214:217], v[154:157]
	v_mfma_f32_16x16x32_bf16 v[38:41], v[26:29], v[218:221], v[18:21]
	v_mfma_f32_16x16x32_bf16 v[18:21], v[30:33], v[214:217], v[158:161]
	v_mfma_f32_16x16x32_bf16 v[34:37], v[62:65], v[218:221], v[18:21]
	v_mfma_f32_16x16x32_bf16 v[18:21], v[6:9], v[222:225], v[162:165]
	v_mfma_f32_16x16x32_bf16 v[2:5], v[6:9], v[230:233], v[2:5]
	v_mfma_f32_16x16x32_bf16 v[22:25], v[26:29], v[226:229], v[18:21]
	v_mfma_f32_16x16x32_bf16 v[18:21], v[30:33], v[222:225], v[166:169]
	v_mfma_f32_16x16x32_bf16 v[6:9], v[26:29], v[234:237], v[2:5]
	v_mfma_f32_16x16x32_bf16 v[2:5], v[30:33], v[230:233], v[10:13]
	v_mfma_f32_16x16x32_bf16 v[18:21], v[62:65], v[226:229], v[18:21]
	v_mfma_f32_16x16x32_bf16 v[2:5], v[62:65], v[234:237], v[2:5]
	v_mfma_f32_16x16x32_bf16 v[10:13], v[198:201], v[42:45], v[14:17]
	v_mfma_f32_16x16x32_bf16 v[62:65], v[202:205], v[46:49], v[10:13]
	v_mfma_f32_16x16x32_bf16 v[10:13], v[206:209], v[42:45], v[170:173]
	v_mfma_f32_16x16x32_bf16 v[58:61], v[210:213], v[46:49], v[10:13]
	v_mfma_f32_16x16x32_bf16 v[10:13], v[198:201], v[214:217], v[174:177]
	v_mfma_f32_16x16x32_bf16 v[46:49], v[202:205], v[218:221], v[10:13]
	v_mfma_f32_16x16x32_bf16 v[10:13], v[206:209], v[214:217], v[178:181]
	v_mfma_f32_16x16x32_bf16 v[42:45], v[210:213], v[218:221], v[10:13]
	v_mfma_f32_16x16x32_bf16 v[10:13], v[198:201], v[222:225], v[182:185]
	v_mfma_f32_16x16x32_bf16 v[30:33], v[202:205], v[226:229], v[10:13]
	v_mfma_f32_16x16x32_bf16 v[10:13], v[206:209], v[222:225], v[186:189]
	v_mfma_f32_16x16x32_bf16 v[26:29], v[210:213], v[226:229], v[10:13]
	v_mfma_f32_16x16x32_bf16 v[10:13], v[198:201], v[230:233], v[190:193]
	v_mfma_f32_16x16x32_bf16 v[14:17], v[202:205], v[234:237], v[10:13]
	v_mfma_f32_16x16x32_bf16 v[10:13], v[206:209], v[230:233], v[194:197]
	v_mfma_f32_16x16x32_bf16 v[10:13], v[210:213], v[234:237], v[10:13]
	s_barrier
	s_add_u32 s70, s70, 0x80180
	s_addc_u32 s71, s71, 0
	s_add_u32 s57, s68, 0x200
	s_addc_u32 s68, s69, 0
	s_mov_b32 s69, 0
	.p2align 6

.LBB0_2964:
	ds_read_b128 v[2:5], v1
	ds_read_b128 v[6:9], v1 offset:1024
	ds_read_b128 v[10:13], v1 offset:2048
	ds_read_b128 v[14:17], v1 offset:3072
	ds_read_b128 v[18:21], v168
	ds_read_b128 v[22:25], v168 offset:1024
	ds_read_b128 v[26:29], v168 offset:2048
	ds_read_b128 v[30:33], v168 offset:3072
	v_lshl_add_u64 v[244:245], s[46:47], 0, v[150:151]
	s_add_i32 s81, s53, 0xc000
	v_lshl_add_u64 v[66:67], v[244:245], 0, s[14:15]
	s_mov_b32 m0, s81
	s_add_i32 s82, s53, 0xe000
	ds_read_b128 v[34:37], v169
	ds_read_b128 v[38:41], v169 offset:1024
	ds_read_b128 v[42:45], v169 offset:2048
	ds_read_b128 v[46:49], v169 offset:3072
	ds_read_b128 v[50:53], v169 offset:4096
	ds_read_b128 v[54:57], v169 offset:5120
	ds_read_b128 v[58:61], v169 offset:6144
	ds_read_b128 v[62:65], v169 offset:7168
	global_load_lds_dwordx4 v[66:67], off
	v_lshl_add_u64 v[66:67], v[244:245], 0, s[16:17]
	s_mov_b32 m0, s82
	s_nop 0
	global_load_lds_dwordx4 v[66:67], off
	s_waitcnt vmcnt(24)
	s_waitcnt lgkmcnt(0)
	s_barrier
	s_waitcnt lgkmcnt(0)
	v_mfma_f32_16x16x32_bf16 v[66:69], v[2:5], v[34:37], 0
	v_mfma_f32_16x16x32_bf16 v[70:73], v[10:13], v[34:37], 0
	v_mfma_f32_16x16x32_bf16 v[74:77], v[2:5], v[42:45], 0
	v_mfma_f32_16x16x32_bf16 v[78:81], v[10:13], v[42:45], 0
	v_mfma_f32_16x16x32_bf16 v[90:93], v[2:5], v[58:61], 0
	v_mfma_f32_16x16x32_bf16 v[66:69], v[6:9], v[38:41], v[66:69]
	v_mfma_f32_16x16x32_bf16 v[70:73], v[14:17], v[38:41], v[70:73]
	v_mfma_f32_16x16x32_bf16 v[74:77], v[6:9], v[46:49], v[74:77]
	v_mfma_f32_16x16x32_bf16 v[78:81], v[14:17], v[46:49], v[78:81]
	v_mfma_f32_16x16x32_bf16 v[82:85], v[2:5], v[50:53], 0
	v_mfma_f32_16x16x32_bf16 v[86:89], v[10:13], v[50:53], 0
	v_mfma_f32_16x16x32_bf16 v[90:93], v[6:9], v[62:65], v[90:93]
	v_mfma_f32_16x16x32_bf16 v[94:97], v[10:13], v[58:61], 0
	v_mfma_f32_16x16x32_bf16 v[82:85], v[6:9], v[54:57], v[82:85]
	v_mfma_f32_16x16x32_bf16 v[86:89], v[14:17], v[54:57], v[86:89]
	v_mfma_f32_16x16x32_bf16 v[94:97], v[14:17], v[62:65], v[94:97]
	v_mfma_f32_16x16x32_bf16 v[98:101], v[18:21], v[34:37], 0
	v_mfma_f32_16x16x32_bf16 v[34:37], v[26:29], v[34:37], 0
	v_mfma_f32_16x16x32_bf16 v[98:101], v[22:25], v[38:41], v[98:101]
	v_mfma_f32_16x16x32_bf16 v[34:37], v[30:33], v[38:41], v[34:37]
	v_mfma_f32_16x16x32_bf16 v[38:41], v[18:21], v[42:45], 0
	v_mfma_f32_16x16x32_bf16 v[42:45], v[26:29], v[42:45], 0
	v_mfma_f32_16x16x32_bf16 v[38:41], v[22:25], v[46:49], v[38:41]
	v_mfma_f32_16x16x32_bf16 v[42:45], v[30:33], v[46:49], v[42:45]
	v_mfma_f32_16x16x32_bf16 v[46:49], v[18:21], v[50:53], 0
	v_mfma_f32_16x16x32_bf16 v[50:53], v[26:29], v[50:53], 0
	v_mfma_f32_16x16x32_bf16 v[46:49], v[22:25], v[54:57], v[46:49]
	v_mfma_f32_16x16x32_bf16 v[50:53], v[30:33], v[54:57], v[50:53]
	v_mfma_f32_16x16x32_bf16 v[54:57], v[18:21], v[58:61], 0
	v_mfma_f32_16x16x32_bf16 v[58:61], v[26:29], v[58:61], 0
	v_mfma_f32_16x16x32_bf16 v[54:57], v[22:25], v[62:65], v[54:57]
	v_mfma_f32_16x16x32_bf16 v[58:61], v[30:33], v[62:65], v[58:61]
	s_barrier
	v_lshl_add_u64 v[246:247], s[58:59], 0, v[152:153]
	s_add_i32 s83, s73, s52
	v_lshl_add_u64 v[130:131], v[246:247], 0, s[18:19]
	s_mov_b32 m0, s83
	s_add_i32 s84, s83, 0x2000
	ds_read_b128 v[62:65], v169 offset:16384
	ds_read_b128 v[102:105], v169 offset:17408
	ds_read_b128 v[106:109], v169 offset:18432
	ds_read_b128 v[110:113], v169 offset:19456
	ds_read_b128 v[114:117], v169 offset:20480
	ds_read_b128 v[118:121], v169 offset:21504
	ds_read_b128 v[122:125], v169 offset:22528
	ds_read_b128 v[126:129], v169 offset:23552
	global_load_lds_dwordx4 v[130:131], off
	v_lshl_add_u64 v[130:131], v[246:247], 0, s[20:21]
	s_mov_b32 m0, s84
	s_add_i32 s85, s74, s52
	global_load_lds_dwordx4 v[130:131], off
	v_lshl_add_u64 v[130:131], v[246:247], 0, s[22:23]
	s_mov_b32 m0, s85
	s_add_i32 s87, s85, 0x2000
	global_load_lds_dwordx4 v[130:131], off
	v_lshl_add_u64 v[130:131], v[246:247], 0, s[24:25]
	s_mov_b32 m0, s87
	s_nop 0
	global_load_lds_dwordx4 v[130:131], off
	v_lshl_add_u64 v[130:131], v[244:245], 0, s[18:19]
	s_mov_b32 m0, s53
	s_nop 0
	global_load_lds_dwordx4 v[130:131], off
	v_lshl_add_u64 v[130:131], v[244:245], 0, s[20:21]
	s_mov_b32 m0, s54
	s_nop 0
	global_load_lds_dwordx4 v[130:131], off
	s_waitcnt vmcnt(24)
	s_waitcnt lgkmcnt(0)
	s_barrier
	s_waitcnt lgkmcnt(0)
	v_mfma_f32_16x16x32_bf16 v[130:133], v[2:5], v[62:65], 0
	v_mfma_f32_16x16x32_bf16 v[146:149], v[6:9], v[102:105], v[130:133]
	v_mfma_f32_16x16x32_bf16 v[130:133], v[10:13], v[62:65], 0
	v_mfma_f32_16x16x32_bf16 v[160:163], v[14:17], v[102:105], v[130:133]
	v_mfma_f32_16x16x32_bf16 v[130:133], v[2:5], v[106:109], 0
	v_mfma_f32_16x16x32_bf16 v[164:167], v[6:9], v[110:113], v[130:133]
	v_mfma_f32_16x16x32_bf16 v[130:133], v[10:13], v[106:109], 0
	v_mfma_f32_16x16x32_bf16 v[172:175], v[14:17], v[110:113], v[130:133]
	v_mfma_f32_16x16x32_bf16 v[130:133], v[2:5], v[114:117], 0
	v_mfma_f32_16x16x32_bf16 v[2:5], v[2:5], v[122:125], 0
	v_mfma_f32_16x16x32_bf16 v[176:179], v[6:9], v[118:121], v[130:133]
	v_mfma_f32_16x16x32_bf16 v[2:5], v[6:9], v[126:129], v[2:5]
	v_mfma_f32_16x16x32_bf16 v[6:9], v[10:13], v[122:125], 0
	v_mfma_f32_16x16x32_bf16 v[130:133], v[10:13], v[114:117], 0
	v_mfma_f32_16x16x32_bf16 v[6:9], v[14:17], v[126:129], v[6:9]
	v_mfma_f32_16x16x32_bf16 v[180:183], v[14:17], v[118:121], v[130:133]
	v_mfma_f32_16x16x32_bf16 v[10:13], v[18:21], v[62:65], 0
	v_mfma_f32_16x16x32_bf16 v[184:187], v[22:25], v[102:105], v[10:13]
	v_mfma_f32_16x16x32_bf16 v[10:13], v[26:29], v[62:65], 0
	v_mfma_f32_16x16x32_bf16 v[102:105], v[30:33], v[102:105], v[10:13]
	v_mfma_f32_16x16x32_bf16 v[10:13], v[18:21], v[106:109], 0
	v_mfma_f32_16x16x32_bf16 v[188:191], v[22:25], v[110:113], v[10:13]
	v_mfma_f32_16x16x32_bf16 v[10:13], v[26:29], v[106:109], 0
	v_mfma_f32_16x16x32_bf16 v[192:195], v[30:33], v[110:113], v[10:13]
	v_mfma_f32_16x16x32_bf16 v[10:13], v[18:21], v[114:117], 0
	v_mfma_f32_16x16x32_bf16 v[196:199], v[22:25], v[118:121], v[10:13]
	v_mfma_f32_16x16x32_bf16 v[10:13], v[26:29], v[114:117], 0
	v_mfma_f32_16x16x32_bf16 v[200:203], v[30:33], v[118:121], v[10:13]
	v_mfma_f32_16x16x32_bf16 v[10:13], v[18:21], v[122:125], 0
	v_mfma_f32_16x16x32_bf16 v[204:207], v[22:25], v[126:129], v[10:13]
	v_mfma_f32_16x16x32_bf16 v[10:13], v[26:29], v[122:125], 0
	v_mfma_f32_16x16x32_bf16 v[208:211], v[30:33], v[126:129], v[10:13]
	s_barrier
; #define PG8_WAIT_V(n) asm volatile("s_waitcnt vmcnt(" #n ")" ::: "memory")
; template <class Epi, class Sched, bool ALIGN_EPI = true, bool SP2 = true, bool FULLLINE = false, bool NOSTAGE = false, bool FP8 = false>
; __device__ __forceinline__ void gemm_phase(PG8_LAS unsigned char* lds, const Gemm g, const Sched& S, const Epi& E) {
;     ...
;         static_assert(SP2, "only the SP2 loop is kept");
;         { const int t = 0; if constexpr (Epi::NST == 16) PG8_ITER(PG8_WAIT_V(24)); else if constexpr (Epi::NST == 8) PG8_ITER(PG8_WAIT_V(16)); else PG8_ITER(PG8_WAIT_V(8)); }
;         for (int t = 2; t < nt; t += 2) PG8_ITER(PG8_WAIT_V(8));
	s_nop 5
	ds_read_b128 v[10:13], v170
	ds_read_b128 v[14:17], v170 offset:1024
	ds_read_b128 v[18:21], v170 offset:2048
	ds_read_b128 v[22:25], v170 offset:3072
	ds_read_b128 v[212:215], v171
	ds_read_b128 v[216:219], v171 offset:1024
	ds_read_b128 v[220:223], v171 offset:2048
	ds_read_b128 v[224:227], v171 offset:3072
	s_mov_b32 m0, s55
	v_lshl_add_u64 v[106:107], v[244:245], 0, s[22:23]
	ds_read_b128 v[26:29], v169 offset:32768
	ds_read_b128 v[30:33], v169 offset:33792
	ds_read_b128 v[62:65], v169 offset:34816
	ds_read_b128 v[114:117], v169 offset:35840
	ds_read_b128 v[228:231], v169 offset:36864
	ds_read_b128 v[232:235], v169 offset:37888
	ds_read_b128 v[236:239], v169 offset:38912
	ds_read_b128 v[240:243], v169 offset:39936
	global_load_lds_dwordx4 v[106:107], off
	v_lshl_add_u64 v[106:107], v[244:245], 0, s[24:25]
	s_mov_b32 m0, s62
	s_nop 0
	global_load_lds_dwordx4 v[106:107], off
	s_waitcnt vmcnt(8)
	s_waitcnt lgkmcnt(0)
	s_barrier
	s_waitcnt lgkmcnt(0)
	v_mfma_f32_16x16x32_bf16 v[66:69], v[10:13], v[26:29], v[66:69]
	v_mfma_f32_16x16x32_bf16 v[138:141], v[14:17], v[30:33], v[66:69]
	v_mfma_f32_16x16x32_bf16 v[66:69], v[18:21], v[26:29], v[70:73]
	v_mfma_f32_16x16x32_bf16 v[134:137], v[22:25], v[30:33], v[66:69]
	v_mfma_f32_16x16x32_bf16 v[66:69], v[10:13], v[62:65], v[74:77]
	v_mfma_f32_16x16x32_bf16 v[126:129], v[14:17], v[114:117], v[66:69]
	v_mfma_f32_16x16x32_bf16 v[66:69], v[18:21], v[62:65], v[78:81]
	v_mfma_f32_16x16x32_bf16 v[122:125], v[22:25], v[114:117], v[66:69]
	v_mfma_f32_16x16x32_bf16 v[66:69], v[10:13], v[228:231], v[82:85]
	v_mfma_f32_16x16x32_bf16 v[110:113], v[14:17], v[232:235], v[66:69]
	v_mfma_f32_16x16x32_bf16 v[66:69], v[18:21], v[228:231], v[86:89]
	v_mfma_f32_16x16x32_bf16 v[106:109], v[22:25], v[232:235], v[66:69]
	v_mfma_f32_16x16x32_bf16 v[66:69], v[10:13], v[236:239], v[90:93]
	v_mfma_f32_16x16x32_bf16 v[78:81], v[14:17], v[240:243], v[66:69]
	v_mfma_f32_16x16x32_bf16 v[66:69], v[18:21], v[236:239], v[94:97]
	v_mfma_f32_16x16x32_bf16 v[74:77], v[22:25], v[240:243], v[66:69]
	v_mfma_f32_16x16x32_bf16 v[66:69], v[212:215], v[26:29], v[98:101]
	v_mfma_f32_16x16x32_bf16 v[26:29], v[220:223], v[26:29], v[34:37]
	v_mfma_f32_16x16x32_bf16 v[130:133], v[224:227], v[30:33], v[26:29]
	v_mfma_f32_16x16x32_bf16 v[26:29], v[212:215], v[62:65], v[38:41]
	v_mfma_f32_16x16x32_bf16 v[118:121], v[216:219], v[114:117], v[26:29]
	v_mfma_f32_16x16x32_bf16 v[26:29], v[220:223], v[62:65], v[42:45]
	v_mfma_f32_16x16x32_bf16 v[114:117], v[224:227], v[114:117], v[26:29]
	v_mfma_f32_16x16x32_bf16 v[26:29], v[212:215], v[228:231], v[46:49]
	v_mfma_f32_16x16x32_bf16 v[98:101], v[216:219], v[232:235], v[26:29]
	v_mfma_f32_16x16x32_bf16 v[26:29], v[220:223], v[228:231], v[50:53]
	v_mfma_f32_16x16x32_bf16 v[90:93], v[224:227], v[232:235], v[26:29]
	v_mfma_f32_16x16x32_bf16 v[26:29], v[212:215], v[236:239], v[54:57]
	v_mfma_f32_16x16x32_bf16 v[70:73], v[216:219], v[240:243], v[26:29]
	v_mfma_f32_16x16x32_bf16 v[26:29], v[220:223], v[236:239], v[58:61]
	v_mfma_f32_16x16x32_bf16 v[142:145], v[216:219], v[30:33], v[66:69]
	v_mfma_f32_16x16x32_bf16 v[66:69], v[224:227], v[240:243], v[26:29]
	s_barrier
	s_add_i32 s50, s75, s52
	s_nop 3
	v_lshl_add_u64 v[26:27], v[246:247], 0, s[26:27]
	s_mov_b32 m0, s50
	s_add_i32 s51, s50, 0x2000
	ds_read_b128 v[34:37], v169 offset:49152
	ds_read_b128 v[38:41], v169 offset:50176
	ds_read_b128 v[82:85], v169 offset:51200
	ds_read_b128 v[86:89], v169 offset:52224
	ds_read_b128 v[94:97], v169 offset:53248
	ds_read_b128 v[228:231], v169 offset:54272
	ds_read_b128 v[232:235], v169 offset:55296
	ds_read_b128 v[236:239], v169 offset:56320
	global_load_lds_dwordx4 v[26:27], off
	v_lshl_add_u64 v[26:27], v[246:247], 0, s[28:29]
	s_mov_b32 m0, s51
	s_mov_b64 s[0:1], 0x160180
	s_add_i32 s33, s76, s52
	global_load_lds_dwordx4 v[26:27], off
	v_lshl_add_u64 v[26:27], v[246:247], 0, s[0:1]
	s_mov_b32 m0, s33
	s_mov_b64 s[0:1], 0x210180
	s_add_i32 s56, s33, 0x2000
	global_load_lds_dwordx4 v[26:27], off
	v_lshl_add_u64 v[26:27], v[246:247], 0, s[0:1]
	s_mov_b32 m0, s56
	s_nop 0
	global_load_lds_dwordx4 v[26:27], off
	v_lshl_add_u64 v[26:27], v[244:245], 0, s[26:27]
	s_mov_b32 m0, s63
	s_nop 0
	global_load_lds_dwordx4 v[26:27], off
	v_lshl_add_u64 v[26:27], v[244:245], 0, s[28:29]
	s_mov_b32 m0, s66
	s_nop 0
	global_load_lds_dwordx4 v[26:27], off
	s_waitcnt vmcnt(8)
	s_waitcnt lgkmcnt(0)
	s_barrier
	s_waitcnt lgkmcnt(0)
	v_mfma_f32_16x16x32_bf16 v[26:29], v[10:13], v[34:37], v[146:149]
	v_mfma_f32_16x16x32_bf16 v[62:65], v[14:17], v[38:41], v[26:29]
	v_mfma_f32_16x16x32_bf16 v[26:29], v[18:21], v[34:37], v[160:163]
	v_mfma_f32_16x16x32_bf16 v[58:61], v[22:25], v[38:41], v[26:29]
	v_mfma_f32_16x16x32_bf16 v[26:29], v[10:13], v[82:85], v[164:167]
	v_mfma_f32_16x16x32_bf16 v[46:49], v[14:17], v[86:89], v[26:29]
	v_mfma_f32_16x16x32_bf16 v[26:29], v[18:21], v[82:85], v[172:175]
	v_mfma_f32_16x16x32_bf16 v[42:45], v[22:25], v[86:89], v[26:29]
	v_mfma_f32_16x16x32_bf16 v[26:29], v[10:13], v[94:97], v[176:179]
	v_mfma_f32_16x16x32_bf16 v[2:5], v[10:13], v[232:235], v[2:5]
	v_mfma_f32_16x16x32_bf16 v[30:33], v[14:17], v[228:231], v[26:29]
	v_mfma_f32_16x16x32_bf16 v[26:29], v[18:21], v[94:97], v[180:183]
	v_mfma_f32_16x16x32_bf16 v[14:17], v[14:17], v[236:239], v[2:5]
	v_mfma_f32_16x16x32_bf16 v[2:5], v[18:21], v[232:235], v[6:9]
	v_mfma_f32_16x16x32_bf16 v[26:29], v[22:25], v[228:231], v[26:29]
	v_mfma_f32_16x16x32_bf16 v[10:13], v[22:25], v[236:239], v[2:5]
	v_mfma_f32_16x16x32_bf16 v[2:5], v[212:215], v[34:37], v[184:187]
	v_mfma_f32_16x16x32_bf16 v[54:57], v[216:219], v[38:41], v[2:5]
	v_mfma_f32_16x16x32_bf16 v[2:5], v[220:223], v[34:37], v[102:105]
	v_mfma_f32_16x16x32_bf16 v[50:53], v[224:227], v[38:41], v[2:5]
	v_mfma_f32_16x16x32_bf16 v[2:5], v[212:215], v[82:85], v[188:191]
	v_mfma_f32_16x16x32_bf16 v[38:41], v[216:219], v[86:89], v[2:5]
	v_mfma_f32_16x16x32_bf16 v[2:5], v[220:223], v[82:85], v[192:195]
	v_mfma_f32_16x16x32_bf16 v[34:37], v[224:227], v[86:89], v[2:5]
	v_mfma_f32_16x16x32_bf16 v[2:5], v[212:215], v[94:97], v[196:199]
	v_mfma_f32_16x16x32_bf16 v[22:25], v[216:219], v[228:231], v[2:5]
	v_mfma_f32_16x16x32_bf16 v[2:5], v[220:223], v[94:97], v[200:203]
	v_mfma_f32_16x16x32_bf16 v[18:21], v[224:227], v[228:231], v[2:5]
	v_mfma_f32_16x16x32_bf16 v[2:5], v[212:215], v[232:235], v[204:207]
	v_mfma_f32_16x16x32_bf16 v[6:9], v[216:219], v[236:239], v[2:5]
	v_mfma_f32_16x16x32_bf16 v[2:5], v[220:223], v[232:235], v[208:211]
	v_mfma_f32_16x16x32_bf16 v[2:5], v[224:227], v[236:239], v[2:5]
	s_barrier
	s_add_u32 s46, s46, 0x160180
	s_addc_u32 s47, s47, 0
	s_add_u32 s57, s58, 0x200
	s_addc_u32 s58, s59, 0
	s_mov_b32 s59, 0
	.p2align 6
